# gate pre-activations kept in accumulator lane order: P1 stores gate tiles without the LDS transpose, P3 gate hooks use the loaded quads directly (96 LDS staging ops per wave-unit removed)
# speedup vs baseline: 1.0029x; 1.0029x over previous
; #define PG8_LAS __attribute__((address_space(3)))
; __device__ __forceinline__ size_t tm_block(int pm, int ct, int nct) { return ((size_t)pm * nct + ct) * 32768; }
; __device__ __forceinline__ u32x4 pack8(const f32x4& v0, const f32x4& v1) { u32x4 w; w.x = cvt_pk_bf16(v0[0], v0[1]); w.y = cvt_pk_bf16(v0[2], v0[3]); w.z = cvt_pk_bf16(v1[0], v1[1]); w.w = cvt_pk_bf16(v1[2], v1[3]); return w; }
;     template <bool NT> __device__ __forceinline__ void flush(int ai, int m) const {
;         const u32x4 r0 = *(const PG8_LAS u32x4*)rp, r1 = *(const PG8_LAS u32x4*)(rp + 8 * PG8_SCR_STRIDE);
;         u32x4* p = (u32x4*)(ob + ai * 16384 + m * 2048);
;         if (NT) { __builtin_nontemporal_store(r0, p); __builtin_nontemporal_store(r1, p + 64); } else { *p = r0; *(p + 64) = r1; } }
;     __device__ __forceinline__ void operator()(const f32x4 (&acc)[2][2][4][2], const Unit& u, int wr, int wc, int fr, int fq) const {
;         const PieceOut po(scr, O, tm_block(u.pm, u.pn * 4 + wc, nct), wr, wc, fr, fq);
;         const float qs = (u.pn < 2 || u.pn == 3 || u.pn == 4) ? 0.125f * 1.4426950408889634f : 1.0f;
; #pragma unroll
;         for (int ai = 0; ai < 2; ++ai)
; #pragma unroll
;             for (int m = 0; m < 4; ++m) { po.put(0, pack8(acc[ai][0][m][0] * qs, acc[ai][0][m][1] * qs)); po.put(1, pack8(acc[ai][1][m][0] * qs, acc[ai][1][m][1] * qs)); po.flush<true>(ai, m); }
.Lp1_epi_plain:
	s_cmp_gt_u32 s70, 8
	s_cbranch_scc1 .Lp1_epi_gate
	v_cvt_pk_bf16_f32 v125, v124, v125
	v_cvt_pk_bf16_f32 v124, v122, v123
	v_cvt_pk_bf16_f32 v122, v126, v127
	v_cvt_pk_bf16_f32 v123, v128, v129
	ds_write_b128 v153, v[122:125]
	v_cvt_pk_bf16_f32 v113, v112, v113
	v_cvt_pk_bf16_f32 v112, v110, v111
	v_cvt_pk_bf16_f32 v110, v118, v119
	v_cvt_pk_bf16_f32 v111, v120, v121
	ds_write_b128 v153, v[110:113] offset:64
	ds_read_b128 v[110:113], v154
	ds_read_b128 v[118:121], v154 offset:1152
	v_lshl_add_u64 v[122:123], v[138:139], 0, s[24:25]
	s_waitcnt lgkmcnt(0)
	global_store_dwordx4 v[122:123], v[110:113], off nt
	global_store_dwordx4 v[122:123], v[118:121], off offset:1024 nt
	s_nop 0
	v_cvt_pk_bf16_f32 v109, v108, v109
	v_cvt_pk_bf16_f32 v108, v106, v107
	v_cvt_pk_bf16_f32 v106, v114, v115
	v_cvt_pk_bf16_f32 v107, v116, v117
	ds_write_b128 v153, v[106:109]
	v_cvt_pk_bf16_f32 v97, v96, v97
	v_cvt_pk_bf16_f32 v96, v94, v95
	v_cvt_pk_bf16_f32 v94, v102, v103
	v_cvt_pk_bf16_f32 v95, v104, v105
	ds_write_b128 v153, v[94:97] offset:64
	ds_read_b128 v[94:97], v154
	ds_read_b128 v[102:105], v154 offset:1152
	s_waitcnt lgkmcnt(0)
	global_store_dwordx4 v[122:123], v[94:97], off offset:2048 nt
	global_store_dwordx4 v[122:123], v[102:105], off offset:3072 nt
	s_nop 0
	v_cvt_pk_bf16_f32 v93, v92, v93
	v_cvt_pk_bf16_f32 v92, v90, v91
	v_cvt_pk_bf16_f32 v90, v98, v99
	v_cvt_pk_bf16_f32 v91, v100, v101
	ds_write_b128 v153, v[90:93]
	v_cvt_pk_bf16_f32 v85, v84, v85
	v_cvt_pk_bf16_f32 v84, v82, v83
	v_cvt_pk_bf16_f32 v82, v86, v87
	v_cvt_pk_bf16_f32 v83, v88, v89
	ds_write_b128 v153, v[82:85] offset:64
	ds_read_b128 v[82:85], v154
	ds_read_b128 v[86:89], v154 offset:1152
	v_add_co_u32_e32 v90, vcc, s58, v122
	s_nop 0
	s_nop 0
	v_addc_co_u32_e32 v91, vcc, 0, v123, vcc
	s_waitcnt lgkmcnt(0)
	global_store_dwordx4 v[90:91], v[82:85], off nt
	global_store_dwordx4 v[90:91], v[86:89], off offset:1024 nt
	v_cvt_pk_bf16_f32 v77, v76, v77
	v_cvt_pk_bf16_f32 v76, v74, v75
	v_cvt_pk_bf16_f32 v74, v78, v79
	v_cvt_pk_bf16_f32 v75, v80, v81
	ds_write_b128 v153, v[74:77]
	v_cvt_pk_bf16_f32 v69, v68, v69
	v_cvt_pk_bf16_f32 v68, v66, v67
	v_cvt_pk_bf16_f32 v66, v70, v71
	v_cvt_pk_bf16_f32 v67, v72, v73
	ds_write_b128 v153, v[66:69] offset:64
	ds_read_b128 v[66:69], v154
	ds_read_b128 v[70:73], v154 offset:1152
	s_waitcnt lgkmcnt(0)
	global_store_dwordx4 v[90:91], v[66:69], off offset:2048 nt
	global_store_dwordx4 v[90:91], v[70:73], off offset:3072 nt
	v_cvt_pk_bf16_f32 v61, v60, v61
	v_cvt_pk_bf16_f32 v60, v58, v59
	v_cvt_pk_bf16_f32 v58, v62, v63
	v_cvt_pk_bf16_f32 v59, v64, v65
	ds_write_b128 v153, v[58:61]
	v_cvt_pk_bf16_f32 v53, v52, v53
	v_cvt_pk_bf16_f32 v52, v50, v51
	v_cvt_pk_bf16_f32 v50, v54, v55
	v_cvt_pk_bf16_f32 v51, v56, v57
	ds_write_b128 v153, v[50:53] offset:64
	ds_read_b128 v[50:53], v154
	ds_read_b128 v[54:57], v154 offset:1152
	v_add_co_u32_e32 v58, vcc, s52, v122
	s_nop 0
	s_nop 0
	v_addc_co_u32_e32 v59, vcc, 0, v123, vcc
	v_add_co_u32_e32 v60, vcc, s59, v122
	s_nop 0
	s_nop 0
	v_addc_co_u32_e32 v61, vcc, 0, v123, vcc
	s_waitcnt lgkmcnt(0)
	global_store_dwordx4 v[60:61], v[50:53], off offset:-4096 nt
	global_store_dwordx4 v[58:59], v[54:57], off offset:1024 nt
	v_cvt_pk_bf16_f32 v45, v44, v45
	v_cvt_pk_bf16_f32 v44, v42, v43
	v_cvt_pk_bf16_f32 v42, v46, v47
	v_cvt_pk_bf16_f32 v43, v48, v49
	ds_write_b128 v153, v[42:45]
	v_cvt_pk_bf16_f32 v33, v32, v33
	v_cvt_pk_bf16_f32 v32, v30, v31
	v_cvt_pk_bf16_f32 v30, v38, v39
	v_cvt_pk_bf16_f32 v31, v40, v41
	ds_write_b128 v153, v[30:33] offset:64
	ds_read_b128 v[30:33], v154
	ds_read_b128 v[38:41], v154 offset:1152
	s_waitcnt lgkmcnt(0)
	global_store_dwordx4 v[58:59], v[30:33], off offset:2048 nt
	global_store_dwordx4 v[58:59], v[38:41], off offset:3072 nt
	s_nop 0
	v_cvt_pk_bf16_f32 v29, v28, v29
	v_cvt_pk_bf16_f32 v28, v26, v27
	v_cvt_pk_bf16_f32 v26, v34, v35
	v_cvt_pk_bf16_f32 v27, v36, v37
	ds_write_b128 v153, v[26:29]
	v_cvt_pk_bf16_f32 v17, v16, v17
	v_cvt_pk_bf16_f32 v16, v14, v15
	v_cvt_pk_bf16_f32 v14, v22, v23
	v_cvt_pk_bf16_f32 v15, v24, v25
	ds_write_b128 v153, v[14:17] offset:64
	ds_read_b128 v[14:17], v154
	ds_read_b128 v[22:25], v154 offset:1152
	s_waitcnt lgkmcnt(0)
	global_store_dwordx4 v[60:61], v[14:17], off nt
	global_store_dwordx4 v[60:61], v[22:25], off offset:1024 nt
	s_nop 0
	v_cvt_pk_bf16_f32 v13, v12, v13
	v_cvt_pk_bf16_f32 v12, v10, v11
	v_cvt_pk_bf16_f32 v10, v18, v19
	v_cvt_pk_bf16_f32 v11, v20, v21
	ds_write_b128 v153, v[10:13]
	v_cvt_pk_bf16_f32 v5, v4, v5
	v_cvt_pk_bf16_f32 v4, v2, v3
	v_cvt_pk_bf16_f32 v2, v6, v7
	v_cvt_pk_bf16_f32 v3, v8, v9
	ds_write_b128 v153, v[2:5] offset:64
	ds_read_b128 v[2:5], v154
	ds_read_b128 v[6:9], v154 offset:1152
	s_andn2_b64 vcc, exec, s[4:5]
	s_mov_b64 s[4:5], -1
	s_waitcnt lgkmcnt(0)
	global_store_dwordx4 v[60:61], v[2:5], off offset:2048 nt
	global_store_dwordx4 v[60:61], v[6:9], off offset:3072 nt
	s_branch .Lp1_epi_join
; __device__ __forceinline__ unsigned cvt_pk_bf16(float lo, float hi) { unsigned r; asm volatile("v_cvt_pk_bf16_f32 %0, %1, %2" : "=v"(r) : "v"(lo), "v"(hi)); return r; }
; __device__ __forceinline__ size_t tm_block(int pm, int ct, int nct) { return ((size_t)pm * nct + ct) * 32768; }
; __device__ __forceinline__ u32x4 pack8(const f32x4& v0, const f32x4& v1) { u32x4 w; w.x = cvt_pk_bf16(v0[0], v0[1]); w.y = cvt_pk_bf16(v0[2], v0[3]); w.z = cvt_pk_bf16(v1[0], v1[1]); w.w = cvt_pk_bf16(v1[2], v1[3]); return w; }
;     __device__ __forceinline__ void operator()(const f32x4 (&acc)[2][2][4][2], const Unit& u, int wr, int wc, int fr, int fq) const {
;         const PieceOut po(scr, O, tm_block(u.pm, u.pn * 4 + wc, nct), wr, wc, fr, fq);
;         const float qs = (u.pn < 2 || u.pn == 3 || u.pn == 4) ? 0.125f * 1.4426950408889634f : 1.0f;
; #pragma unroll
;         for (int ai = 0; ai < 2; ++ai)
; #pragma unroll
;             for (int m = 0; m < 4; ++m) { po.put(0, pack8(acc[ai][0][m][0] * qs, acc[ai][0][m][1] * qs)); po.put(1, pack8(acc[ai][1][m][0] * qs, acc[ai][1][m][1] * qs)); po.flush<true>(ai, m); }
.Lp1_epi_gate:
	v_lshl_add_u64 v[160:161], v[138:139], 0, s[24:25]
	v_add_co_u32_e32 v162, vcc, 0x1000, v160
	s_nop 1
	v_addc_co_u32_e32 v163, vcc, 0, v161, vcc
	v_add_co_u32_e32 v164, vcc, 0x4000, v160
	s_nop 1
	v_addc_co_u32_e32 v165, vcc, 0, v161, vcc
	v_add_co_u32_e32 v166, vcc, 0x5000, v160
	s_nop 1
	v_addc_co_u32_e32 v167, vcc, 0, v161, vcc
	v_cvt_pk_bf16_f32 v125, v124, v125
	v_cvt_pk_bf16_f32 v124, v122, v123
	v_cvt_pk_bf16_f32 v122, v126, v127
	v_cvt_pk_bf16_f32 v123, v128, v129
	global_store_dwordx4 v[160:161], v[122:125], off nt
	v_cvt_pk_bf16_f32 v113, v112, v113
	v_cvt_pk_bf16_f32 v112, v110, v111
	v_cvt_pk_bf16_f32 v110, v118, v119
	v_cvt_pk_bf16_f32 v111, v120, v121
	global_store_dwordx4 v[160:161], v[110:113], off offset:1024 nt
	v_cvt_pk_bf16_f32 v109, v108, v109
	v_cvt_pk_bf16_f32 v108, v106, v107
	v_cvt_pk_bf16_f32 v106, v114, v115
	v_cvt_pk_bf16_f32 v107, v116, v117
	global_store_dwordx4 v[160:161], v[106:109], off offset:2048 nt
	v_cvt_pk_bf16_f32 v97, v96, v97
	v_cvt_pk_bf16_f32 v96, v94, v95
	v_cvt_pk_bf16_f32 v94, v102, v103
	v_cvt_pk_bf16_f32 v95, v104, v105
	global_store_dwordx4 v[160:161], v[94:97], off offset:3072 nt
	v_cvt_pk_bf16_f32 v93, v92, v93
	v_cvt_pk_bf16_f32 v92, v90, v91
	v_cvt_pk_bf16_f32 v90, v98, v99
	v_cvt_pk_bf16_f32 v91, v100, v101
	global_store_dwordx4 v[162:163], v[90:93], off nt
	v_cvt_pk_bf16_f32 v85, v84, v85
	v_cvt_pk_bf16_f32 v84, v82, v83
	v_cvt_pk_bf16_f32 v82, v86, v87
	v_cvt_pk_bf16_f32 v83, v88, v89
	global_store_dwordx4 v[162:163], v[82:85], off offset:1024 nt
	v_cvt_pk_bf16_f32 v77, v76, v77
	v_cvt_pk_bf16_f32 v76, v74, v75
	v_cvt_pk_bf16_f32 v74, v78, v79
	v_cvt_pk_bf16_f32 v75, v80, v81
	global_store_dwordx4 v[162:163], v[74:77], off offset:2048 nt
	v_cvt_pk_bf16_f32 v69, v68, v69
	v_cvt_pk_bf16_f32 v68, v66, v67
	v_cvt_pk_bf16_f32 v66, v70, v71
	v_cvt_pk_bf16_f32 v67, v72, v73
	global_store_dwordx4 v[162:163], v[66:69], off offset:3072 nt
	v_cvt_pk_bf16_f32 v61, v60, v61
	v_cvt_pk_bf16_f32 v60, v58, v59
	v_cvt_pk_bf16_f32 v58, v62, v63
	v_cvt_pk_bf16_f32 v59, v64, v65
	global_store_dwordx4 v[164:165], v[58:61], off nt
	v_cvt_pk_bf16_f32 v53, v52, v53
	v_cvt_pk_bf16_f32 v52, v50, v51
	v_cvt_pk_bf16_f32 v50, v54, v55
	v_cvt_pk_bf16_f32 v51, v56, v57
	global_store_dwordx4 v[164:165], v[50:53], off offset:1024 nt
	v_cvt_pk_bf16_f32 v45, v44, v45
	v_cvt_pk_bf16_f32 v44, v42, v43
	v_cvt_pk_bf16_f32 v42, v46, v47
	v_cvt_pk_bf16_f32 v43, v48, v49
	global_store_dwordx4 v[164:165], v[42:45], off offset:2048 nt
	v_cvt_pk_bf16_f32 v33, v32, v33
	v_cvt_pk_bf16_f32 v32, v30, v31
	v_cvt_pk_bf16_f32 v30, v38, v39
	v_cvt_pk_bf16_f32 v31, v40, v41
	global_store_dwordx4 v[164:165], v[30:33], off offset:3072 nt
	v_cvt_pk_bf16_f32 v29, v28, v29
	v_cvt_pk_bf16_f32 v28, v26, v27
	v_cvt_pk_bf16_f32 v26, v34, v35
	v_cvt_pk_bf16_f32 v27, v36, v37
	global_store_dwordx4 v[166:167], v[26:29], off nt
	v_cvt_pk_bf16_f32 v17, v16, v17
	v_cvt_pk_bf16_f32 v16, v14, v15
	v_cvt_pk_bf16_f32 v14, v22, v23
	v_cvt_pk_bf16_f32 v15, v24, v25
	global_store_dwordx4 v[166:167], v[14:17], off offset:1024 nt
	v_cvt_pk_bf16_f32 v13, v12, v13
	v_cvt_pk_bf16_f32 v12, v10, v11
	v_cvt_pk_bf16_f32 v10, v18, v19
	v_cvt_pk_bf16_f32 v11, v20, v21
	global_store_dwordx4 v[166:167], v[10:13], off offset:2048 nt
	v_cvt_pk_bf16_f32 v5, v4, v5
	v_cvt_pk_bf16_f32 v4, v2, v3
	v_cvt_pk_bf16_f32 v2, v6, v7
	v_cvt_pk_bf16_f32 v3, v8, v9
	global_store_dwordx4 v[166:167], v[2:5], off offset:3072 nt
	s_andn2_b64 vcc, exec, s[4:5]
	s_mov_b64 s[4:5], -1
	s_branch .Lp1_epi_join

; __device__ __forceinline__ size_t tm_block(int pm, int ct, int nct) { return ((size_t)pm * nct + ct) * 32768; }
; #define UNPK0(q_) ((f32x4){bf_lo((q_).x), bf_hi((q_).x), bf_lo((q_).y), bf_hi((q_).y)})
; #define UNPK1(q_) ((f32x4){bf_lo((q_).z), bf_hi((q_).z), bf_lo((q_).w), bf_hi((q_).w)})
;     __device__ __forceinline__ void mid(f32x4 (&acc)[2][2][4][2], const Unit& u, int wr, int wc, int fr, int fq) const {
;         int pm = u.pm, cb = u.pn * 4 + wc;
;         asm volatile("" : "+v"(pm), "+v"(cb));
;         const PieceIn pa(scr, Z, tm_block(pm, ga_ct + cb, znct), wr, wc, fr, fq), pb(scr, Z, tm_block(pm, gb_ct + cb, znct), wr, wc, fr, fq);
;         const int col0 = cb * 64 + 8 * fq;
;         f32x4 ba[2][2], bb[2][2];
; #pragma unroll
;         for (int bj = 0; bj < 2; ++bj) { ba[bj][0] = *(const f32x4*)(bg + col0 + bj * 32); ba[bj][1] = *(const f32x4*)(bg + col0 + bj * 32 + 4); bb[bj][0] = *(const f32x4*)(bg + 1024 + col0 + bj * 32); bb[bj][1] = *(const f32x4*)(bg + 1024 + col0 + bj * 32 + 4); }
; #pragma unroll
;         for (int am = 0; am < 4; ++am) { const int ai = am >> 1;
;             u32x4 ra[4][2], rb[4][2];
; #pragma unroll
;             for (int m = 2 * (am & 1); m < 2 * (am & 1) + 2; ++m) { pa.fetch(ai, m, ra[m][0], ra[m][1]); pb.fetch(ai, m, rb[m][0], rb[m][1]); }
;             asm volatile("" ::: "memory");
; #pragma unroll
;             for (int m = 2 * (am & 1); m < 2 * (am & 1) + 2; ++m) {
;                 pa.stage(ra[m][0], ra[m][1]); const u32x4 ga0 = pa.get(0), ga1 = pa.get(1);
;                 asm volatile("" ::: "memory");
;                 pb.stage(rb[m][0], rb[m][1]); const u32x4 gb0 = pb.get(0), gb1 = pb.get(1);
;                 asm volatile("" ::: "memory");
; #pragma unroll
;                 for (int bj = 0; bj < 2; ++bj) { const u32x4 ga = bj ? ga1 : ga0, gb = bj ? gb1 : gb0;
;                     const f32x4 a0 = UNPK0(ga) + ba[bj][0], a1 = UNPK1(ga) + ba[bj][1], b0 = UNPK0(gb) + bb[bj][0], b1 = UNPK1(gb) + bb[bj][1];
.LBB0_381:
	s_cmp_lg_u32 s46, 0x40000
	s_cbranch_scc1 .LBB0_380
	v_mov_b32_e32 v3, s26
	v_mov_b32_e32 v136, s44
	v_add_u32_e32 v188, v223, v220
	v_add_u32_e32 v4, 36, v136
	v_ashrrev_i32_e32 v5, 31, v4
	v_mad_i64_i32 v[4:5], s[48:49], v3, s83, v[4:5]
	v_add_u32_e32 v134, 52, v136
	v_ashrrev_i32_e32 v135, 31, v134
	v_lshlrev_b64 v[4:5], 15, v[4:5]
	v_lshl_add_u64 v[186:187], v[208:209], 0, v[4:5]
	v_mad_i64_i32 v[4:5], s[48:49], v3, s83, v[134:135]
	global_load_dwordx4 v[190:193], v[186:187], off
	global_load_dwordx4 v[194:197], v[186:187], off offset:1024
	v_lshlrev_b64 v[4:5], 15, v[4:5]
	v_lshl_add_u64 v[4:5], v[208:209], 0, v[4:5]
	global_load_dwordx4 v[228:231], v[4:5], off
	global_load_dwordx4 v[232:235], v[4:5], off offset:1024
	v_lshl_or_b32 v134, v136, 6, v219
	v_ashrrev_i32_e32 v135, 31, v134
	v_lshlrev_b64 v[134:135], 2, v[134:135]
	v_lshl_add_u64 v[138:139], s[42:43], 0, v[134:135]
	v_add_co_u32_e32 v166, vcc, s84, v138
	v_lshl_add_u64 v[140:141], s[16:17], 0, v[134:135]
	global_load_dwordx4 v[150:153], v[138:139], off offset:16
	global_load_dwordx4 v[158:161], v[138:139], off
	global_load_dwordx4 v[162:165], v[140:141], off
	v_addc_co_u32_e32 v167, vcc, 0, v139, vcc
	global_load_dwordx4 v[154:157], v[166:167], off offset:16
	global_load_dwordx4 v[134:137], v[138:139], off offset:144
	global_load_dwordx4 v[142:145], v[138:139], off offset:128
	global_load_dwordx4 v[146:149], v[140:141], off offset:128
	s_nop 0
	global_load_dwordx4 v[138:141], v[166:167], off offset:144
	global_load_dwordx4 v[174:177], v[186:187], off offset:2048
	global_load_dwordx4 v[178:181], v[186:187], off offset:3072
	s_nop 0
	global_load_dwordx4 v[166:169], v[4:5], off offset:2048
	global_load_dwordx4 v[170:173], v[4:5], off offset:3072
	v_add_u32_e32 v3, v224, v222
	s_waitcnt vmcnt(0)
	v_mul_f32_e32 v134, 0xbfb8aa3b, v134
	v_mul_f32_e32 v135, 0xbfb8aa3b, v135
	v_mul_f32_e32 v136, 0xbfb8aa3b, v136
	v_mul_f32_e32 v137, 0xbfb8aa3b, v137
	v_mul_f32_e32 v138, 0xbfb8aa3b, v138
	v_mul_f32_e32 v139, 0xbfb8aa3b, v139
	v_mul_f32_e32 v140, 0xbfb8aa3b, v140
	v_mul_f32_e32 v141, 0xbfb8aa3b, v141
	v_mul_f32_e32 v142, 0xbfb8aa3b, v142
	v_mul_f32_e32 v143, 0xbfb8aa3b, v143
	v_mul_f32_e32 v144, 0xbfb8aa3b, v144
	v_mul_f32_e32 v145, 0xbfb8aa3b, v145
	v_mul_f32_e32 v146, 0xbfb8aa3b, v146
	v_mul_f32_e32 v147, 0xbfb8aa3b, v147
	v_mul_f32_e32 v148, 0xbfb8aa3b, v148
	v_mul_f32_e32 v149, 0xbfb8aa3b, v149
	v_mul_f32_e32 v150, 0xbfb8aa3b, v150
	v_mul_f32_e32 v151, 0xbfb8aa3b, v151
	v_mul_f32_e32 v152, 0xbfb8aa3b, v152
	v_mul_f32_e32 v153, 0xbfb8aa3b, v153
	v_mul_f32_e32 v154, 0xbfb8aa3b, v154
	v_mul_f32_e32 v155, 0xbfb8aa3b, v155
	v_mul_f32_e32 v156, 0xbfb8aa3b, v156
	v_mul_f32_e32 v157, 0xbfb8aa3b, v157
	v_mul_f32_e32 v158, 0xbfb8aa3b, v158
	v_mul_f32_e32 v159, 0xbfb8aa3b, v159
	v_mul_f32_e32 v160, 0xbfb8aa3b, v160
	v_mul_f32_e32 v161, 0xbfb8aa3b, v161
	v_mul_f32_e32 v162, 0xbfb8aa3b, v162
	v_mul_f32_e32 v163, 0xbfb8aa3b, v163
	v_mul_f32_e32 v164, 0xbfb8aa3b, v164
	v_mul_f32_e32 v165, 0xbfb8aa3b, v165
	v_lshlrev_b32_e32 v189, 16, v190
	v_and_b32_e32 v190, 0xffff0000, v190
	v_lshlrev_b32_e32 v227, 16, v191
	v_and_b32_e32 v237, 0xffff0000, v191
	v_lshlrev_b32_e32 v191, 16, v192
	v_fma_f32 v189, v189, s89, v158
	v_and_b32_e32 v192, 0xffff0000, v192
	v_lshlrev_b32_e32 v239, 16, v193
	v_and_b32_e32 v241, 0xffff0000, v193
	v_lshlrev_b32_e32 v193, 16, v228
	v_and_b32_e32 v228, 0xffff0000, v228
	v_lshlrev_b32_e32 v236, 16, v229
	v_and_b32_e32 v242, 0xffff0000, v229
	v_lshlrev_b32_e32 v229, 16, v230
	v_fma_f32 v191, v191, s89, v150
	v_fma_f32 v190, v190, s89, v159
	v_fma_f32 v192, v192, s89, v151
	v_fma_f32 v193, v193, s89, v162
	v_fma_f32 v229, v229, s89, v154
	v_fma_f32 v228, v228, s89, v163
	v_med3_f32 v189, v189, s85, v226
	v_med3_f32 v191, v191, s85, v226
	v_med3_f32 v190, v190, s85, v226
	v_exp_f32_e32 v189, v189
	v_med3_f32 v238, v192, s85, v226
	v_med3_f32 v192, v193, s85, v226
	v_med3_f32 v193, v229, s85, v226
	v_exp_f32_e32 v229, v191
	v_med3_f32 v191, v228, s85, v226
	v_exp_f32_e32 v228, v190
	v_add_f32_e32 v189, 1.0, v189
	v_exp_f32_e32 v190, v192
	v_exp_f32_e32 v192, v193
	v_add_f32_e32 v193, 1.0, v229
	v_add_f32_e32 v229, 1.0, v228
	v_rcp_f32_e32 v228, v189
	v_exp_f32_e32 v189, v238
	v_fma_f32 v227, v227, s89, v160
	v_and_b32_e32 v230, 0xffff0000, v230
	v_med3_f32 v227, v227, s85, v226
	v_lshlrev_b32_e32 v240, 16, v231
	v_and_b32_e32 v243, 0xffff0000, v231
	v_fma_f32 v231, v230, s89, v155
	v_add_f32_e32 v189, 1.0, v189
	v_exp_f32_e32 v227, v227
	v_rcp_f32_e32 v230, v193
	v_med3_f32 v193, v231, s85, v226
	v_rcp_f32_e32 v231, v189
	v_fma_f32 v189, v236, s89, v164
	v_med3_f32 v189, v189, s85, v226
	v_exp_f32_e32 v236, v189
	v_add_f32_e32 v189, 1.0, v227
	v_fma_f32 v227, v239, s89, v152
	v_med3_f32 v227, v227, s85, v226
	v_exp_f32_e32 v227, v227
	v_rcp_f32_e32 v238, v189
	v_fma_f32 v189, v240, s89, v156
	v_med3_f32 v189, v189, s85, v226
	v_fma_f32 v237, v237, s89, v161
	v_exp_f32_e32 v240, v189
	v_add_f32_e32 v189, 1.0, v227
	v_fma_f32 v227, v242, s89, v165
	v_med3_f32 v237, v237, s85, v226
	v_exp_f32_e32 v239, v237
	v_med3_f32 v227, v227, s85, v226
	v_exp_f32_e32 v237, v227
	v_fma_f32 v227, v241, s89, v153
	v_med3_f32 v227, v227, s85, v226
	v_rcp_f32_e32 v242, v189
	v_add_f32_e32 v189, 1.0, v239
	v_exp_f32_e32 v227, v227
	v_rcp_f32_e32 v239, v189
	v_fma_f32 v189, v243, s89, v157
	v_exp_f32_e32 v193, v193
	v_med3_f32 v189, v189, s85, v226
	v_exp_f32_e32 v241, v189
	v_add_f32_e32 v189, 1.0, v227
	v_exp_f32_e32 v191, v191
	v_rcp_f32_e32 v243, v189
	v_lshlrev_b32_e32 v189, 16, v194
	v_rcp_f32_e32 v229, v229
	v_fma_f32 v189, v189, s89, v142
	v_pk_add_f32 v[192:193], v[192:193], 1.0 op_sel_hi:[1,0]
; #define UNPK0(q_) ((f32x4){bf_lo((q_).x), bf_hi((q_).x), bf_lo((q_).y), bf_hi((q_).y)})
; #define UNPK1(q_) ((f32x4){bf_lo((q_).z), bf_hi((q_).z), bf_lo((q_).w), bf_hi((q_).w)})
;     static __device__ __forceinline__ float eneg(float g) { return __builtin_amdgcn_exp2f(-1.4426950408889634f * fminf(fmaxf(g, -30.f), 30.f)); }
;     __device__ __forceinline__ void mid(f32x4 (&acc)[2][2][4][2], const Unit& u, int wr, int wc, int fr, int fq) const {
;     ...
;         for (int am = 0; am < 4; ++am) { const int ai = am >> 1;
;             u32x4 ra[4][2], rb[4][2];
; #pragma unroll
;             for (int m = 2 * (am & 1); m < 2 * (am & 1) + 2; ++m) { pa.fetch(ai, m, ra[m][0], ra[m][1]); pb.fetch(ai, m, rb[m][0], rb[m][1]); }
;             asm volatile("" ::: "memory");
; #pragma unroll
;             for (int m = 2 * (am & 1); m < 2 * (am & 1) + 2; ++m) {
;                 pa.stage(ra[m][0], ra[m][1]); const u32x4 ga0 = pa.get(0), ga1 = pa.get(1);
;                 asm volatile("" ::: "memory");
;                 pb.stage(rb[m][0], rb[m][1]); const u32x4 gb0 = pb.get(0), gb1 = pb.get(1);
;                 asm volatile("" ::: "memory");
; #pragma unroll
;                 for (int bj = 0; bj < 2; ++bj) { const u32x4 ga = bj ? ga1 : ga0, gb = bj ? gb1 : gb0;
;                     const f32x4 a0 = UNPK0(ga) + ba[bj][0], a1 = UNPK1(ga) + ba[bj][1], b0 = UNPK0(gb) + bb[bj][0], b1 = UNPK1(gb) + bb[bj][1];
; #pragma unroll
;                     for (int k = 0; k < 4; ++k) { acc[ai][bj][m][0][k] *= (1.0f + eneg(b0[k])) * __builtin_amdgcn_rcpf(1.0f + eneg(a0[k]));
;                                                   acc[ai][bj][m][1][k] *= (1.0f + eneg(b1[k])) * __builtin_amdgcn_rcpf(1.0f + eneg(a1[k])); } } }
	v_pk_mul_f32 v[192:193], v[230:231], v[192:193]
	v_med3_f32 v189, v189, s85, v226
	v_pk_add_f32 v[190:191], v[190:191], 1.0 op_sel_hi:[1,0]
	v_pk_mul_f32 v[126:127], v[126:127], v[192:193]
	v_lshlrev_b32_e32 v193, 16, v196
	v_exp_f32_e32 v189, v189
	v_pk_mul_f32 v[190:191], v[228:229], v[190:191]
	v_fma_f32 v193, v193, s89, v134
	v_pk_mul_f32 v[130:131], v[130:131], v[190:191]
	v_pk_add_f32 v[190:191], v[240:241], 1.0 op_sel_hi:[1,0]
	v_pk_mul_f32 v[190:191], v[242:243], v[190:191]
	v_med3_f32 v193, v193, s85, v226
	v_pk_mul_f32 v[128:129], v[128:129], v[190:191]
	v_and_b32_e32 v191, 0xffff0000, v194
	v_lshlrev_b32_e32 v194, 16, v234
	v_add_f32_e32 v189, 1.0, v189
	v_exp_f32_e32 v193, v193
	v_rcp_f32_e32 v192, v189
	v_fma_f32 v189, v194, s89, v138
	v_fma_f32 v191, v191, s89, v143
	v_pk_add_f32 v[236:237], v[236:237], 1.0 op_sel_hi:[1,0]
	v_pk_mul_f32 v[228:229], v[238:239], v[236:237]
	v_med3_f32 v189, v189, s85, v226
	v_med3_f32 v191, v191, s85, v226
	v_pk_mul_f32 v[132:133], v[132:133], v[228:229]
	v_lshlrev_b32_e32 v227, 16, v195
	v_and_b32_e32 v229, 0xffff0000, v195
	v_and_b32_e32 v195, 0xffff0000, v196
	v_lshlrev_b32_e32 v231, 16, v197
	v_and_b32_e32 v236, 0xffff0000, v197
	v_and_b32_e32 v197, 0xffff0000, v232
	v_exp_f32_e32 v194, v189
	v_add_f32_e32 v189, 1.0, v193
	v_exp_f32_e32 v193, v191
	v_rcp_f32_e32 v196, v189
	v_fma_f32 v189, v197, s89, v147
	v_fma_f32 v195, v195, s89, v135
	v_med3_f32 v189, v189, s85, v226
	v_med3_f32 v195, v195, s85, v226
	v_and_b32_e32 v230, 0xffff0000, v234
	v_exp_f32_e32 v191, v189
	v_add_f32_e32 v189, 1.0, v193
	v_exp_f32_e32 v197, v195
	v_rcp_f32_e32 v193, v189
	v_fma_f32 v189, v230, s89, v139
	v_fma_f32 v227, v227, s89, v144
	v_med3_f32 v189, v189, s85, v226
	v_med3_f32 v227, v227, s85, v226
	v_lshlrev_b32_e32 v228, 16, v233
	v_exp_f32_e32 v195, v189
	v_add_f32_e32 v189, 1.0, v197
	v_exp_f32_e32 v227, v227
	v_rcp_f32_e32 v197, v189
	v_fma_f32 v189, v228, s89, v148
	v_med3_f32 v189, v189, s85, v226
	v_exp_f32_e32 v228, v189
	v_add_f32_e32 v189, 1.0, v227
	v_fma_f32 v227, v231, s89, v136
	v_med3_f32 v227, v227, s85, v226
	v_lshlrev_b32_e32 v190, 16, v232
	v_lshlrev_b32_e32 v232, 16, v235
	v_exp_f32_e32 v227, v227
	v_fma_f32 v229, v229, s89, v145
	v_rcp_f32_e32 v230, v189
	v_fma_f32 v189, v232, s89, v140
	v_med3_f32 v229, v229, s85, v226
	v_and_b32_e32 v233, 0xffff0000, v233
	v_med3_f32 v189, v189, s85, v226
	v_exp_f32_e32 v231, v229
	v_fma_f32 v190, v190, s89, v146
	v_exp_f32_e32 v232, v189
	v_add_f32_e32 v189, 1.0, v227
	v_fma_f32 v227, v233, s89, v149
	v_med3_f32 v190, v190, s85, v226
	v_med3_f32 v227, v227, s85, v226
	v_exp_f32_e32 v190, v190
	v_exp_f32_e32 v229, v227
	v_rcp_f32_e32 v234, v189
	v_add_f32_e32 v189, 1.0, v231
	v_rcp_f32_e32 v231, v189
	v_pk_add_f32 v[228:229], v[228:229], 1.0 op_sel_hi:[1,0]
	v_pk_add_f32 v[190:191], v[190:191], 1.0 op_sel_hi:[1,0]
	v_and_b32_e32 v235, 0xffff0000, v235
	v_pk_mul_f32 v[190:191], v[192:193], v[190:191]
	v_pk_mul_f32 v[192:193], v[230:231], v[228:229]
	v_fma_f32 v189, v235, s89, v141
	v_pk_mul_f32 v[124:125], v[124:125], v[192:193]
	v_fma_f32 v192, v236, s89, v137
	v_med3_f32 v192, v192, s85, v226
	v_exp_f32_e32 v192, v192
	v_med3_f32 v189, v189, s85, v226
	v_exp_f32_e32 v233, v189
	v_add_f32_e32 v189, 1.0, v192
	v_rcp_f32_e32 v235, v189
	v_pk_mul_f32 v[122:123], v[122:123], v[190:191]
	v_pk_add_f32 v[190:191], v[232:233], 1.0 op_sel_hi:[1,0]
	v_lshlrev_b32_e32 v189, 16, v174
	v_pk_mul_f32 v[190:191], v[234:235], v[190:191]
	v_lshlrev_b32_e32 v227, 16, v169
	v_pk_mul_f32 v[120:121], v[120:121], v[190:191]
	v_and_b32_e32 v190, 0xffff0000, v174
	v_lshlrev_b32_e32 v174, 16, v176
	v_and_b32_e32 v228, 0xffff0000, v169
	v_fma_f32 v169, v174, s89, v150
	v_pk_add_f32 v[192:193], v[194:195], 1.0 op_sel_hi:[1,0]
	v_pk_mul_f32 v[192:193], v[196:197], v[192:193]
	v_med3_f32 v169, v169, s85, v226
	v_pk_mul_f32 v[118:119], v[118:119], v[192:193]
	v_lshlrev_b32_e32 v191, 16, v175
	v_and_b32_e32 v193, 0xffff0000, v175
	v_and_b32_e32 v175, 0xffff0000, v176
	v_lshlrev_b32_e32 v192, 16, v167
	v_and_b32_e32 v196, 0xffff0000, v167
	v_lshlrev_b32_e32 v167, 16, v168
	v_exp_f32_e32 v169, v169
	v_fma_f32 v167, v167, s89, v154
	v_fma_f32 v175, v175, s89, v151
	v_med3_f32 v167, v167, s85, v226
	v_med3_f32 v175, v175, s85, v226
	v_and_b32_e32 v197, 0xffff0000, v168
	v_fma_f32 v168, v189, s89, v158
	v_exp_f32_e32 v174, v167
	v_add_f32_e32 v167, 1.0, v169
	v_fma_f32 v169, v190, s89, v159
	v_exp_f32_e32 v189, v175
	v_fma_f32 v190, v191, s89, v160
	v_lshlrev_b32_e32 v194, 16, v177
	v_and_b32_e32 v195, 0xffff0000, v177
	v_lshlrev_b32_e32 v176, 16, v166
	v_and_b32_e32 v177, 0xffff0000, v166
	v_med3_f32 v190, v190, s85, v226
	v_fma_f32 v166, v176, s89, v162
	v_rcp_f32_e32 v176, v167
	v_fma_f32 v167, v177, s89, v163
	v_fma_f32 v177, v197, s89, v155
	v_exp_f32_e32 v191, v190
	v_med3_f32 v175, v177, s85, v226
	v_add_f32_e32 v177, 1.0, v189
	v_fma_f32 v189, v192, s89, v164
	v_med3_f32 v189, v189, s85, v226
	v_exp_f32_e32 v190, v189
	v_add_f32_e32 v189, 1.0, v191
	v_fma_f32 v191, v194, s89, v152
	v_med3_f32 v191, v191, s85, v226
	v_exp_f32_e32 v191, v191
	v_fma_f32 v193, v193, s89, v161
	v_rcp_f32_e32 v192, v189
	v_fma_f32 v189, v227, s89, v156
	v_med3_f32 v168, v168, s85, v226
	v_med3_f32 v169, v169, s85, v226
	v_med3_f32 v193, v193, s85, v226
	v_exp_f32_e32 v168, v168
	v_exp_f32_e32 v169, v169
	v_med3_f32 v189, v189, s85, v226
	v_exp_f32_e32 v193, v193
	v_exp_f32_e32 v194, v189
	v_add_f32_e32 v189, 1.0, v191
	v_fma_f32 v191, v196, s89, v165
	v_med3_f32 v166, v166, s85, v226
	v_med3_f32 v167, v167, s85, v226
	v_med3_f32 v191, v191, s85, v226
	v_exp_f32_e32 v166, v166
	v_add_f32_e32 v168, 1.0, v168
; #define UNPK0(q_) ((f32x4){bf_lo((q_).x), bf_hi((q_).x), bf_lo((q_).y), bf_hi((q_).y)})
; #define UNPK1(q_) ((f32x4){bf_lo((q_).z), bf_hi((q_).z), bf_lo((q_).w), bf_hi((q_).w)})
;     static __device__ __forceinline__ float eneg(float g) { return __builtin_amdgcn_exp2f(-1.4426950408889634f * fminf(fmaxf(g, -30.f), 30.f)); }
;     __device__ __forceinline__ void mid(f32x4 (&acc)[2][2][4][2], const Unit& u, int wr, int wc, int fr, int fq) const {
;     ...
;         for (int am = 0; am < 4; ++am) { const int ai = am >> 1;
;             u32x4 ra[4][2], rb[4][2];
; #pragma unroll
;             for (int m = 2 * (am & 1); m < 2 * (am & 1) + 2; ++m) { pa.fetch(ai, m, ra[m][0], ra[m][1]); pb.fetch(ai, m, rb[m][0], rb[m][1]); }
;             asm volatile("" ::: "memory");
; #pragma unroll
;             for (int m = 2 * (am & 1); m < 2 * (am & 1) + 2; ++m) {
;                 pa.stage(ra[m][0], ra[m][1]); const u32x4 ga0 = pa.get(0), ga1 = pa.get(1);
;                 asm volatile("" ::: "memory");
;                 pb.stage(rb[m][0], rb[m][1]); const u32x4 gb0 = pb.get(0), gb1 = pb.get(1);
;                 asm volatile("" ::: "memory");
; #pragma unroll
;                 for (int bj = 0; bj < 2; ++bj) { const u32x4 ga = bj ? ga1 : ga0, gb = bj ? gb1 : gb0;
;                     const f32x4 a0 = UNPK0(ga) + ba[bj][0], a1 = UNPK1(ga) + ba[bj][1], b0 = UNPK0(gb) + bb[bj][0], b1 = UNPK1(gb) + bb[bj][1];
; #pragma unroll
;                     for (int k = 0; k < 4; ++k) { acc[ai][bj][m][0][k] *= (1.0f + eneg(b0[k])) * __builtin_amdgcn_rcpf(1.0f + eneg(a0[k]));
;                                                   acc[ai][bj][m][1][k] *= (1.0f + eneg(b1[k])) * __builtin_amdgcn_rcpf(1.0f + eneg(a1[k])); } } }
	v_exp_f32_e32 v167, v167
	v_add_f32_e32 v169, 1.0, v169
	v_exp_f32_e32 v191, v191
	v_rcp_f32_e32 v196, v189
	v_add_f32_e32 v189, 1.0, v193
	v_rcp_f32_e32 v168, v168
	v_rcp_f32_e32 v169, v169
	v_rcp_f32_e32 v193, v189
	v_pk_add_f32 v[190:191], v[190:191], 1.0 op_sel_hi:[1,0]
	v_pk_add_f32 v[166:167], v[166:167], 1.0 op_sel_hi:[1,0]
	v_pk_mul_f32 v[166:167], v[168:169], v[166:167]
	v_pk_mul_f32 v[168:169], v[192:193], v[190:191]
	v_exp_f32_e32 v175, v175
	v_pk_mul_f32 v[116:117], v[116:117], v[168:169]
	v_fma_f32 v169, v195, s89, v153
	v_med3_f32 v169, v169, s85, v226
	v_exp_f32_e32 v169, v169
	v_fma_f32 v168, v228, s89, v157
	v_med3_f32 v168, v168, s85, v226
	v_rcp_f32_e32 v177, v177
	v_exp_f32_e32 v195, v168
	v_pk_mul_f32 v[114:115], v[114:115], v[166:167]
	v_add_f32_e32 v166, 1.0, v169
	v_rcp_f32_e32 v197, v166
	v_pk_add_f32 v[168:169], v[174:175], 1.0 op_sel_hi:[1,0]
	v_pk_add_f32 v[166:167], v[194:195], 1.0 op_sel_hi:[1,0]
	v_pk_mul_f32 v[168:169], v[176:177], v[168:169]
	v_pk_mul_f32 v[166:167], v[196:197], v[166:167]
	v_pk_mul_f32 v[110:111], v[110:111], v[168:169]
	v_lshlrev_b32_e32 v169, 16, v180
	v_pk_mul_f32 v[112:113], v[112:113], v[166:167]
	v_lshlrev_b32_e32 v166, 16, v178
	v_fma_f32 v169, v169, s89, v134
	v_fma_f32 v166, v166, s89, v142
	v_med3_f32 v169, v169, s85, v226
	v_med3_f32 v166, v166, s85, v226
	v_exp_f32_e32 v169, v169
	v_and_b32_e32 v167, 0xffff0000, v178
	v_and_b32_e32 v176, 0xffff0000, v180
	v_lshlrev_b32_e32 v168, 16, v170
	v_and_b32_e32 v178, 0xffff0000, v170
	v_lshlrev_b32_e32 v180, 16, v171
	v_and_b32_e32 v189, 0xffff0000, v171
	v_lshlrev_b32_e32 v170, 16, v172
	v_and_b32_e32 v171, 0xffff0000, v172
	v_exp_f32_e32 v172, v166
	v_fma_f32 v168, v168, s89, v146
	v_add_f32_e32 v169, 1.0, v169
	v_med3_f32 v166, v168, s85, v226
	v_add_f32_e32 v168, 1.0, v172
	v_rcp_f32_e32 v172, v169
	v_fma_f32 v169, v178, s89, v147
	v_add_co_u32_e32 v178, vcc, s84, v186
	v_lshlrev_b32_e32 v174, 16, v179
	v_and_b32_e32 v175, 0xffff0000, v179
	v_addc_co_u32_e32 v179, vcc, 0, v187, vcc
	global_load_dwordx4 v[190:193], v[178:179], off
	global_load_dwordx4 v[194:197], v[178:179], off offset:1024
	v_add_co_u32_e32 v236, vcc, s84, v4
	v_fma_f32 v167, v167, s89, v143
	s_nop 0
	v_addc_co_u32_e32 v237, vcc, 0, v5, vcc
	global_load_dwordx4 v[228:231], v[236:237], off
	global_load_dwordx4 v[232:235], v[236:237], off offset:1024
	v_med3_f32 v167, v167, s85, v226
	v_lshlrev_b32_e32 v227, 16, v173
	v_and_b32_e32 v239, 0xffff0000, v173
	v_exp_f32_e32 v173, v167
	v_fma_f32 v174, v174, s89, v144
	v_lshlrev_b32_e32 v177, 16, v181
	v_med3_f32 v174, v174, s85, v226
	v_med3_f32 v167, v169, s85, v226
	v_add_f32_e32 v169, 1.0, v173
	v_fma_f32 v173, v176, s89, v135
	v_fma_f32 v176, v180, s89, v148
	v_exp_f32_e32 v180, v174
	v_fma_f32 v177, v177, s89, v136
	v_fma_f32 v175, v175, s89, v145
	v_med3_f32 v177, v177, s85, v226
	v_exp_f32_e32 v177, v177
	v_med3_f32 v175, v175, s85, v226
	v_med3_f32 v174, v176, s85, v226
	v_add_f32_e32 v176, 1.0, v180
	v_fma_f32 v180, v227, s89, v140
	v_exp_f32_e32 v227, v175
	v_fma_f32 v189, v189, s89, v149
	v_add_f32_e32 v177, 1.0, v177
	v_med3_f32 v175, v189, s85, v226
	v_exp_f32_e32 v166, v166
	v_exp_f32_e32 v167, v167
	v_exp_f32_e32 v174, v174
	v_exp_f32_e32 v175, v175
	v_rcp_f32_e32 v238, v177
	v_add_f32_e32 v177, 1.0, v227
	v_rcp_f32_e32 v168, v168
	v_rcp_f32_e32 v169, v169
	v_rcp_f32_e32 v176, v176
	v_rcp_f32_e32 v177, v177
	v_pk_add_f32 v[174:175], v[174:175], 1.0 op_sel_hi:[1,0]
	v_pk_add_f32 v[166:167], v[166:167], 1.0 op_sel_hi:[1,0]
	v_and_b32_e32 v181, 0xffff0000, v181
	v_pk_mul_f32 v[166:167], v[168:169], v[166:167]
	v_pk_mul_f32 v[168:169], v[176:177], v[174:175]
	v_pk_mul_f32 v[108:109], v[108:109], v[168:169]
	v_fma_f32 v169, v181, s89, v137
	v_med3_f32 v173, v173, s85, v226
	v_med3_f32 v169, v169, s85, v226
	v_exp_f32_e32 v173, v173
	v_exp_f32_e32 v169, v169
	v_fma_f32 v170, v170, s89, v138
	v_fma_f32 v171, v171, s89, v139
	v_fma_f32 v168, v239, s89, v141
	v_med3_f32 v170, v170, s85, v226
	v_med3_f32 v171, v171, s85, v226
	v_med3_f32 v180, v180, s85, v226
	v_med3_f32 v168, v168, s85, v226
	v_exp_f32_e32 v170, v170
	v_exp_f32_e32 v171, v171
	v_add_f32_e32 v173, 1.0, v173
	v_exp_f32_e32 v180, v180
	v_exp_f32_e32 v181, v168
	v_pk_mul_f32 v[106:107], v[106:107], v[166:167]
	v_add_f32_e32 v166, 1.0, v169
	v_rcp_f32_e32 v173, v173
	v_rcp_f32_e32 v239, v166
	v_pk_add_f32 v[166:167], v[180:181], 1.0 op_sel_hi:[1,0]
	v_pk_add_f32 v[168:169], v[170:171], 1.0 op_sel_hi:[1,0]
	v_pk_mul_f32 v[166:167], v[238:239], v[166:167]
	v_pk_mul_f32 v[168:169], v[172:173], v[168:169]
	v_pk_mul_f32 v[104:105], v[104:105], v[166:167]
	v_pk_mul_f32 v[102:103], v[102:103], v[168:169]
	global_load_dwordx4 v[174:177], v[178:179], off offset:2048
	s_nop 0
	global_load_dwordx4 v[178:181], v[178:179], off offset:3072
	s_nop 0
	global_load_dwordx4 v[166:169], v[236:237], off offset:2048
	global_load_dwordx4 v[170:173], v[236:237], off offset:3072
	s_waitcnt vmcnt(7)
	s_waitcnt vmcnt(6)
	s_waitcnt vmcnt(5)
	s_waitcnt vmcnt(4)
; #define UNPK0(q_) ((f32x4){bf_lo((q_).x), bf_hi((q_).x), bf_lo((q_).y), bf_hi((q_).y)})
; #define UNPK1(q_) ((f32x4){bf_lo((q_).z), bf_hi((q_).z), bf_lo((q_).w), bf_hi((q_).w)})
;     static __device__ __forceinline__ float eneg(float g) { return __builtin_amdgcn_exp2f(-1.4426950408889634f * fminf(fmaxf(g, -30.f), 30.f)); }
;     __device__ __forceinline__ void mid(f32x4 (&acc)[2][2][4][2], const Unit& u, int wr, int wc, int fr, int fq) const {
;     ...
;         for (int am = 0; am < 4; ++am) { const int ai = am >> 1;
;             u32x4 ra[4][2], rb[4][2];
; #pragma unroll
;             for (int m = 2 * (am & 1); m < 2 * (am & 1) + 2; ++m) { pa.fetch(ai, m, ra[m][0], ra[m][1]); pb.fetch(ai, m, rb[m][0], rb[m][1]); }
;             asm volatile("" ::: "memory");
; #pragma unroll
;             for (int m = 2 * (am & 1); m < 2 * (am & 1) + 2; ++m) {
;                 pa.stage(ra[m][0], ra[m][1]); const u32x4 ga0 = pa.get(0), ga1 = pa.get(1);
;                 asm volatile("" ::: "memory");
;                 pb.stage(rb[m][0], rb[m][1]); const u32x4 gb0 = pb.get(0), gb1 = pb.get(1);
;                 asm volatile("" ::: "memory");
; #pragma unroll
;                 for (int bj = 0; bj < 2; ++bj) { const u32x4 ga = bj ? ga1 : ga0, gb = bj ? gb1 : gb0;
;                     const f32x4 a0 = UNPK0(ga) + ba[bj][0], a1 = UNPK1(ga) + ba[bj][1], b0 = UNPK0(gb) + bb[bj][0], b1 = UNPK1(gb) + bb[bj][1];
; #pragma unroll
;                     for (int k = 0; k < 4; ++k) { acc[ai][bj][m][0][k] *= (1.0f + eneg(b0[k])) * __builtin_amdgcn_rcpf(1.0f + eneg(a0[k]));
;                                                   acc[ai][bj][m][1][k] *= (1.0f + eneg(b1[k])) * __builtin_amdgcn_rcpf(1.0f + eneg(a1[k])); } } }
	v_lshlrev_b32_e32 v189, 16, v190
	v_fma_f32 v189, v189, s89, v158
	v_med3_f32 v189, v189, s85, v226
	v_lshlrev_b32_e32 v236, 16, v191
	v_and_b32_e32 v237, 0xffff0000, v191
	v_lshlrev_b32_e32 v191, 16, v192
	v_exp_f32_e32 v189, v189
	v_fma_f32 v191, v191, s89, v150
	v_med3_f32 v191, v191, s85, v226
	v_and_b32_e32 v227, 0xffff0000, v190
	v_lshlrev_b32_e32 v239, 16, v193
	v_and_b32_e32 v241, 0xffff0000, v193
	v_lshlrev_b32_e32 v190, 16, v228
	v_and_b32_e32 v193, 0xffff0000, v228
	v_lshlrev_b32_e32 v228, 16, v230
	v_add_f32_e32 v189, 1.0, v189
	v_exp_f32_e32 v191, v191
	v_and_b32_e32 v238, 0xffff0000, v192
	v_rcp_f32_e32 v192, v189
	v_fma_f32 v189, v228, s89, v154
	v_med3_f32 v189, v189, s85, v226
	v_exp_f32_e32 v228, v189
	v_add_f32_e32 v189, 1.0, v191
	v_fma_f32 v191, v227, s89, v159
	v_med3_f32 v191, v191, s85, v226
	v_lshlrev_b32_e32 v240, 16, v229
	v_and_b32_e32 v242, 0xffff0000, v229
	v_and_b32_e32 v229, 0xffff0000, v230
	v_rcp_f32_e32 v230, v189
	v_fma_f32 v189, v193, s89, v163
	v_exp_f32_e32 v193, v191
	v_fma_f32 v227, v238, s89, v151
	v_med3_f32 v189, v189, s85, v226
	v_med3_f32 v227, v227, s85, v226
	v_exp_f32_e32 v191, v189
	v_add_f32_e32 v189, 1.0, v193
	v_exp_f32_e32 v227, v227
	v_rcp_f32_e32 v193, v189
	v_fma_f32 v189, v229, s89, v155
	v_med3_f32 v189, v189, s85, v226
	v_exp_f32_e32 v229, v189
	v_add_f32_e32 v189, 1.0, v227
	v_fma_f32 v227, v236, s89, v160
	v_med3_f32 v227, v227, s85, v226
	v_exp_f32_e32 v227, v227
	v_lshlrev_b32_e32 v243, 16, v231
	v_and_b32_e32 v244, 0xffff0000, v231
	v_rcp_f32_e32 v231, v189
	v_fma_f32 v189, v240, s89, v164
	v_med3_f32 v189, v189, s85, v226
	v_exp_f32_e32 v236, v189
	v_add_f32_e32 v189, 1.0, v227
	v_fma_f32 v227, v239, s89, v152
	v_med3_f32 v227, v227, s85, v226
	v_exp_f32_e32 v227, v227
	v_fma_f32 v237, v237, s89, v161
	v_rcp_f32_e32 v238, v189
	v_fma_f32 v189, v243, s89, v156
	v_med3_f32 v237, v237, s85, v226
	v_med3_f32 v189, v189, s85, v226
	v_exp_f32_e32 v239, v237
	v_fma_f32 v190, v190, s89, v162
	v_exp_f32_e32 v240, v189
	v_add_f32_e32 v189, 1.0, v227
	v_fma_f32 v227, v242, s89, v165
	v_med3_f32 v190, v190, s85, v226
	v_med3_f32 v227, v227, s85, v226
	v_exp_f32_e32 v190, v190
	v_exp_f32_e32 v237, v227
	v_rcp_f32_e32 v242, v189
	v_add_f32_e32 v189, 1.0, v239
	v_rcp_f32_e32 v239, v189
	v_pk_add_f32 v[236:237], v[236:237], 1.0 op_sel_hi:[1,0]
	v_pk_add_f32 v[190:191], v[190:191], 1.0 op_sel_hi:[1,0]
	v_fma_f32 v189, v244, s89, v157
	v_pk_mul_f32 v[190:191], v[192:193], v[190:191]
	v_pk_mul_f32 v[192:193], v[238:239], v[236:237]
	v_pk_mul_f32 v[100:101], v[100:101], v[192:193]
	v_fma_f32 v192, v241, s89, v153
	v_med3_f32 v192, v192, s85, v226
	v_exp_f32_e32 v192, v192
	v_med3_f32 v189, v189, s85, v226
	v_exp_f32_e32 v241, v189
	v_pk_mul_f32 v[98:99], v[98:99], v[190:191]
	v_add_f32_e32 v189, 1.0, v192
	v_rcp_f32_e32 v243, v189
	v_lshlrev_b32_e32 v189, 16, v194
	v_fma_f32 v189, v189, s89, v142
	v_pk_add_f32 v[192:193], v[228:229], 1.0 op_sel_hi:[1,0]
	v_pk_mul_f32 v[192:193], v[230:231], v[192:193]
	v_med3_f32 v189, v189, s85, v226
	v_pk_mul_f32 v[94:95], v[94:95], v[192:193]
	v_lshlrev_b32_e32 v193, 16, v196
	v_exp_f32_e32 v189, v189
	v_fma_f32 v193, v193, s89, v134
	v_pk_add_f32 v[190:191], v[240:241], 1.0 op_sel_hi:[1,0]
	v_pk_mul_f32 v[190:191], v[242:243], v[190:191]
	v_med3_f32 v193, v193, s85, v226
	v_pk_mul_f32 v[96:97], v[96:97], v[190:191]
	v_and_b32_e32 v191, 0xffff0000, v194
	v_lshlrev_b32_e32 v194, 16, v234
	v_add_f32_e32 v189, 1.0, v189
	v_exp_f32_e32 v193, v193
	v_rcp_f32_e32 v192, v189
	v_fma_f32 v189, v194, s89, v138
	v_fma_f32 v191, v191, s89, v143
	v_med3_f32 v189, v189, s85, v226
	v_med3_f32 v191, v191, s85, v226
	v_lshlrev_b32_e32 v227, 16, v195
	v_and_b32_e32 v229, 0xffff0000, v195
	v_and_b32_e32 v195, 0xffff0000, v196
	v_lshlrev_b32_e32 v231, 16, v197
	v_and_b32_e32 v236, 0xffff0000, v197
	v_and_b32_e32 v197, 0xffff0000, v232
	v_exp_f32_e32 v194, v189
	v_add_f32_e32 v189, 1.0, v193
	v_exp_f32_e32 v193, v191
	v_rcp_f32_e32 v196, v189
	v_fma_f32 v189, v197, s89, v147
	v_fma_f32 v195, v195, s89, v135
	v_med3_f32 v189, v189, s85, v226
	v_med3_f32 v195, v195, s85, v226
	v_and_b32_e32 v230, 0xffff0000, v234
	v_exp_f32_e32 v191, v189
	v_add_f32_e32 v189, 1.0, v193
	v_exp_f32_e32 v197, v195
	v_rcp_f32_e32 v193, v189
	v_fma_f32 v189, v230, s89, v139
	v_fma_f32 v227, v227, s89, v144
	v_med3_f32 v189, v189, s85, v226
	v_med3_f32 v227, v227, s85, v226
	v_lshlrev_b32_e32 v228, 16, v233
	v_exp_f32_e32 v195, v189
	v_add_f32_e32 v189, 1.0, v197
	v_exp_f32_e32 v227, v227
	v_rcp_f32_e32 v197, v189
	v_fma_f32 v189, v228, s89, v148
	v_med3_f32 v189, v189, s85, v226
	v_exp_f32_e32 v228, v189
	v_add_f32_e32 v189, 1.0, v227
	v_fma_f32 v227, v231, s89, v136
	v_med3_f32 v227, v227, s85, v226
	v_lshlrev_b32_e32 v190, 16, v232
	v_lshlrev_b32_e32 v232, 16, v235
	v_exp_f32_e32 v227, v227
	v_fma_f32 v229, v229, s89, v145
	v_rcp_f32_e32 v230, v189
	v_fma_f32 v189, v232, s89, v140
	v_med3_f32 v229, v229, s85, v226
	v_and_b32_e32 v233, 0xffff0000, v233
	v_med3_f32 v189, v189, s85, v226
	v_exp_f32_e32 v231, v229
	v_fma_f32 v190, v190, s89, v146
	v_exp_f32_e32 v232, v189
	v_add_f32_e32 v189, 1.0, v227
	v_fma_f32 v227, v233, s89, v149
	v_med3_f32 v190, v190, s85, v226
	v_med3_f32 v227, v227, s85, v226
	v_exp_f32_e32 v190, v190
	v_exp_f32_e32 v229, v227
	v_rcp_f32_e32 v234, v189
	v_add_f32_e32 v189, 1.0, v231
	v_rcp_f32_e32 v231, v189
	v_pk_add_f32 v[228:229], v[228:229], 1.0 op_sel_hi:[1,0]
	v_pk_add_f32 v[190:191], v[190:191], 1.0 op_sel_hi:[1,0]
	v_and_b32_e32 v235, 0xffff0000, v235
	v_pk_mul_f32 v[190:191], v[192:193], v[190:191]
	v_pk_mul_f32 v[192:193], v[230:231], v[228:229]
	v_fma_f32 v189, v235, s89, v141
	v_pk_mul_f32 v[92:93], v[92:93], v[192:193]
	v_fma_f32 v192, v236, s89, v137
	v_med3_f32 v192, v192, s85, v226
	v_exp_f32_e32 v192, v192
	v_med3_f32 v189, v189, s85, v226
	v_exp_f32_e32 v233, v189
	v_add_f32_e32 v189, 1.0, v192
	v_rcp_f32_e32 v235, v189
	s_waitcnt vmcnt(3)
; #define UNPK0(q_) ((f32x4){bf_lo((q_).x), bf_hi((q_).x), bf_lo((q_).y), bf_hi((q_).y)})
; #define UNPK1(q_) ((f32x4){bf_lo((q_).z), bf_hi((q_).z), bf_lo((q_).w), bf_hi((q_).w)})
;     static __device__ __forceinline__ float eneg(float g) { return __builtin_amdgcn_exp2f(-1.4426950408889634f * fminf(fmaxf(g, -30.f), 30.f)); }
;     __device__ __forceinline__ void mid(f32x4 (&acc)[2][2][4][2], const Unit& u, int wr, int wc, int fr, int fq) const {
;     ...
;         for (int am = 0; am < 4; ++am) { const int ai = am >> 1;
;             u32x4 ra[4][2], rb[4][2];
; #pragma unroll
;             for (int m = 2 * (am & 1); m < 2 * (am & 1) + 2; ++m) { pa.fetch(ai, m, ra[m][0], ra[m][1]); pb.fetch(ai, m, rb[m][0], rb[m][1]); }
;             asm volatile("" ::: "memory");
; #pragma unroll
;             for (int m = 2 * (am & 1); m < 2 * (am & 1) + 2; ++m) {
;                 pa.stage(ra[m][0], ra[m][1]); const u32x4 ga0 = pa.get(0), ga1 = pa.get(1);
;                 asm volatile("" ::: "memory");
;                 pb.stage(rb[m][0], rb[m][1]); const u32x4 gb0 = pb.get(0), gb1 = pb.get(1);
;                 asm volatile("" ::: "memory");
; #pragma unroll
;                 for (int bj = 0; bj < 2; ++bj) { const u32x4 ga = bj ? ga1 : ga0, gb = bj ? gb1 : gb0;
;                     const f32x4 a0 = UNPK0(ga) + ba[bj][0], a1 = UNPK1(ga) + ba[bj][1], b0 = UNPK0(gb) + bb[bj][0], b1 = UNPK1(gb) + bb[bj][1];
; #pragma unroll
;                     for (int k = 0; k < 4; ++k) { acc[ai][bj][m][0][k] *= (1.0f + eneg(b0[k])) * __builtin_amdgcn_rcpf(1.0f + eneg(a0[k]));
;                                                   acc[ai][bj][m][1][k] *= (1.0f + eneg(b1[k])) * __builtin_amdgcn_rcpf(1.0f + eneg(a1[k])); } } }
	s_waitcnt vmcnt(2)
	s_waitcnt vmcnt(1)
	s_waitcnt vmcnt(0)
	v_pk_mul_f32 v[90:91], v[90:91], v[190:191]
	v_pk_add_f32 v[190:191], v[232:233], 1.0 op_sel_hi:[1,0]
	v_lshlrev_b32_e32 v189, 16, v174
	v_pk_mul_f32 v[190:191], v[234:235], v[190:191]
	v_lshlrev_b32_e32 v227, 16, v169
	v_pk_mul_f32 v[88:89], v[88:89], v[190:191]
	v_and_b32_e32 v190, 0xffff0000, v174
	v_lshlrev_b32_e32 v174, 16, v176
	v_and_b32_e32 v228, 0xffff0000, v169
	v_fma_f32 v169, v174, s89, v150
	v_pk_add_f32 v[192:193], v[194:195], 1.0 op_sel_hi:[1,0]
	v_pk_mul_f32 v[192:193], v[196:197], v[192:193]
	v_med3_f32 v169, v169, s85, v226
	v_pk_mul_f32 v[86:87], v[86:87], v[192:193]
	v_lshlrev_b32_e32 v191, 16, v175
	v_and_b32_e32 v193, 0xffff0000, v175
	v_and_b32_e32 v175, 0xffff0000, v176
	v_lshlrev_b32_e32 v192, 16, v167
	v_and_b32_e32 v196, 0xffff0000, v167
	v_lshlrev_b32_e32 v167, 16, v168
	v_exp_f32_e32 v169, v169
	v_fma_f32 v167, v167, s89, v154
	v_fma_f32 v175, v175, s89, v151
	v_med3_f32 v167, v167, s85, v226
	v_med3_f32 v175, v175, s85, v226
	v_and_b32_e32 v197, 0xffff0000, v168
	v_fma_f32 v168, v189, s89, v158
	v_exp_f32_e32 v174, v167
	v_add_f32_e32 v167, 1.0, v169
	v_fma_f32 v169, v190, s89, v159
	v_exp_f32_e32 v189, v175
	v_fma_f32 v190, v191, s89, v160
	v_lshlrev_b32_e32 v194, 16, v177
	v_and_b32_e32 v195, 0xffff0000, v177
	v_lshlrev_b32_e32 v176, 16, v166
	v_and_b32_e32 v177, 0xffff0000, v166
	v_med3_f32 v190, v190, s85, v226
	v_fma_f32 v166, v176, s89, v162
	v_rcp_f32_e32 v176, v167
	v_fma_f32 v167, v177, s89, v163
	v_fma_f32 v177, v197, s89, v155
	v_exp_f32_e32 v191, v190
	v_med3_f32 v175, v177, s85, v226
	v_add_f32_e32 v177, 1.0, v189
	v_fma_f32 v189, v192, s89, v164
	v_med3_f32 v189, v189, s85, v226
	v_exp_f32_e32 v190, v189
	v_add_f32_e32 v189, 1.0, v191
	v_fma_f32 v191, v194, s89, v152
	v_med3_f32 v191, v191, s85, v226
	v_exp_f32_e32 v191, v191
	v_fma_f32 v193, v193, s89, v161
	v_rcp_f32_e32 v192, v189
	v_fma_f32 v189, v227, s89, v156
	v_med3_f32 v168, v168, s85, v226
	v_med3_f32 v169, v169, s85, v226
	v_med3_f32 v193, v193, s85, v226
	v_exp_f32_e32 v168, v168
	v_exp_f32_e32 v169, v169
	v_med3_f32 v189, v189, s85, v226
	v_exp_f32_e32 v193, v193
	v_exp_f32_e32 v194, v189
	v_add_f32_e32 v189, 1.0, v191
	v_fma_f32 v191, v196, s89, v165
	v_med3_f32 v166, v166, s85, v226
	v_med3_f32 v167, v167, s85, v226
	v_med3_f32 v191, v191, s85, v226
	v_exp_f32_e32 v166, v166
	v_add_f32_e32 v168, 1.0, v168
	v_exp_f32_e32 v167, v167
	v_add_f32_e32 v169, 1.0, v169
	v_exp_f32_e32 v191, v191
	v_rcp_f32_e32 v196, v189
	v_add_f32_e32 v189, 1.0, v193
	v_rcp_f32_e32 v168, v168
	v_rcp_f32_e32 v169, v169
	v_rcp_f32_e32 v193, v189
	v_pk_add_f32 v[190:191], v[190:191], 1.0 op_sel_hi:[1,0]
	v_pk_add_f32 v[166:167], v[166:167], 1.0 op_sel_hi:[1,0]
	v_pk_mul_f32 v[166:167], v[168:169], v[166:167]
	v_pk_mul_f32 v[168:169], v[192:193], v[190:191]
	v_exp_f32_e32 v175, v175
	v_pk_mul_f32 v[84:85], v[84:85], v[168:169]
	v_fma_f32 v169, v195, s89, v153
	v_med3_f32 v169, v169, s85, v226
	v_exp_f32_e32 v169, v169
	v_fma_f32 v168, v228, s89, v157
	v_med3_f32 v168, v168, s85, v226
	v_rcp_f32_e32 v177, v177
	v_exp_f32_e32 v195, v168
	v_pk_mul_f32 v[82:83], v[82:83], v[166:167]
	v_add_f32_e32 v166, 1.0, v169
	v_rcp_f32_e32 v197, v166
	v_pk_add_f32 v[168:169], v[174:175], 1.0 op_sel_hi:[1,0]
	v_pk_add_f32 v[166:167], v[194:195], 1.0 op_sel_hi:[1,0]
	v_pk_mul_f32 v[168:169], v[176:177], v[168:169]
	v_pk_mul_f32 v[166:167], v[196:197], v[166:167]
	v_pk_mul_f32 v[78:79], v[78:79], v[168:169]
	v_lshlrev_b32_e32 v169, 16, v180
	v_pk_mul_f32 v[80:81], v[80:81], v[166:167]
	v_lshlrev_b32_e32 v166, 16, v178
	v_fma_f32 v169, v169, s89, v134
	v_fma_f32 v166, v166, s89, v142
	v_med3_f32 v169, v169, s85, v226
	v_med3_f32 v166, v166, s85, v226
	v_exp_f32_e32 v169, v169
	v_and_b32_e32 v167, 0xffff0000, v178
	v_and_b32_e32 v176, 0xffff0000, v180
	v_lshlrev_b32_e32 v168, 16, v170
	v_and_b32_e32 v178, 0xffff0000, v170
	v_lshlrev_b32_e32 v180, 16, v171
	v_and_b32_e32 v189, 0xffff0000, v171
	v_lshlrev_b32_e32 v170, 16, v172
	v_and_b32_e32 v171, 0xffff0000, v172
	v_exp_f32_e32 v172, v166
	v_fma_f32 v168, v168, s89, v146
	v_add_f32_e32 v169, 1.0, v169
	v_med3_f32 v166, v168, s85, v226
	v_add_f32_e32 v168, 1.0, v172
	v_rcp_f32_e32 v172, v169
	v_fma_f32 v169, v178, s89, v147
	v_add_co_u32_e32 v178, vcc, s79, v186
	v_lshlrev_b32_e32 v174, 16, v179
	v_and_b32_e32 v175, 0xffff0000, v179
	v_addc_co_u32_e32 v179, vcc, 0, v187, vcc
	v_add_co_u32_e32 v186, vcc, s86, v186
	v_fma_f32 v167, v167, s89, v143
	s_nop 0
	v_addc_co_u32_e32 v187, vcc, 0, v187, vcc
	global_load_dwordx4 v[190:193], v[186:187], off offset:-4096
	global_load_dwordx4 v[194:197], v[178:179], off offset:1024
	v_add_co_u32_e32 v236, vcc, s79, v4
	s_nop 0
	s_nop 0
	v_addc_co_u32_e32 v237, vcc, 0, v5, vcc
	v_add_co_u32_e32 v4, vcc, s86, v4
	v_med3_f32 v167, v167, s85, v226
	s_nop 0
	v_addc_co_u32_e32 v5, vcc, 0, v5, vcc
	global_load_dwordx4 v[228:231], v[4:5], off offset:-4096
	global_load_dwordx4 v[232:235], v[236:237], off offset:1024
	v_lshlrev_b32_e32 v227, 16, v173
	v_and_b32_e32 v239, 0xffff0000, v173
	v_exp_f32_e32 v173, v167
	v_fma_f32 v174, v174, s89, v144
	v_lshlrev_b32_e32 v177, 16, v181
	v_med3_f32 v174, v174, s85, v226
	v_med3_f32 v167, v169, s85, v226
	v_add_f32_e32 v169, 1.0, v173
	v_fma_f32 v173, v176, s89, v135
	v_fma_f32 v176, v180, s89, v148
	v_exp_f32_e32 v180, v174
	v_fma_f32 v177, v177, s89, v136
	v_fma_f32 v175, v175, s89, v145
	v_med3_f32 v177, v177, s85, v226
	v_exp_f32_e32 v177, v177
	v_med3_f32 v175, v175, s85, v226
	v_med3_f32 v174, v176, s85, v226
	v_add_f32_e32 v176, 1.0, v180
	v_fma_f32 v180, v227, s89, v140
	v_exp_f32_e32 v227, v175
; #define UNPK0(q_) ((f32x4){bf_lo((q_).x), bf_hi((q_).x), bf_lo((q_).y), bf_hi((q_).y)})
; #define UNPK1(q_) ((f32x4){bf_lo((q_).z), bf_hi((q_).z), bf_lo((q_).w), bf_hi((q_).w)})
;     static __device__ __forceinline__ float eneg(float g) { return __builtin_amdgcn_exp2f(-1.4426950408889634f * fminf(fmaxf(g, -30.f), 30.f)); }
;     __device__ __forceinline__ void mid(f32x4 (&acc)[2][2][4][2], const Unit& u, int wr, int wc, int fr, int fq) const {
;     ...
;         for (int am = 0; am < 4; ++am) { const int ai = am >> 1;
;             u32x4 ra[4][2], rb[4][2];
; #pragma unroll
;             for (int m = 2 * (am & 1); m < 2 * (am & 1) + 2; ++m) { pa.fetch(ai, m, ra[m][0], ra[m][1]); pb.fetch(ai, m, rb[m][0], rb[m][1]); }
;             asm volatile("" ::: "memory");
; #pragma unroll
;             for (int m = 2 * (am & 1); m < 2 * (am & 1) + 2; ++m) {
;                 pa.stage(ra[m][0], ra[m][1]); const u32x4 ga0 = pa.get(0), ga1 = pa.get(1);
;                 asm volatile("" ::: "memory");
;                 pb.stage(rb[m][0], rb[m][1]); const u32x4 gb0 = pb.get(0), gb1 = pb.get(1);
;                 asm volatile("" ::: "memory");
; #pragma unroll
;                 for (int bj = 0; bj < 2; ++bj) { const u32x4 ga = bj ? ga1 : ga0, gb = bj ? gb1 : gb0;
;                     const f32x4 a0 = UNPK0(ga) + ba[bj][0], a1 = UNPK1(ga) + ba[bj][1], b0 = UNPK0(gb) + bb[bj][0], b1 = UNPK1(gb) + bb[bj][1];
; #pragma unroll
;                     for (int k = 0; k < 4; ++k) { acc[ai][bj][m][0][k] *= (1.0f + eneg(b0[k])) * __builtin_amdgcn_rcpf(1.0f + eneg(a0[k]));
;                                                   acc[ai][bj][m][1][k] *= (1.0f + eneg(b1[k])) * __builtin_amdgcn_rcpf(1.0f + eneg(a1[k])); } } }
	v_fma_f32 v189, v189, s89, v149
	v_add_f32_e32 v177, 1.0, v177
	v_med3_f32 v175, v189, s85, v226
	v_exp_f32_e32 v166, v166
	v_exp_f32_e32 v167, v167
	v_exp_f32_e32 v174, v174
	v_exp_f32_e32 v175, v175
	v_rcp_f32_e32 v238, v177
	v_add_f32_e32 v177, 1.0, v227
	v_rcp_f32_e32 v168, v168
	v_rcp_f32_e32 v169, v169
	v_rcp_f32_e32 v176, v176
	v_rcp_f32_e32 v177, v177
	v_pk_add_f32 v[174:175], v[174:175], 1.0 op_sel_hi:[1,0]
	v_pk_add_f32 v[166:167], v[166:167], 1.0 op_sel_hi:[1,0]
	v_and_b32_e32 v181, 0xffff0000, v181
	v_pk_mul_f32 v[166:167], v[168:169], v[166:167]
	v_pk_mul_f32 v[168:169], v[176:177], v[174:175]
	v_pk_mul_f32 v[76:77], v[76:77], v[168:169]
	v_fma_f32 v169, v181, s89, v137
	v_med3_f32 v173, v173, s85, v226
	v_med3_f32 v169, v169, s85, v226
	v_exp_f32_e32 v173, v173
	v_exp_f32_e32 v169, v169
	v_fma_f32 v170, v170, s89, v138
	v_fma_f32 v171, v171, s89, v139
	v_fma_f32 v168, v239, s89, v141
	v_med3_f32 v170, v170, s85, v226
	v_med3_f32 v171, v171, s85, v226
	v_med3_f32 v180, v180, s85, v226
	v_med3_f32 v168, v168, s85, v226
	v_exp_f32_e32 v170, v170
	v_exp_f32_e32 v171, v171
	v_add_f32_e32 v173, 1.0, v173
	v_exp_f32_e32 v180, v180
	v_exp_f32_e32 v181, v168
	v_pk_mul_f32 v[74:75], v[74:75], v[166:167]
	v_add_f32_e32 v166, 1.0, v169
	v_rcp_f32_e32 v173, v173
	v_rcp_f32_e32 v239, v166
	v_pk_add_f32 v[166:167], v[180:181], 1.0 op_sel_hi:[1,0]
	v_pk_add_f32 v[168:169], v[170:171], 1.0 op_sel_hi:[1,0]
	v_pk_mul_f32 v[166:167], v[238:239], v[166:167]
	v_pk_mul_f32 v[168:169], v[172:173], v[168:169]
	v_pk_mul_f32 v[72:73], v[72:73], v[166:167]
	v_pk_mul_f32 v[70:71], v[70:71], v[168:169]
	global_load_dwordx4 v[174:177], v[178:179], off offset:2048
	s_nop 0
	global_load_dwordx4 v[178:181], v[178:179], off offset:3072
	s_nop 0
	global_load_dwordx4 v[166:169], v[236:237], off offset:2048
	global_load_dwordx4 v[170:173], v[236:237], off offset:3072
	s_waitcnt vmcnt(7)
	s_waitcnt vmcnt(6)
	s_waitcnt vmcnt(5)
	s_waitcnt vmcnt(4)
	v_lshlrev_b32_e32 v189, 16, v190
	v_fma_f32 v189, v189, s89, v158
	v_med3_f32 v189, v189, s85, v226
	v_lshlrev_b32_e32 v236, 16, v191
	v_and_b32_e32 v237, 0xffff0000, v191
	v_lshlrev_b32_e32 v191, 16, v192
	v_exp_f32_e32 v189, v189
	v_fma_f32 v191, v191, s89, v150
	v_med3_f32 v191, v191, s85, v226
	v_and_b32_e32 v227, 0xffff0000, v190
	v_lshlrev_b32_e32 v239, 16, v193
	v_and_b32_e32 v241, 0xffff0000, v193
	v_lshlrev_b32_e32 v190, 16, v228
	v_and_b32_e32 v193, 0xffff0000, v228
	v_lshlrev_b32_e32 v228, 16, v230
	v_add_f32_e32 v189, 1.0, v189
	v_exp_f32_e32 v191, v191
	v_and_b32_e32 v238, 0xffff0000, v192
	v_rcp_f32_e32 v192, v189
	v_fma_f32 v189, v228, s89, v154
	v_med3_f32 v189, v189, s85, v226
	v_exp_f32_e32 v228, v189
	v_add_f32_e32 v189, 1.0, v191
	v_fma_f32 v191, v227, s89, v159
	v_med3_f32 v191, v191, s85, v226
	v_lshlrev_b32_e32 v240, 16, v229
	v_and_b32_e32 v242, 0xffff0000, v229
	v_and_b32_e32 v229, 0xffff0000, v230
	v_rcp_f32_e32 v230, v189
	v_fma_f32 v189, v193, s89, v163
	v_exp_f32_e32 v193, v191
	v_fma_f32 v227, v238, s89, v151
	v_med3_f32 v189, v189, s85, v226
	v_med3_f32 v227, v227, s85, v226
	v_exp_f32_e32 v191, v189
	v_add_f32_e32 v189, 1.0, v193
	v_exp_f32_e32 v227, v227
	v_rcp_f32_e32 v193, v189
	v_fma_f32 v189, v229, s89, v155
	v_med3_f32 v189, v189, s85, v226
	v_exp_f32_e32 v229, v189
	v_add_f32_e32 v189, 1.0, v227
	v_fma_f32 v227, v236, s89, v160
	v_med3_f32 v227, v227, s85, v226
	v_exp_f32_e32 v227, v227
	v_lshlrev_b32_e32 v243, 16, v231
	v_and_b32_e32 v244, 0xffff0000, v231
	v_rcp_f32_e32 v231, v189
	v_fma_f32 v189, v240, s89, v164
	v_med3_f32 v189, v189, s85, v226
	v_exp_f32_e32 v236, v189
	v_add_f32_e32 v189, 1.0, v227
	v_fma_f32 v227, v239, s89, v152
	v_med3_f32 v227, v227, s85, v226
	v_exp_f32_e32 v227, v227
	v_fma_f32 v237, v237, s89, v161
	v_rcp_f32_e32 v238, v189
	v_fma_f32 v189, v243, s89, v156
	v_med3_f32 v237, v237, s85, v226
	v_med3_f32 v189, v189, s85, v226
	v_exp_f32_e32 v239, v237
	v_fma_f32 v190, v190, s89, v162
	v_exp_f32_e32 v240, v189
	v_add_f32_e32 v189, 1.0, v227
	v_fma_f32 v227, v242, s89, v165
	v_med3_f32 v190, v190, s85, v226
	v_med3_f32 v227, v227, s85, v226
	v_exp_f32_e32 v190, v190
	v_exp_f32_e32 v237, v227
	v_rcp_f32_e32 v242, v189
	v_add_f32_e32 v189, 1.0, v239
	v_rcp_f32_e32 v239, v189
	v_pk_add_f32 v[236:237], v[236:237], 1.0 op_sel_hi:[1,0]
	v_pk_add_f32 v[190:191], v[190:191], 1.0 op_sel_hi:[1,0]
	v_fma_f32 v189, v244, s89, v157
	v_pk_mul_f32 v[190:191], v[192:193], v[190:191]
	v_pk_mul_f32 v[192:193], v[238:239], v[236:237]
	v_pk_mul_f32 v[68:69], v[68:69], v[192:193]
	v_fma_f32 v192, v241, s89, v153
	v_med3_f32 v192, v192, s85, v226
	v_exp_f32_e32 v192, v192
	v_med3_f32 v189, v189, s85, v226
	v_exp_f32_e32 v241, v189
	v_pk_mul_f32 v[66:67], v[66:67], v[190:191]
	v_add_f32_e32 v189, 1.0, v192
	v_rcp_f32_e32 v243, v189
	v_lshlrev_b32_e32 v189, 16, v194
	v_fma_f32 v189, v189, s89, v142
	v_pk_add_f32 v[192:193], v[228:229], 1.0 op_sel_hi:[1,0]
	v_pk_mul_f32 v[192:193], v[230:231], v[192:193]
	v_med3_f32 v189, v189, s85, v226
	v_pk_mul_f32 v[62:63], v[62:63], v[192:193]
	v_lshlrev_b32_e32 v193, 16, v196
	v_exp_f32_e32 v189, v189
	v_fma_f32 v193, v193, s89, v134
	v_pk_add_f32 v[190:191], v[240:241], 1.0 op_sel_hi:[1,0]
	v_pk_mul_f32 v[190:191], v[242:243], v[190:191]
	v_med3_f32 v193, v193, s85, v226
	v_pk_mul_f32 v[64:65], v[64:65], v[190:191]
	v_and_b32_e32 v191, 0xffff0000, v194
	v_lshlrev_b32_e32 v194, 16, v234
	v_add_f32_e32 v189, 1.0, v189
	v_exp_f32_e32 v193, v193
	v_rcp_f32_e32 v192, v189
	v_fma_f32 v189, v194, s89, v138
	v_fma_f32 v191, v191, s89, v143
	v_med3_f32 v189, v189, s85, v226
	v_med3_f32 v191, v191, s85, v226
	v_lshlrev_b32_e32 v227, 16, v195
; #define UNPK0(q_) ((f32x4){bf_lo((q_).x), bf_hi((q_).x), bf_lo((q_).y), bf_hi((q_).y)})
; #define UNPK1(q_) ((f32x4){bf_lo((q_).z), bf_hi((q_).z), bf_lo((q_).w), bf_hi((q_).w)})
;     static __device__ __forceinline__ float eneg(float g) { return __builtin_amdgcn_exp2f(-1.4426950408889634f * fminf(fmaxf(g, -30.f), 30.f)); }
;     __device__ __forceinline__ void mid(f32x4 (&acc)[2][2][4][2], const Unit& u, int wr, int wc, int fr, int fq) const {
;     ...
;         for (int am = 0; am < 4; ++am) { const int ai = am >> 1;
;             u32x4 ra[4][2], rb[4][2];
; #pragma unroll
;             for (int m = 2 * (am & 1); m < 2 * (am & 1) + 2; ++m) { pa.fetch(ai, m, ra[m][0], ra[m][1]); pb.fetch(ai, m, rb[m][0], rb[m][1]); }
;             asm volatile("" ::: "memory");
; #pragma unroll
;             for (int m = 2 * (am & 1); m < 2 * (am & 1) + 2; ++m) {
;                 pa.stage(ra[m][0], ra[m][1]); const u32x4 ga0 = pa.get(0), ga1 = pa.get(1);
;                 asm volatile("" ::: "memory");
;                 pb.stage(rb[m][0], rb[m][1]); const u32x4 gb0 = pb.get(0), gb1 = pb.get(1);
;                 asm volatile("" ::: "memory");
; #pragma unroll
;                 for (int bj = 0; bj < 2; ++bj) { const u32x4 ga = bj ? ga1 : ga0, gb = bj ? gb1 : gb0;
;                     const f32x4 a0 = UNPK0(ga) + ba[bj][0], a1 = UNPK1(ga) + ba[bj][1], b0 = UNPK0(gb) + bb[bj][0], b1 = UNPK1(gb) + bb[bj][1];
; #pragma unroll
;                     for (int k = 0; k < 4; ++k) { acc[ai][bj][m][0][k] *= (1.0f + eneg(b0[k])) * __builtin_amdgcn_rcpf(1.0f + eneg(a0[k]));
;                                                   acc[ai][bj][m][1][k] *= (1.0f + eneg(b1[k])) * __builtin_amdgcn_rcpf(1.0f + eneg(a1[k])); } } }
	v_and_b32_e32 v229, 0xffff0000, v195
	v_and_b32_e32 v195, 0xffff0000, v196
	v_lshlrev_b32_e32 v231, 16, v197
	v_and_b32_e32 v236, 0xffff0000, v197
	v_and_b32_e32 v197, 0xffff0000, v232
	v_exp_f32_e32 v194, v189
	v_add_f32_e32 v189, 1.0, v193
	v_exp_f32_e32 v193, v191
	v_rcp_f32_e32 v196, v189
	v_fma_f32 v189, v197, s89, v147
	v_fma_f32 v195, v195, s89, v135
	v_med3_f32 v189, v189, s85, v226
	v_med3_f32 v195, v195, s85, v226
	v_and_b32_e32 v230, 0xffff0000, v234
	v_exp_f32_e32 v191, v189
	v_add_f32_e32 v189, 1.0, v193
	v_exp_f32_e32 v197, v195
	v_rcp_f32_e32 v193, v189
	v_fma_f32 v189, v230, s89, v139
	v_fma_f32 v227, v227, s89, v144
	v_med3_f32 v189, v189, s85, v226
	v_med3_f32 v227, v227, s85, v226
	v_lshlrev_b32_e32 v228, 16, v233
	v_exp_f32_e32 v195, v189
	v_add_f32_e32 v189, 1.0, v197
	v_exp_f32_e32 v227, v227
	v_rcp_f32_e32 v197, v189
	v_fma_f32 v189, v228, s89, v148
	v_med3_f32 v189, v189, s85, v226
	v_exp_f32_e32 v228, v189
	v_add_f32_e32 v189, 1.0, v227
	v_fma_f32 v227, v231, s89, v136
	v_med3_f32 v227, v227, s85, v226
	v_lshlrev_b32_e32 v190, 16, v232
	v_lshlrev_b32_e32 v232, 16, v235
	v_exp_f32_e32 v227, v227
	v_fma_f32 v229, v229, s89, v145
	v_rcp_f32_e32 v230, v189
	v_fma_f32 v189, v232, s89, v140
	v_med3_f32 v229, v229, s85, v226
	v_and_b32_e32 v233, 0xffff0000, v233
	v_med3_f32 v189, v189, s85, v226
	v_exp_f32_e32 v231, v229
	v_fma_f32 v190, v190, s89, v146
	v_exp_f32_e32 v232, v189
	v_add_f32_e32 v189, 1.0, v227
	v_fma_f32 v227, v233, s89, v149
	v_med3_f32 v190, v190, s85, v226
	v_med3_f32 v227, v227, s85, v226
	v_exp_f32_e32 v190, v190
	v_exp_f32_e32 v229, v227
	v_rcp_f32_e32 v234, v189
	v_add_f32_e32 v189, 1.0, v231
	v_rcp_f32_e32 v231, v189
	v_pk_add_f32 v[228:229], v[228:229], 1.0 op_sel_hi:[1,0]
	v_pk_add_f32 v[190:191], v[190:191], 1.0 op_sel_hi:[1,0]
	v_and_b32_e32 v235, 0xffff0000, v235
	v_pk_mul_f32 v[190:191], v[192:193], v[190:191]
	v_pk_mul_f32 v[192:193], v[230:231], v[228:229]
	v_fma_f32 v189, v235, s89, v141
	v_pk_mul_f32 v[60:61], v[60:61], v[192:193]
	v_fma_f32 v192, v236, s89, v137
	v_med3_f32 v192, v192, s85, v226
	v_exp_f32_e32 v192, v192
	v_med3_f32 v189, v189, s85, v226
	v_exp_f32_e32 v233, v189
	v_add_f32_e32 v189, 1.0, v192
	v_rcp_f32_e32 v235, v189
	s_waitcnt vmcnt(3)
	s_waitcnt vmcnt(2)
	s_waitcnt vmcnt(1)
	s_waitcnt vmcnt(0)
	v_pk_mul_f32 v[58:59], v[58:59], v[190:191]
	v_pk_add_f32 v[190:191], v[232:233], 1.0 op_sel_hi:[1,0]
	v_lshlrev_b32_e32 v189, 16, v174
	v_pk_mul_f32 v[190:191], v[234:235], v[190:191]
	v_lshlrev_b32_e32 v227, 16, v169
	v_pk_mul_f32 v[56:57], v[56:57], v[190:191]
	v_and_b32_e32 v190, 0xffff0000, v174
	v_lshlrev_b32_e32 v174, 16, v176
	v_and_b32_e32 v228, 0xffff0000, v169
	v_fma_f32 v169, v174, s89, v150
	v_pk_add_f32 v[192:193], v[194:195], 1.0 op_sel_hi:[1,0]
	v_pk_mul_f32 v[192:193], v[196:197], v[192:193]
	v_med3_f32 v169, v169, s85, v226
	v_pk_mul_f32 v[54:55], v[54:55], v[192:193]
	v_lshlrev_b32_e32 v191, 16, v175
	v_and_b32_e32 v193, 0xffff0000, v175
	v_and_b32_e32 v175, 0xffff0000, v176
	v_lshlrev_b32_e32 v192, 16, v167
	v_and_b32_e32 v196, 0xffff0000, v167
	v_lshlrev_b32_e32 v167, 16, v168
	v_exp_f32_e32 v169, v169
	v_fma_f32 v167, v167, s89, v154
	v_fma_f32 v175, v175, s89, v151
	v_med3_f32 v167, v167, s85, v226
	v_med3_f32 v175, v175, s85, v226
	v_and_b32_e32 v197, 0xffff0000, v168
	v_fma_f32 v168, v189, s89, v158
	v_exp_f32_e32 v174, v167
	v_add_f32_e32 v167, 1.0, v169
	v_fma_f32 v169, v190, s89, v159
	v_exp_f32_e32 v189, v175
	v_fma_f32 v190, v191, s89, v160
	v_lshlrev_b32_e32 v194, 16, v177
	v_and_b32_e32 v195, 0xffff0000, v177
	v_lshlrev_b32_e32 v176, 16, v166
	v_and_b32_e32 v177, 0xffff0000, v166
	v_med3_f32 v190, v190, s85, v226
	v_fma_f32 v166, v176, s89, v162
	v_rcp_f32_e32 v176, v167
	v_fma_f32 v167, v177, s89, v163
	v_fma_f32 v177, v197, s89, v155
	v_exp_f32_e32 v191, v190
	v_med3_f32 v175, v177, s85, v226
	v_add_f32_e32 v177, 1.0, v189
	v_fma_f32 v189, v192, s89, v164
	v_med3_f32 v189, v189, s85, v226
	v_exp_f32_e32 v190, v189
	v_add_f32_e32 v189, 1.0, v191
	v_fma_f32 v191, v194, s89, v152
	v_med3_f32 v191, v191, s85, v226
	v_exp_f32_e32 v191, v191
	v_fma_f32 v193, v193, s89, v161
	v_rcp_f32_e32 v192, v189
	v_fma_f32 v189, v227, s89, v156
	v_med3_f32 v168, v168, s85, v226
	v_med3_f32 v169, v169, s85, v226
	v_med3_f32 v193, v193, s85, v226
	v_exp_f32_e32 v168, v168
	v_exp_f32_e32 v169, v169
	v_med3_f32 v189, v189, s85, v226
	v_exp_f32_e32 v193, v193
	v_exp_f32_e32 v194, v189
	v_add_f32_e32 v189, 1.0, v191
	v_fma_f32 v191, v196, s89, v165
	v_med3_f32 v166, v166, s85, v226
	v_med3_f32 v167, v167, s85, v226
	v_med3_f32 v191, v191, s85, v226
	v_exp_f32_e32 v166, v166
	v_add_f32_e32 v168, 1.0, v168
	v_exp_f32_e32 v167, v167
	v_add_f32_e32 v169, 1.0, v169
	v_exp_f32_e32 v191, v191
	v_rcp_f32_e32 v196, v189
	v_add_f32_e32 v189, 1.0, v193
	v_rcp_f32_e32 v168, v168
	v_rcp_f32_e32 v169, v169
	v_rcp_f32_e32 v193, v189
	v_pk_add_f32 v[190:191], v[190:191], 1.0 op_sel_hi:[1,0]
	v_pk_add_f32 v[166:167], v[166:167], 1.0 op_sel_hi:[1,0]
	v_pk_mul_f32 v[166:167], v[168:169], v[166:167]
	v_pk_mul_f32 v[168:169], v[192:193], v[190:191]
	v_pk_mul_f32 v[50:51], v[50:51], v[166:167]
	v_pk_mul_f32 v[52:53], v[52:53], v[168:169]
	v_fma_f32 v169, v195, s89, v153
	v_med3_f32 v169, v169, s85, v226
	v_exp_f32_e32 v169, v169
	v_fma_f32 v168, v228, s89, v157
	v_med3_f32 v168, v168, s85, v226
	v_exp_f32_e32 v195, v168
	v_add_f32_e32 v166, 1.0, v169
	v_rcp_f32_e32 v197, v166
	v_exp_f32_e32 v175, v175
	v_pk_add_f32 v[166:167], v[194:195], 1.0 op_sel_hi:[1,0]
	v_rcp_f32_e32 v177, v177
	v_pk_mul_f32 v[166:167], v[196:197], v[166:167]
	global_load_dwordx4 v[190:193], v[186:187], off
; #define UNPK0(q_) ((f32x4){bf_lo((q_).x), bf_hi((q_).x), bf_lo((q_).y), bf_hi((q_).y)})
; #define UNPK1(q_) ((f32x4){bf_lo((q_).z), bf_hi((q_).z), bf_lo((q_).w), bf_hi((q_).w)})
;     static __device__ __forceinline__ float eneg(float g) { return __builtin_amdgcn_exp2f(-1.4426950408889634f * fminf(fmaxf(g, -30.f), 30.f)); }
;     __device__ __forceinline__ void mid(f32x4 (&acc)[2][2][4][2], const Unit& u, int wr, int wc, int fr, int fq) const {
;     ...
;         for (int am = 0; am < 4; ++am) { const int ai = am >> 1;
;             u32x4 ra[4][2], rb[4][2];
; #pragma unroll
;             for (int m = 2 * (am & 1); m < 2 * (am & 1) + 2; ++m) { pa.fetch(ai, m, ra[m][0], ra[m][1]); pb.fetch(ai, m, rb[m][0], rb[m][1]); }
;             asm volatile("" ::: "memory");
; #pragma unroll
;             for (int m = 2 * (am & 1); m < 2 * (am & 1) + 2; ++m) {
;                 pa.stage(ra[m][0], ra[m][1]); const u32x4 ga0 = pa.get(0), ga1 = pa.get(1);
;                 asm volatile("" ::: "memory");
;                 pb.stage(rb[m][0], rb[m][1]); const u32x4 gb0 = pb.get(0), gb1 = pb.get(1);
;                 asm volatile("" ::: "memory");
; #pragma unroll
;                 for (int bj = 0; bj < 2; ++bj) { const u32x4 ga = bj ? ga1 : ga0, gb = bj ? gb1 : gb0;
;                     const f32x4 a0 = UNPK0(ga) + ba[bj][0], a1 = UNPK1(ga) + ba[bj][1], b0 = UNPK0(gb) + bb[bj][0], b1 = UNPK1(gb) + bb[bj][1];
; #pragma unroll
;                     for (int k = 0; k < 4; ++k) { acc[ai][bj][m][0][k] *= (1.0f + eneg(b0[k])) * __builtin_amdgcn_rcpf(1.0f + eneg(a0[k]));
;                                                   acc[ai][bj][m][1][k] *= (1.0f + eneg(b1[k])) * __builtin_amdgcn_rcpf(1.0f + eneg(a1[k])); } } }
	global_load_dwordx4 v[194:197], v[186:187], off offset:1024
	global_load_dwordx4 v[228:231], v[4:5], off
	global_load_dwordx4 v[232:235], v[4:5], off offset:1024
	v_pk_add_f32 v[168:169], v[174:175], 1.0 op_sel_hi:[1,0]
	v_pk_mul_f32 v[48:49], v[48:49], v[166:167]
	v_pk_mul_f32 v[168:169], v[176:177], v[168:169]
	v_lshlrev_b32_e32 v166, 16, v178
	v_pk_mul_f32 v[46:47], v[46:47], v[168:169]
	v_lshlrev_b32_e32 v169, 16, v180
	v_fma_f32 v169, v169, s89, v134
	v_and_b32_e32 v167, 0xffff0000, v178
	v_fma_f32 v166, v166, s89, v142
	v_med3_f32 v169, v169, s85, v226
	v_fma_f32 v167, v167, s89, v143
	v_med3_f32 v166, v166, s85, v226
	v_exp_f32_e32 v169, v169
	v_lshlrev_b32_e32 v174, 16, v179
	v_and_b32_e32 v175, 0xffff0000, v179
	v_and_b32_e32 v176, 0xffff0000, v180
	v_lshlrev_b32_e32 v177, 16, v181
	v_and_b32_e32 v179, 0xffff0000, v181
	v_lshlrev_b32_e32 v168, 16, v170
	v_and_b32_e32 v178, 0xffff0000, v170
	v_lshlrev_b32_e32 v180, 16, v171
	v_and_b32_e32 v181, 0xffff0000, v171
	v_lshlrev_b32_e32 v170, 16, v172
	v_and_b32_e32 v171, 0xffff0000, v172
	v_exp_f32_e32 v172, v166
	v_med3_f32 v167, v167, s85, v226
	v_lshlrev_b32_e32 v189, 16, v173
	v_and_b32_e32 v227, 0xffff0000, v173
	v_exp_f32_e32 v173, v167
	v_fma_f32 v177, v177, s89, v136
	v_fma_f32 v174, v174, s89, v144
	v_fma_f32 v175, v175, s89, v145
	v_fma_f32 v168, v168, s89, v146
	v_add_f32_e32 v169, 1.0, v169
	v_med3_f32 v177, v177, s85, v226
	v_med3_f32 v166, v168, s85, v226
	v_add_f32_e32 v168, 1.0, v172
	v_rcp_f32_e32 v172, v169
	v_fma_f32 v169, v178, s89, v147
	v_med3_f32 v174, v174, s85, v226
	v_exp_f32_e32 v177, v177
	v_med3_f32 v175, v175, s85, v226
	v_med3_f32 v167, v169, s85, v226
	v_add_f32_e32 v169, 1.0, v173
	v_fma_f32 v173, v176, s89, v135
	v_fma_f32 v176, v180, s89, v148
	v_exp_f32_e32 v178, v174
	v_fma_f32 v180, v181, s89, v149
	v_exp_f32_e32 v181, v175
	v_med3_f32 v174, v176, s85, v226
	v_add_f32_e32 v177, 1.0, v177
	v_med3_f32 v175, v180, s85, v226
	v_exp_f32_e32 v166, v166
	v_exp_f32_e32 v167, v167
	v_exp_f32_e32 v174, v174
	v_add_f32_e32 v176, 1.0, v178
	v_exp_f32_e32 v175, v175
	v_rcp_f32_e32 v180, v177
	v_add_f32_e32 v177, 1.0, v181
	v_rcp_f32_e32 v168, v168
	v_rcp_f32_e32 v169, v169
	v_rcp_f32_e32 v176, v176
	v_rcp_f32_e32 v177, v177
	v_pk_add_f32 v[174:175], v[174:175], 1.0 op_sel_hi:[1,0]
	v_pk_add_f32 v[166:167], v[166:167], 1.0 op_sel_hi:[1,0]
	v_pk_mul_f32 v[166:167], v[168:169], v[166:167]
	v_pk_mul_f32 v[168:169], v[176:177], v[174:175]
	v_med3_f32 v173, v173, s85, v226
	v_pk_mul_f32 v[44:45], v[44:45], v[168:169]
	v_fma_f32 v169, v179, s89, v137
	v_med3_f32 v169, v169, s85, v226
	v_exp_f32_e32 v173, v173
	v_exp_f32_e32 v169, v169
	v_fma_f32 v170, v170, s89, v138
	v_fma_f32 v171, v171, s89, v139
	v_fma_f32 v178, v189, s89, v140
	v_fma_f32 v168, v227, s89, v141
	v_med3_f32 v170, v170, s85, v226
	v_med3_f32 v171, v171, s85, v226
	v_med3_f32 v178, v178, s85, v226
	v_med3_f32 v168, v168, s85, v226
	v_exp_f32_e32 v170, v170
	v_exp_f32_e32 v171, v171
	v_add_f32_e32 v173, 1.0, v173
	v_exp_f32_e32 v178, v178
	v_exp_f32_e32 v179, v168
	v_pk_mul_f32 v[42:43], v[42:43], v[166:167]
	v_add_f32_e32 v166, 1.0, v169
	v_rcp_f32_e32 v173, v173
	v_rcp_f32_e32 v181, v166
	v_pk_add_f32 v[166:167], v[178:179], 1.0 op_sel_hi:[1,0]
	v_pk_add_f32 v[168:169], v[170:171], 1.0 op_sel_hi:[1,0]
	v_pk_mul_f32 v[166:167], v[180:181], v[166:167]
	v_pk_mul_f32 v[168:169], v[172:173], v[168:169]
	v_pk_mul_f32 v[40:41], v[40:41], v[166:167]
	v_pk_mul_f32 v[38:39], v[38:39], v[168:169]
	global_load_dwordx4 v[174:177], v[186:187], off offset:2048
	global_load_dwordx4 v[178:181], v[186:187], off offset:3072
	global_load_dwordx4 v[166:169], v[4:5], off offset:2048
	global_load_dwordx4 v[170:173], v[4:5], off offset:3072
	s_waitcnt vmcnt(7)
	s_waitcnt vmcnt(6)
	s_waitcnt vmcnt(5)
	s_waitcnt vmcnt(4)
	v_lshlrev_b32_e32 v187, 16, v192
	v_lshlrev_b32_e32 v4, 16, v190
	v_fma_f32 v187, v187, s89, v150
	v_fma_f32 v4, v4, s89, v158
	v_med3_f32 v187, v187, s85, v226
	v_med3_f32 v4, v4, s85, v226
	v_exp_f32_e32 v187, v187
	v_and_b32_e32 v5, 0xffff0000, v190
	v_lshlrev_b32_e32 v189, 16, v191
	v_and_b32_e32 v227, 0xffff0000, v191
	v_and_b32_e32 v191, 0xffff0000, v192
	v_exp_f32_e32 v192, v4
	v_fma_f32 v5, v5, s89, v159
	v_lshlrev_b32_e32 v186, 16, v228
	v_lshlrev_b32_e32 v236, 16, v193
	v_and_b32_e32 v237, 0xffff0000, v193
	v_and_b32_e32 v193, 0xffff0000, v228
	v_fma_f32 v186, v186, s89, v162
	v_add_f32_e32 v187, 1.0, v187
	v_med3_f32 v5, v5, s85, v226
	v_med3_f32 v4, v186, s85, v226
	v_add_f32_e32 v186, 1.0, v192
	v_rcp_f32_e32 v192, v187
	v_fma_f32 v187, v193, s89, v163
	v_exp_f32_e32 v193, v5
	v_fma_f32 v189, v189, s89, v160
	v_fma_f32 v191, v191, s89, v151
	v_med3_f32 v189, v189, s85, v226
	v_lshlrev_b32_e32 v190, 16, v230
	v_and_b32_e32 v230, 0xffff0000, v230
	v_med3_f32 v191, v191, s85, v226
	v_exp_f32_e32 v189, v189
	v_lshlrev_b32_e32 v238, 16, v231
	v_and_b32_e32 v239, 0xffff0000, v231
	v_med3_f32 v5, v187, s85, v226
	v_add_f32_e32 v187, 1.0, v193
	v_fma_f32 v193, v230, s89, v155
	v_exp_f32_e32 v230, v191
	v_fma_f32 v231, v236, s89, v152
	v_fma_f32 v227, v227, s89, v161
	v_med3_f32 v231, v231, s85, v226
	v_add_f32_e32 v189, 1.0, v189
	v_exp_f32_e32 v231, v231
	v_med3_f32 v227, v227, s85, v226
	v_lshlrev_b32_e32 v228, 16, v229
	v_and_b32_e32 v229, 0xffff0000, v229
	v_med3_f32 v191, v193, s85, v226
	v_add_f32_e32 v193, 1.0, v230
	v_rcp_f32_e32 v230, v189
	v_fma_f32 v189, v238, s89, v156
	v_exp_f32_e32 v227, v227
	v_fma_f32 v228, v228, s89, v164
	v_fma_f32 v229, v229, s89, v165
	v_med3_f32 v189, v189, s85, v226
	v_med3_f32 v228, v228, s85, v226
	v_exp_f32_e32 v236, v189
	v_add_f32_e32 v189, 1.0, v231
; #define UNPK0(q_) ((f32x4){bf_lo((q_).x), bf_hi((q_).x), bf_lo((q_).y), bf_hi((q_).y)})
; #define UNPK1(q_) ((f32x4){bf_lo((q_).z), bf_hi((q_).z), bf_lo((q_).w), bf_hi((q_).w)})
;     static __device__ __forceinline__ float eneg(float g) { return __builtin_amdgcn_exp2f(-1.4426950408889634f * fminf(fmaxf(g, -30.f), 30.f)); }
;     __device__ __forceinline__ void mid(f32x4 (&acc)[2][2][4][2], const Unit& u, int wr, int wc, int fr, int fq) const {
;     ...
;         for (int am = 0; am < 4; ++am) { const int ai = am >> 1;
;             u32x4 ra[4][2], rb[4][2];
; #pragma unroll
;             for (int m = 2 * (am & 1); m < 2 * (am & 1) + 2; ++m) { pa.fetch(ai, m, ra[m][0], ra[m][1]); pb.fetch(ai, m, rb[m][0], rb[m][1]); }
;             asm volatile("" ::: "memory");
; #pragma unroll
;             for (int m = 2 * (am & 1); m < 2 * (am & 1) + 2; ++m) {
;                 pa.stage(ra[m][0], ra[m][1]); const u32x4 ga0 = pa.get(0), ga1 = pa.get(1);
;                 asm volatile("" ::: "memory");
;                 pb.stage(rb[m][0], rb[m][1]); const u32x4 gb0 = pb.get(0), gb1 = pb.get(1);
;                 asm volatile("" ::: "memory");
; #pragma unroll
;                 for (int bj = 0; bj < 2; ++bj) { const u32x4 ga = bj ? ga1 : ga0, gb = bj ? gb1 : gb0;
;                     const f32x4 a0 = UNPK0(ga) + ba[bj][0], a1 = UNPK1(ga) + ba[bj][1], b0 = UNPK0(gb) + bb[bj][0], b1 = UNPK1(gb) + bb[bj][1];
; #pragma unroll
;                     for (int k = 0; k < 4; ++k) { acc[ai][bj][m][0][k] *= (1.0f + eneg(b0[k])) * __builtin_amdgcn_rcpf(1.0f + eneg(a0[k]));
;                                                   acc[ai][bj][m][1][k] *= (1.0f + eneg(b1[k])) * __builtin_amdgcn_rcpf(1.0f + eneg(a1[k])); } } }
	v_med3_f32 v229, v229, s85, v226
	v_exp_f32_e32 v4, v4
	v_exp_f32_e32 v5, v5
	v_exp_f32_e32 v228, v228
	v_exp_f32_e32 v229, v229
	v_rcp_f32_e32 v238, v189
	v_add_f32_e32 v189, 1.0, v227
	v_rcp_f32_e32 v186, v186
	v_rcp_f32_e32 v187, v187
	v_rcp_f32_e32 v231, v189
	v_pk_add_f32 v[228:229], v[228:229], 1.0 op_sel_hi:[1,0]
	v_pk_add_f32 v[4:5], v[4:5], 1.0 op_sel_hi:[1,0]
	v_fma_f32 v190, v190, s89, v154
	v_pk_mul_f32 v[4:5], v[186:187], v[4:5]
	v_pk_mul_f32 v[186:187], v[230:231], v[228:229]
	v_pk_mul_f32 v[36:37], v[36:37], v[186:187]
	v_fma_f32 v187, v237, s89, v153
	v_med3_f32 v187, v187, s85, v226
	v_exp_f32_e32 v187, v187
	v_fma_f32 v186, v239, s89, v157
	v_med3_f32 v190, v190, s85, v226
	v_exp_f32_e32 v190, v190
	v_exp_f32_e32 v191, v191
	v_med3_f32 v186, v186, s85, v226
	v_rcp_f32_e32 v193, v193
	v_exp_f32_e32 v237, v186
	v_pk_mul_f32 v[34:35], v[34:35], v[4:5]
	v_add_f32_e32 v4, 1.0, v187
	v_rcp_f32_e32 v239, v4
	v_pk_add_f32 v[186:187], v[190:191], 1.0 op_sel_hi:[1,0]
	v_pk_add_f32 v[4:5], v[236:237], 1.0 op_sel_hi:[1,0]
	v_pk_mul_f32 v[186:187], v[192:193], v[186:187]
	v_pk_mul_f32 v[4:5], v[238:239], v[4:5]
	v_pk_mul_f32 v[30:31], v[30:31], v[186:187]
	v_lshlrev_b32_e32 v187, 16, v196
	v_pk_mul_f32 v[32:33], v[32:33], v[4:5]
	v_lshlrev_b32_e32 v4, 16, v194
	v_fma_f32 v187, v187, s89, v134
	v_fma_f32 v4, v4, s89, v142
	v_med3_f32 v187, v187, s85, v226
	v_med3_f32 v4, v4, s85, v226
	v_exp_f32_e32 v187, v187
	v_and_b32_e32 v5, 0xffff0000, v194
	v_exp_f32_e32 v192, v4
	v_fma_f32 v5, v5, s89, v143
	v_lshlrev_b32_e32 v186, 16, v232
	v_lshlrev_b32_e32 v189, 16, v195
	v_and_b32_e32 v193, 0xffff0000, v232
	v_fma_f32 v186, v186, s89, v146
	v_add_f32_e32 v187, 1.0, v187
	v_med3_f32 v5, v5, s85, v226
	v_and_b32_e32 v191, 0xffff0000, v196
	v_med3_f32 v4, v186, s85, v226
	v_add_f32_e32 v186, 1.0, v192
	v_rcp_f32_e32 v192, v187
	v_fma_f32 v187, v193, s89, v147
	v_exp_f32_e32 v193, v5
	v_fma_f32 v189, v189, s89, v144
	v_fma_f32 v191, v191, s89, v135
	v_med3_f32 v189, v189, s85, v226
	v_lshlrev_b32_e32 v227, 16, v197
	v_and_b32_e32 v196, 0xffff0000, v234
	v_med3_f32 v191, v191, s85, v226
	v_exp_f32_e32 v189, v189
	v_med3_f32 v5, v187, s85, v226
	v_add_f32_e32 v187, 1.0, v193
	v_fma_f32 v193, v196, s89, v139
	v_exp_f32_e32 v196, v191
	v_fma_f32 v227, v227, s89, v136
	v_med3_f32 v227, v227, s85, v226
	v_and_b32_e32 v195, 0xffff0000, v195
	v_lshlrev_b32_e32 v228, 16, v235
	v_add_f32_e32 v189, 1.0, v189
	v_exp_f32_e32 v227, v227
	v_med3_f32 v191, v193, s85, v226
	v_add_f32_e32 v193, 1.0, v196
	v_rcp_f32_e32 v196, v189
	v_fma_f32 v189, v228, s89, v140
	v_fma_f32 v195, v195, s89, v145
	v_med3_f32 v189, v189, s85, v226
	v_med3_f32 v195, v195, s85, v226
	v_and_b32_e32 v229, 0xffff0000, v197
	v_lshlrev_b32_e32 v194, 16, v233
	v_and_b32_e32 v197, 0xffff0000, v233
	v_exp_f32_e32 v228, v189
	v_add_f32_e32 v189, 1.0, v227
	v_exp_f32_e32 v227, v195
	v_fma_f32 v194, v194, s89, v148
	v_fma_f32 v197, v197, s89, v149
	v_med3_f32 v194, v194, s85, v226
	v_med3_f32 v195, v197, s85, v226
	v_exp_f32_e32 v4, v4
	v_exp_f32_e32 v5, v5
	v_exp_f32_e32 v194, v194
	v_exp_f32_e32 v195, v195
	v_rcp_f32_e32 v230, v189
	v_add_f32_e32 v189, 1.0, v227
	v_rcp_f32_e32 v186, v186
	v_rcp_f32_e32 v187, v187
	v_rcp_f32_e32 v197, v189
	v_pk_add_f32 v[194:195], v[194:195], 1.0 op_sel_hi:[1,0]
	v_pk_add_f32 v[4:5], v[4:5], 1.0 op_sel_hi:[1,0]
	v_lshlrev_b32_e32 v190, 16, v234
	v_pk_mul_f32 v[4:5], v[186:187], v[4:5]
	v_pk_mul_f32 v[186:187], v[196:197], v[194:195]
	s_waitcnt vmcnt(3)
	s_waitcnt vmcnt(2)
	v_fma_f32 v190, v190, s89, v138
	v_pk_mul_f32 v[28:29], v[28:29], v[186:187]
	v_fma_f32 v187, v229, s89, v137
	v_med3_f32 v190, v190, s85, v226
	v_med3_f32 v187, v187, s85, v226
	v_and_b32_e32 v231, 0xffff0000, v235
	v_exp_f32_e32 v190, v190
	v_exp_f32_e32 v191, v191
	v_exp_f32_e32 v187, v187
	v_rcp_f32_e32 v193, v193
	v_fma_f32 v186, v231, s89, v141
	s_waitcnt vmcnt(1)
	s_waitcnt vmcnt(0)
; #define UNPK0(q_) ((f32x4){bf_lo((q_).x), bf_hi((q_).x), bf_lo((q_).y), bf_hi((q_).y)})
; #define UNPK1(q_) ((f32x4){bf_lo((q_).z), bf_hi((q_).z), bf_lo((q_).w), bf_hi((q_).w)})
;     static __device__ __forceinline__ float eneg(float g) { return __builtin_amdgcn_exp2f(-1.4426950408889634f * fminf(fmaxf(g, -30.f), 30.f)); }
;     __device__ __forceinline__ void mid(f32x4 (&acc)[2][2][4][2], const Unit& u, int wr, int wc, int fr, int fq) const {
;     ...
;         for (int am = 0; am < 4; ++am) { const int ai = am >> 1;
;             u32x4 ra[4][2], rb[4][2];
; #pragma unroll
;             for (int m = 2 * (am & 1); m < 2 * (am & 1) + 2; ++m) { pa.fetch(ai, m, ra[m][0], ra[m][1]); pb.fetch(ai, m, rb[m][0], rb[m][1]); }
;             asm volatile("" ::: "memory");
; #pragma unroll
;             for (int m = 2 * (am & 1); m < 2 * (am & 1) + 2; ++m) {
;                 pa.stage(ra[m][0], ra[m][1]); const u32x4 ga0 = pa.get(0), ga1 = pa.get(1);
;                 asm volatile("" ::: "memory");
;                 pb.stage(rb[m][0], rb[m][1]); const u32x4 gb0 = pb.get(0), gb1 = pb.get(1);
;                 asm volatile("" ::: "memory");
; #pragma unroll
;                 for (int bj = 0; bj < 2; ++bj) { const u32x4 ga = bj ? ga1 : ga0, gb = bj ? gb1 : gb0;
;                     const f32x4 a0 = UNPK0(ga) + ba[bj][0], a1 = UNPK1(ga) + ba[bj][1], b0 = UNPK0(gb) + bb[bj][0], b1 = UNPK1(gb) + bb[bj][1];
; #pragma unroll
;                     for (int k = 0; k < 4; ++k) { acc[ai][bj][m][0][k] *= (1.0f + eneg(b0[k])) * __builtin_amdgcn_rcpf(1.0f + eneg(a0[k]));
;                                                   acc[ai][bj][m][1][k] *= (1.0f + eneg(b1[k])) * __builtin_amdgcn_rcpf(1.0f + eneg(a1[k])); } } }
	v_lshlrev_b32_e32 v3, 16, v174
	v_fma_f32 v3, v3, s89, v158
	v_med3_f32 v186, v186, s85, v226
	v_exp_f32_e32 v229, v186
	v_pk_mul_f32 v[26:27], v[26:27], v[4:5]
	v_add_f32_e32 v4, 1.0, v187
	v_pk_add_f32 v[186:187], v[190:191], 1.0 op_sel_hi:[1,0]
	v_med3_f32 v3, v3, s85, v226
	v_rcp_f32_e32 v231, v4
	v_pk_mul_f32 v[186:187], v[192:193], v[186:187]
	v_exp_f32_e32 v3, v3
	v_pk_mul_f32 v[22:23], v[22:23], v[186:187]
	v_lshlrev_b32_e32 v186, 16, v176
	v_fma_f32 v150, v186, s89, v150
	v_pk_add_f32 v[4:5], v[228:229], 1.0 op_sel_hi:[1,0]
	v_pk_mul_f32 v[4:5], v[230:231], v[4:5]
	v_lshlrev_b32_e32 v189, 16, v168
	v_add_f32_e32 v3, 1.0, v3
	v_med3_f32 v150, v150, s85, v226
	v_pk_mul_f32 v[24:25], v[24:25], v[4:5]
	v_and_b32_e32 v5, 0xffff0000, v174
	v_rcp_f32_e32 v158, v3
	v_fma_f32 v3, v189, s89, v154
	v_exp_f32_e32 v154, v150
	v_fma_f32 v5, v5, s89, v159
	v_med3_f32 v3, v3, s85, v226
	v_med3_f32 v5, v5, s85, v226
	v_lshlrev_b32_e32 v4, 16, v166
	v_and_b32_e32 v166, 0xffff0000, v166
	v_exp_f32_e32 v150, v3
	v_add_f32_e32 v3, 1.0, v154
	v_exp_f32_e32 v159, v5
	v_and_b32_e32 v176, 0xffff0000, v176
	v_rcp_f32_e32 v154, v3
	v_fma_f32 v3, v166, s89, v163
	v_fma_f32 v151, v176, s89, v151
	v_med3_f32 v3, v3, s85, v226
	v_and_b32_e32 v168, 0xffff0000, v168
	v_exp_f32_e32 v5, v3
	v_add_f32_e32 v3, 1.0, v159
	v_med3_f32 v151, v151, s85, v226
	v_lshlrev_b32_e32 v174, 16, v175
	v_rcp_f32_e32 v159, v3
	v_fma_f32 v3, v168, s89, v155
	v_exp_f32_e32 v155, v151
	v_fma_f32 v160, v174, s89, v160
	v_med3_f32 v3, v3, s85, v226
	v_med3_f32 v160, v160, s85, v226
	v_lshlrev_b32_e32 v188, 16, v167
	v_fma_f32 v4, v4, s89, v162
	v_exp_f32_e32 v151, v3
	v_add_f32_e32 v3, 1.0, v155
	v_exp_f32_e32 v162, v160
	v_lshlrev_b32_e32 v187, 16, v177
	v_rcp_f32_e32 v155, v3
	v_fma_f32 v3, v188, s89, v164
	v_fma_f32 v152, v187, s89, v152
	v_med3_f32 v3, v3, s85, v226
	v_and_b32_e32 v175, 0xffff0000, v175
	v_lshlrev_b32_e32 v190, 16, v169
	v_exp_f32_e32 v160, v3
	v_add_f32_e32 v3, 1.0, v162
	v_med3_f32 v152, v152, s85, v226
	v_rcp_f32_e32 v162, v3
	v_fma_f32 v3, v190, s89, v156
	v_exp_f32_e32 v156, v152
	v_fma_f32 v161, v175, s89, v161
	v_med3_f32 v161, v161, s85, v226
	v_and_b32_e32 v167, 0xffff0000, v167
	v_med3_f32 v3, v3, s85, v226
	v_exp_f32_e32 v163, v161
	v_and_b32_e32 v177, 0xffff0000, v177
	v_exp_f32_e32 v152, v3
	v_add_f32_e32 v3, 1.0, v156
	v_fma_f32 v156, v167, s89, v165
	v_fma_f32 v153, v177, s89, v153
	v_med3_f32 v156, v156, s85, v226
	v_and_b32_e32 v169, 0xffff0000, v169
	v_exp_f32_e32 v161, v156
	v_rcp_f32_e32 v156, v3
	v_add_f32_e32 v3, 1.0, v163
	v_med3_f32 v153, v153, s85, v226
	v_rcp_f32_e32 v163, v3
	v_fma_f32 v3, v169, s89, v157
	v_exp_f32_e32 v157, v153
	v_med3_f32 v4, v4, s85, v226
	v_med3_f32 v3, v3, s85, v226
	v_exp_f32_e32 v4, v4
	v_exp_f32_e32 v153, v3
	v_add_f32_e32 v3, 1.0, v157
	v_rcp_f32_e32 v157, v3
	v_lshlrev_b32_e32 v3, 16, v178
	v_fma_f32 v3, v3, s89, v142
	v_pk_add_f32 v[4:5], v[4:5], 1.0 op_sel_hi:[1,0]
	v_med3_f32 v3, v3, s85, v226
	v_pk_mul_f32 v[4:5], v[158:159], v[4:5]
	v_exp_f32_e32 v3, v3
	v_pk_mul_f32 v[18:19], v[18:19], v[4:5]
	v_pk_add_f32 v[4:5], v[152:153], 1.0 op_sel_hi:[1,0]
	v_lshlrev_b32_e32 v152, 16, v180
	v_pk_add_f32 v[160:161], v[160:161], 1.0 op_sel_hi:[1,0]
	v_fma_f32 v134, v152, s89, v134
	v_pk_mul_f32 v[158:159], v[162:163], v[160:161]
	v_pk_mul_f32 v[20:21], v[20:21], v[158:159]
	v_pk_mul_f32 v[4:5], v[156:157], v[4:5]
	v_lshlrev_b32_e32 v159, 16, v172
	v_add_f32_e32 v3, 1.0, v3
	v_med3_f32 v134, v134, s85, v226
	v_pk_mul_f32 v[16:17], v[16:17], v[4:5]
	v_and_b32_e32 v5, 0xffff0000, v178
	v_rcp_f32_e32 v142, v3
	v_fma_f32 v3, v159, s89, v138
	v_exp_f32_e32 v138, v134
	v_fma_f32 v5, v5, s89, v143
	v_med3_f32 v3, v3, s85, v226
	v_med3_f32 v5, v5, s85, v226
	v_and_b32_e32 v156, 0xffff0000, v170
	v_exp_f32_e32 v134, v3
	v_add_f32_e32 v3, 1.0, v138
	v_exp_f32_e32 v143, v5
	v_and_b32_e32 v153, 0xffff0000, v180
	v_rcp_f32_e32 v138, v3
	v_fma_f32 v3, v156, s89, v147
	v_fma_f32 v135, v153, s89, v135
	v_pk_add_f32 v[150:151], v[150:151], 1.0 op_sel_hi:[1,0]
	v_med3_f32 v3, v3, s85, v226
	v_pk_mul_f32 v[150:151], v[154:155], v[150:151]
	v_and_b32_e32 v160, 0xffff0000, v172
	v_exp_f32_e32 v5, v3
	v_add_f32_e32 v3, 1.0, v143
	v_med3_f32 v135, v135, s85, v226
	v_pk_mul_f32 v[14:15], v[14:15], v[150:151]
	v_lshlrev_b32_e32 v150, 16, v179
	v_rcp_f32_e32 v143, v3
	v_fma_f32 v3, v160, s89, v139
	v_exp_f32_e32 v139, v135
	v_fma_f32 v144, v150, s89, v144
	v_lshlrev_b32_e32 v4, 16, v170
	v_med3_f32 v3, v3, s85, v226
	v_med3_f32 v144, v144, s85, v226
	v_lshlrev_b32_e32 v157, 16, v171
	v_fma_f32 v4, v4, s89, v146
	v_exp_f32_e32 v135, v3
	v_add_f32_e32 v3, 1.0, v139
	v_exp_f32_e32 v146, v144
	v_lshlrev_b32_e32 v154, 16, v181
	v_rcp_f32_e32 v139, v3
	v_fma_f32 v3, v157, s89, v148
	v_fma_f32 v136, v154, s89, v136
	v_med3_f32 v3, v3, s85, v226
	v_and_b32_e32 v151, 0xffff0000, v179
	v_lshlrev_b32_e32 v161, 16, v173
	v_exp_f32_e32 v144, v3
	v_add_f32_e32 v3, 1.0, v146
	v_med3_f32 v136, v136, s85, v226
	v_rcp_f32_e32 v146, v3
	v_fma_f32 v3, v161, s89, v140
	v_exp_f32_e32 v140, v136
	v_fma_f32 v145, v151, s89, v145
	v_med3_f32 v145, v145, s85, v226
	v_and_b32_e32 v158, 0xffff0000, v171
	v_med3_f32 v3, v3, s85, v226
	v_exp_f32_e32 v147, v145
	v_and_b32_e32 v155, 0xffff0000, v181
	v_exp_f32_e32 v136, v3
	v_add_f32_e32 v3, 1.0, v140
	v_fma_f32 v140, v158, s89, v149
	v_fma_f32 v137, v155, s89, v137
	v_med3_f32 v140, v140, s85, v226
	v_and_b32_e32 v162, 0xffff0000, v173
	v_exp_f32_e32 v145, v140
	v_rcp_f32_e32 v140, v3
	v_add_f32_e32 v3, 1.0, v147
	v_med3_f32 v137, v137, s85, v226
	v_rcp_f32_e32 v147, v3
	v_fma_f32 v3, v162, s89, v141
	v_exp_f32_e32 v141, v137
	v_med3_f32 v4, v4, s85, v226
	v_exp_f32_e32 v4, v4
	v_med3_f32 v3, v3, s85, v226
	v_exp_f32_e32 v137, v3
	v_add_f32_e32 v3, 1.0, v141
	v_rcp_f32_e32 v141, v3
	v_pk_add_f32 v[4:5], v[4:5], 1.0 op_sel_hi:[1,0]
	v_pk_add_f32 v[144:145], v[144:145], 1.0 op_sel_hi:[1,0]
	v_pk_mul_f32 v[4:5], v[142:143], v[4:5]
	v_pk_add_f32 v[134:135], v[134:135], 1.0 op_sel_hi:[1,0]
	v_pk_mul_f32 v[10:11], v[10:11], v[4:5]
	v_pk_add_f32 v[4:5], v[136:137], 1.0 op_sel_hi:[1,0]
	v_pk_mul_f32 v[142:143], v[146:147], v[144:145]
	v_pk_mul_f32 v[134:135], v[138:139], v[134:135]
	v_pk_mul_f32 v[4:5], v[140:141], v[4:5]
	v_pk_mul_f32 v[12:13], v[12:13], v[142:143]
	v_pk_mul_f32 v[8:9], v[8:9], v[4:5]
	v_pk_mul_f32 v[6:7], v[6:7], v[134:135]
	s_branch .LBB0_380

; __device__ __forceinline__ size_t tm_block(int pm, int ct, int nct) { return ((size_t)pm * nct + ct) * 32768; }
; __device__ __forceinline__ u32x4 pack8(const f32x4& v0, const f32x4& v1) { u32x4 w; w.x = cvt_pk_bf16(v0[0], v0[1]); w.y = cvt_pk_bf16(v0[2], v0[3]); w.z = cvt_pk_bf16(v1[0], v1[1]); w.w = cvt_pk_bf16(v1[2], v1[3]); return w; }
; #define UNPK0(q_) ((f32x4){bf_lo((q_).x), bf_hi((q_).x), bf_lo((q_).y), bf_hi((q_).y)})
; #define UNPK1(q_) ((f32x4){bf_lo((q_).z), bf_hi((q_).z), bf_lo((q_).w), bf_hi((q_).w)})
;     static __device__ __forceinline__ float eneg(float g) { return __builtin_amdgcn_exp2f(-1.4426950408889634f * fminf(fmaxf(g, -30.f), 30.f)); }
;     __device__ __forceinline__ void operator()(const f32x4 (&acc)[2][2][4][2], const Unit& u, int wr, int wc, int fr, int fq) const {
;         const int cb = u.pn * 4 + wc, col0 = cb * 64 + 8 * fq;
;         const PieceOut po(scr, O, tm_block(u.pm, cb, 16), wr, wc, fr, fq);
;         const PieceIn pb(scr, Z, tm_block(u.pm, gb_ct + cb, znct), wr, wc, fr, fq);
;         f32x4 bb[2][2];
; #pragma unroll
;         for (int bj = 0; bj < 2; ++bj) { bb[bj][0] = *(const f32x4*)(bg + 1024 + col0 + bj * 32); bb[bj][1] = *(const f32x4*)(bg + 1024 + col0 + bj * 32 + 4); }
;         u32x4 rb[2][4][2];
; #pragma unroll
;         for (int ai = 0; ai < 2; ++ai)
; #pragma unroll
;             for (int m = 0; m < 4; ++m) pb.fetch(ai, m, rb[ai][m][0], rb[ai][m][1]);
;         asm volatile("" ::: "memory");
; #pragma unroll
;         for (int ai = 0; ai < 2; ++ai)
; #pragma unroll
;             for (int m = 0; m < 4; ++m) {
;                 pb.stage(rb[ai][m][0], rb[ai][m][1]); const u32x4 gb0 = pb.get(0), gb1 = pb.get(1);
;                 asm volatile("" ::: "memory");
; #pragma unroll
;                 for (int bj = 0; bj < 2; ++bj) { const u32x4 gb = bj ? gb1 : gb0;
;                     const f32x4 b0 = UNPK0(gb) + bb[bj][0], b1 = UNPK1(gb) + bb[bj][1];
;                     f32x4 v0 = acc[ai][bj][m][0], v1 = acc[ai][bj][m][1];
; #pragma unroll
;                     for (int k = 0; k < 4; ++k) { v0[k] *= __builtin_amdgcn_rcpf(1.0f + eneg(b0[k])); v1[k] *= __builtin_amdgcn_rcpf(1.0f + eneg(b1[k])); }
;                     po.put(bj, pack8(v0, v1)); }
.LBB0_385:
	s_ashr_i32 s27, s26, 31
	s_lshl_b64 s[0:1], s[26:27], 19
	s_add_u32 s19, s3, s0
	s_addc_u32 s21, s76, s1
	s_add_i32 s0, s44, 52
	s_mul_hi_i32 s1, s26, 0x44
	s_mulk_i32 s26, 0x44
	s_ashr_i32 s27, s0, 31
	s_add_u32 s0, s26, s0
	s_addc_u32 s1, s1, s27
	s_lshl_b64 s[0:1], s[0:1], 15
	v_lshl_add_u64 v[4:5], v[208:209], 0, s[0:1]
	global_load_dwordx4 v[228:231], v[4:5], off
	global_load_dwordx4 v[232:235], v[4:5], off offset:1024
	v_lshl_or_b32 v134, s44, 6, v219
	v_ashrrev_i32_e32 v135, 31, v134
	v_lshlrev_b64 v[134:135], 2, v[134:135]
	v_lshl_add_u64 v[136:137], s[16:17], 0, v[134:135]
	v_lshl_add_u64 v[134:135], s[42:43], 0, v[134:135]
	v_add_co_u32_e32 v134, vcc, s84, v134
	global_load_dwordx4 v[146:149], v[136:137], off
	s_nop 0
	v_addc_co_u32_e32 v135, vcc, 0, v135, vcc
	global_load_dwordx4 v[142:145], v[134:135], off offset:16
	global_load_dwordx4 v[138:141], v[136:137], off offset:128
	s_nop 0
	global_load_dwordx4 v[134:137], v[134:135], off offset:144
	s_nop 0
	global_load_dwordx4 v[236:239], v[4:5], off offset:2048
	global_load_dwordx4 v[240:243], v[4:5], off offset:3072
	v_add_co_u32_e32 v150, vcc, s84, v4
	v_add_u32_e32 v3, v224, v222
	s_nop 0
	v_addc_co_u32_e32 v151, vcc, 0, v5, vcc
	v_add_co_u32_e32 v152, vcc, s79, v4
	v_add_u32_e32 v227, v223, v220
	s_nop 0
	v_addc_co_u32_e32 v153, vcc, 0, v5, vcc
	v_add_co_u32_e32 v4, vcc, s86, v4
	s_ashr_i32 s45, s44, 31
	s_nop 0
	v_addc_co_u32_e32 v5, vcc, 0, v5, vcc
	global_load_dwordx4 v[190:193], v[150:151], off
	global_load_dwordx4 v[194:197], v[150:151], off offset:1024
	global_load_dwordx4 v[182:185], v[150:151], off offset:2048
	global_load_dwordx4 v[186:189], v[150:151], off offset:3072
	global_load_dwordx4 v[174:177], v[152:153], off offset:1024
	global_load_dwordx4 v[166:169], v[152:153], off offset:2048
	global_load_dwordx4 v[178:181], v[4:5], off offset:-4096
	global_load_dwordx4 v[170:173], v[152:153], off offset:3072
	global_load_dwordx4 v[158:161], v[4:5], off
	global_load_dwordx4 v[162:165], v[4:5], off offset:1024
	s_nop 0
	global_load_dwordx4 v[150:153], v[4:5], off offset:2048
	global_load_dwordx4 v[154:157], v[4:5], off offset:3072
	s_lshl_b64 s[0:1], s[44:45], 15
	s_add_u32 s0, s19, s0
	s_addc_u32 s1, s21, s1
	s_add_u32 s0, s0, s12
	s_addc_u32 s1, s1, s13
	s_waitcnt vmcnt(0)
	v_mul_f32_e32 v134, 0xbfb8aa3b, v134
	v_mul_f32_e32 v135, 0xbfb8aa3b, v135
	v_mul_f32_e32 v136, 0xbfb8aa3b, v136
	v_mul_f32_e32 v137, 0xbfb8aa3b, v137
	v_mul_f32_e32 v138, 0xbfb8aa3b, v138
	v_mul_f32_e32 v139, 0xbfb8aa3b, v139
	v_mul_f32_e32 v140, 0xbfb8aa3b, v140
	v_mul_f32_e32 v141, 0xbfb8aa3b, v141
	v_mul_f32_e32 v142, 0xbfb8aa3b, v142
	v_mul_f32_e32 v143, 0xbfb8aa3b, v143
	v_mul_f32_e32 v144, 0xbfb8aa3b, v144
	v_mul_f32_e32 v145, 0xbfb8aa3b, v145
	v_mul_f32_e32 v146, 0xbfb8aa3b, v146
	v_mul_f32_e32 v147, 0xbfb8aa3b, v147
	v_mul_f32_e32 v148, 0xbfb8aa3b, v148
	v_mul_f32_e32 v149, 0xbfb8aa3b, v149
	v_lshlrev_b32_e32 v4, 16, v228
	v_lshlrev_b32_e32 v244, 16, v230
	v_fma_f32 v4, v4, s89, v146
	v_med3_f32 v4, v4, s85, v226
	v_fma_f32 v244, v244, s89, v142
	v_med3_f32 v244, v244, s85, v226
	v_exp_f32_e32 v4, v4
	v_exp_f32_e32 v244, v244
	v_and_b32_e32 v5, 0xffff0000, v228
	v_lshlrev_b32_e32 v228, 16, v229
	v_fma_f32 v228, v228, s89, v148
	v_and_b32_e32 v230, 0xffff0000, v230
	v_fma_f32 v5, v5, s89, v147
	v_fma_f32 v230, v230, s89, v143
	v_med3_f32 v228, v228, s85, v226
	v_add_f32_e32 v4, 1.0, v4
	v_add_f32_e32 v244, 1.0, v244
	v_exp_f32_e32 v228, v228
	v_rcp_f32_e32 v4, v4
	v_rcp_f32_e32 v244, v244
	v_med3_f32 v5, v5, s85, v226
	v_med3_f32 v230, v230, s85, v226
	v_exp_f32_e32 v5, v5
	v_exp_f32_e32 v230, v230
	v_and_b32_e32 v229, 0xffff0000, v229
	v_lshlrev_b32_e32 v245, 16, v231
	v_and_b32_e32 v231, 0xffff0000, v231
	v_fma_f32 v245, v245, s89, v144
	v_mul_f32_e32 v4, v130, v4
	v_mul_f32_e32 v130, v126, v244
	v_add_f32_e32 v126, 1.0, v228
	v_fma_f32 v228, v229, s89, v149
	v_fma_f32 v229, v231, s89, v145
	v_med3_f32 v245, v245, s85, v226
	v_add_f32_e32 v5, 1.0, v5
	v_add_f32_e32 v230, 1.0, v230
	v_med3_f32 v228, v228, s85, v226
	v_exp_f32_e32 v245, v245
	v_rcp_f32_e32 v5, v5
	v_rcp_f32_e32 v230, v230
	v_exp_f32_e32 v228, v228
	v_med3_f32 v229, v229, s85, v226
	v_exp_f32_e32 v229, v229
	v_mul_f32_e32 v5, v131, v5
	v_mul_f32_e32 v131, v127, v230
	v_add_f32_e32 v127, 1.0, v245
	v_add_f32_e32 v228, 1.0, v228
	v_rcp_f32_e32 v126, v126
	v_rcp_f32_e32 v127, v127
	v_rcp_f32_e32 v228, v228
	v_add_f32_e32 v229, 1.0, v229
	v_rcp_f32_e32 v229, v229
	v_mul_f32_e32 v132, v132, v126
	v_mul_f32_e32 v230, v128, v127
	v_mul_f32_e32 v127, v133, v228
	v_cvt_pk_bf16_f32 v126, v4, v5
	v_and_b32_e32 v5, 0xffff0000, v232
	v_mul_f32_e32 v129, v129, v229
	v_cvt_pk_bf16_f32 v127, v132, v127
	v_cvt_pk_bf16_f32 v128, v130, v131
	v_fma_f32 v5, v5, s89, v139
	v_cvt_pk_bf16_f32 v129, v230, v129
	ds_write_b128 v227, v[126:129]
	v_lshlrev_b32_e32 v4, 16, v232
	v_lshlrev_b32_e32 v128, 16, v234
	v_fma_f32 v4, v4, s89, v138
	v_fma_f32 v128, v128, s89, v134
	v_med3_f32 v5, v5, s85, v226
	v_exp_f32_e32 v5, v5
	v_med3_f32 v4, v4, s85, v226
	v_med3_f32 v128, v128, s85, v226
	v_exp_f32_e32 v4, v4
	v_exp_f32_e32 v128, v128
	v_and_b32_e32 v129, 0xffff0000, v234
	v_add_f32_e32 v5, 1.0, v5
	v_fma_f32 v129, v129, s89, v135
	v_rcp_f32_e32 v5, v5
	v_add_f32_e32 v4, 1.0, v4
	v_add_f32_e32 v128, 1.0, v128
	v_med3_f32 v129, v129, s85, v226
	v_rcp_f32_e32 v4, v4
	v_rcp_f32_e32 v128, v128
	v_exp_f32_e32 v129, v129
	v_lshlrev_b32_e32 v126, 16, v233
	v_lshlrev_b32_e32 v130, 16, v235
	v_mul_f32_e32 v5, v123, v5
	v_fma_f32 v123, v126, s89, v140
	v_fma_f32 v126, v130, s89, v136
	v_mul_f32_e32 v4, v122, v4
	v_mul_f32_e32 v122, v118, v128
	v_add_f32_e32 v118, 1.0, v129
	v_med3_f32 v123, v123, s85, v226
	v_med3_f32 v126, v126, s85, v226
	v_rcp_f32_e32 v118, v118
	v_exp_f32_e32 v123, v123
	v_exp_f32_e32 v126, v126
	v_and_b32_e32 v127, 0xffff0000, v233
	v_and_b32_e32 v131, 0xffff0000, v235
	v_mul_f32_e32 v128, v119, v118
	v_add_f32_e32 v118, 1.0, v123
	v_add_f32_e32 v119, 1.0, v126
	v_fma_f32 v123, v127, s89, v141
	v_fma_f32 v126, v131, s89, v137
	v_med3_f32 v123, v123, s85, v226
	v_med3_f32 v126, v126, s85, v226
	v_exp_f32_e32 v123, v123
	v_exp_f32_e32 v126, v126
	v_rcp_f32_e32 v119, v119
	v_rcp_f32_e32 v118, v118
	v_add_f32_e32 v123, 1.0, v123
	v_add_f32_e32 v126, 1.0, v126
	v_rcp_f32_e32 v123, v123
	v_rcp_f32_e32 v126, v126
	v_mul_f32_e32 v127, v120, v119
	v_mul_f32_e32 v124, v124, v118
	v_mul_f32_e32 v119, v125, v123
	v_mul_f32_e32 v121, v121, v126
	v_cvt_pk_bf16_f32 v118, v4, v5
	v_cvt_pk_bf16_f32 v119, v124, v119
	v_cvt_pk_bf16_f32 v120, v122, v128
	v_cvt_pk_bf16_f32 v121, v127, v121
	ds_write_b128 v227, v[118:121] offset:64
	ds_read_b128 v[118:121], v3
	ds_read_b128 v[122:125], v3 offset:1152
	v_lshl_add_u64 v[4:5], s[0:1], 0, v[206:207]
	s_waitcnt lgkmcnt(1)
; __device__ __forceinline__ u32x4 pack8(const f32x4& v0, const f32x4& v1) { u32x4 w; w.x = cvt_pk_bf16(v0[0], v0[1]); w.y = cvt_pk_bf16(v0[2], v0[3]); w.z = cvt_pk_bf16(v1[0], v1[1]); w.w = cvt_pk_bf16(v1[2], v1[3]); return w; }
; #define UNPK0(q_) ((f32x4){bf_lo((q_).x), bf_hi((q_).x), bf_lo((q_).y), bf_hi((q_).y)})
; #define UNPK1(q_) ((f32x4){bf_lo((q_).z), bf_hi((q_).z), bf_lo((q_).w), bf_hi((q_).w)})
;     static __device__ __forceinline__ float eneg(float g) { return __builtin_amdgcn_exp2f(-1.4426950408889634f * fminf(fmaxf(g, -30.f), 30.f)); }
;     __device__ __forceinline__ void operator()(const f32x4 (&acc)[2][2][4][2], const Unit& u, int wr, int wc, int fr, int fq) const {
;     ...
;         for (int ai = 0; ai < 2; ++ai)
; #pragma unroll
;             for (int m = 0; m < 4; ++m) {
;                 pb.stage(rb[ai][m][0], rb[ai][m][1]); const u32x4 gb0 = pb.get(0), gb1 = pb.get(1);
;                 asm volatile("" ::: "memory");
; #pragma unroll
;                 for (int bj = 0; bj < 2; ++bj) { const u32x4 gb = bj ? gb1 : gb0;
;                     const f32x4 b0 = UNPK0(gb) + bb[bj][0], b1 = UNPK1(gb) + bb[bj][1];
;                     f32x4 v0 = acc[ai][bj][m][0], v1 = acc[ai][bj][m][1];
; #pragma unroll
;                     for (int k = 0; k < 4; ++k) { v0[k] *= __builtin_amdgcn_rcpf(1.0f + eneg(b0[k])); v1[k] *= __builtin_amdgcn_rcpf(1.0f + eneg(b1[k])); }
;                     po.put(bj, pack8(v0, v1)); }
;                 po.flush<false>(ai, m);
;                 asm volatile("" ::: "memory"); }
	global_store_dwordx4 v[4:5], v[118:121], off
	s_waitcnt lgkmcnt(0)
	global_store_dwordx4 v[4:5], v[122:125], off offset:1024
	v_mov_b64_e32 v[118:119], v[236:237]
	v_mov_b64_e32 v[120:121], v[238:239]
	v_mov_b64_e32 v[122:123], v[240:241]
	v_mov_b64_e32 v[124:125], v[242:243]
	s_waitcnt lgkmcnt(0)
	v_lshlrev_b32_e32 v126, 16, v118
	v_and_b32_e32 v118, 0xffff0000, v118
	v_lshlrev_b32_e32 v128, 16, v120
	v_fma_f32 v126, v126, s89, v146
	v_fma_f32 v128, v128, s89, v142
	v_fma_f32 v118, v118, s89, v147
	v_med3_f32 v126, v126, s85, v226
	v_med3_f32 v128, v128, s85, v226
	v_med3_f32 v118, v118, s85, v226
	v_exp_f32_e32 v126, v126
	v_exp_f32_e32 v128, v128
	v_exp_f32_e32 v118, v118
	v_and_b32_e32 v120, 0xffff0000, v120
	v_fma_f32 v120, v120, s89, v143
	v_add_f32_e32 v126, 1.0, v126
	v_add_f32_e32 v128, 1.0, v128
	v_add_f32_e32 v118, 1.0, v118
	v_med3_f32 v120, v120, s85, v226
	v_rcp_f32_e32 v126, v126
	v_rcp_f32_e32 v128, v128
	v_rcp_f32_e32 v118, v118
	v_exp_f32_e32 v120, v120
	v_lshlrev_b32_e32 v127, 16, v119
	v_lshlrev_b32_e32 v129, 16, v121
	v_mul_f32_e32 v114, v114, v126
	v_mul_f32_e32 v126, v110, v128
	v_mul_f32_e32 v110, v115, v118
	v_add_f32_e32 v115, 1.0, v120
	v_fma_f32 v118, v127, s89, v148
	v_fma_f32 v120, v129, s89, v144
	v_med3_f32 v118, v118, s85, v226
	v_med3_f32 v120, v120, s85, v226
	v_rcp_f32_e32 v115, v115
	v_exp_f32_e32 v118, v118
	v_exp_f32_e32 v120, v120
	v_and_b32_e32 v119, 0xffff0000, v119
	v_and_b32_e32 v121, 0xffff0000, v121
	v_mul_f32_e32 v115, v111, v115
	v_add_f32_e32 v111, 1.0, v118
	v_add_f32_e32 v118, 1.0, v120
	v_fma_f32 v119, v119, s89, v149
	v_fma_f32 v120, v121, s89, v145
	v_med3_f32 v119, v119, s85, v226
	v_med3_f32 v120, v120, s85, v226
	v_exp_f32_e32 v119, v119
	v_exp_f32_e32 v120, v120
	v_rcp_f32_e32 v111, v111
	v_rcp_f32_e32 v118, v118
	v_add_f32_e32 v119, 1.0, v119
	v_add_f32_e32 v120, 1.0, v120
	v_rcp_f32_e32 v119, v119
	v_rcp_f32_e32 v120, v120
	v_mul_f32_e32 v111, v116, v111
	v_mul_f32_e32 v116, v112, v118
	v_mul_f32_e32 v112, v117, v119
	v_mul_f32_e32 v113, v113, v120
	v_cvt_pk_bf16_f32 v110, v114, v110
	v_cvt_pk_bf16_f32 v111, v111, v112
	v_cvt_pk_bf16_f32 v112, v126, v115
	v_cvt_pk_bf16_f32 v113, v116, v113
	ds_write_b128 v227, v[110:113]
	s_waitcnt lgkmcnt(1)
	v_lshlrev_b32_e32 v110, 16, v122
	v_and_b32_e32 v111, 0xffff0000, v122
	v_lshlrev_b32_e32 v114, 16, v124
	v_fma_f32 v110, v110, s89, v138
	v_fma_f32 v114, v114, s89, v134
	v_fma_f32 v111, v111, s89, v139
	v_med3_f32 v110, v110, s85, v226
	v_med3_f32 v114, v114, s85, v226
	v_med3_f32 v111, v111, s85, v226
	v_exp_f32_e32 v110, v110
	v_exp_f32_e32 v114, v114
	v_exp_f32_e32 v111, v111
	v_and_b32_e32 v115, 0xffff0000, v124
	v_add_f32_e32 v110, 1.0, v110
	v_add_f32_e32 v114, 1.0, v114
	v_add_f32_e32 v111, 1.0, v111
	v_fma_f32 v115, v115, s89, v135
	v_rcp_f32_e32 v110, v110
	v_rcp_f32_e32 v114, v114
	v_rcp_f32_e32 v111, v111
	v_med3_f32 v115, v115, s85, v226
	v_exp_f32_e32 v115, v115
	v_lshlrev_b32_e32 v112, 16, v123
	v_lshlrev_b32_e32 v116, 16, v125
	v_mul_f32_e32 v106, v106, v110
	v_mul_f32_e32 v110, v102, v114
	v_mul_f32_e32 v102, v107, v111
	v_fma_f32 v111, v112, s89, v140
	v_fma_f32 v112, v116, s89, v136
	v_add_f32_e32 v107, 1.0, v115
	v_med3_f32 v111, v111, s85, v226
	v_med3_f32 v112, v112, s85, v226
	v_rcp_f32_e32 v107, v107
	v_exp_f32_e32 v111, v111
	v_exp_f32_e32 v112, v112
	v_and_b32_e32 v113, 0xffff0000, v123
	v_and_b32_e32 v117, 0xffff0000, v125
	v_mul_f32_e32 v107, v103, v107
	v_add_f32_e32 v103, 1.0, v111
	v_add_f32_e32 v111, 1.0, v112
	v_fma_f32 v112, v113, s89, v141
	v_fma_f32 v113, v117, s89, v137
	v_med3_f32 v112, v112, s85, v226
	v_med3_f32 v113, v113, s85, v226
	v_exp_f32_e32 v112, v112
	v_exp_f32_e32 v113, v113
	v_rcp_f32_e32 v103, v103
	v_rcp_f32_e32 v111, v111
	v_add_f32_e32 v112, 1.0, v112
	v_add_f32_e32 v113, 1.0, v113
	v_rcp_f32_e32 v112, v112
	v_rcp_f32_e32 v113, v113
	v_mul_f32_e32 v103, v108, v103
	v_mul_f32_e32 v108, v104, v111
	v_mul_f32_e32 v104, v109, v112
	v_mul_f32_e32 v105, v105, v113
	v_cvt_pk_bf16_f32 v102, v106, v102
	v_cvt_pk_bf16_f32 v103, v103, v104
	v_cvt_pk_bf16_f32 v104, v110, v107
	v_cvt_pk_bf16_f32 v105, v108, v105
	ds_write_b128 v227, v[102:105] offset:64
	ds_read_b128 v[102:105], v3
	ds_read_b128 v[106:109], v3 offset:1152
	s_waitcnt lgkmcnt(1)
	global_store_dwordx4 v[4:5], v[102:105], off offset:2048
	s_waitcnt lgkmcnt(0)
	global_store_dwordx4 v[4:5], v[106:109], off offset:3072
	v_mov_b64_e32 v[102:103], v[190:191]
	v_mov_b64_e32 v[104:105], v[192:193]
	v_mov_b64_e32 v[106:107], v[194:195]
	v_mov_b64_e32 v[108:109], v[196:197]
	s_waitcnt lgkmcnt(0)
	v_lshlrev_b32_e32 v110, 16, v102
	v_and_b32_e32 v102, 0xffff0000, v102
	v_lshlrev_b32_e32 v112, 16, v104
	v_fma_f32 v110, v110, s89, v146
	v_fma_f32 v112, v112, s89, v142
	v_fma_f32 v102, v102, s89, v147
	v_med3_f32 v110, v110, s85, v226
	v_med3_f32 v112, v112, s85, v226
	v_med3_f32 v102, v102, s85, v226
	v_exp_f32_e32 v110, v110
	v_exp_f32_e32 v112, v112
	v_exp_f32_e32 v102, v102
	v_and_b32_e32 v104, 0xffff0000, v104
	v_fma_f32 v104, v104, s89, v143
	v_add_f32_e32 v110, 1.0, v110
	v_add_f32_e32 v112, 1.0, v112
	v_add_f32_e32 v102, 1.0, v102
	v_med3_f32 v104, v104, s85, v226
	v_rcp_f32_e32 v110, v110
	v_rcp_f32_e32 v112, v112
	v_rcp_f32_e32 v102, v102
	v_exp_f32_e32 v104, v104
	v_lshlrev_b32_e32 v111, 16, v103
	v_lshlrev_b32_e32 v113, 16, v105
	v_mul_f32_e32 v98, v98, v110
	v_mul_f32_e32 v110, v94, v112
	v_mul_f32_e32 v94, v99, v102
	v_add_f32_e32 v99, 1.0, v104
	v_fma_f32 v102, v111, s89, v148
	v_fma_f32 v104, v113, s89, v144
	v_med3_f32 v102, v102, s85, v226
	v_med3_f32 v104, v104, s85, v226
	v_rcp_f32_e32 v99, v99
	v_exp_f32_e32 v102, v102
	v_exp_f32_e32 v104, v104
	v_and_b32_e32 v103, 0xffff0000, v103
	v_and_b32_e32 v105, 0xffff0000, v105
	v_mul_f32_e32 v99, v95, v99
	v_add_f32_e32 v95, 1.0, v102
	v_add_f32_e32 v102, 1.0, v104
	v_fma_f32 v103, v103, s89, v149
	v_fma_f32 v104, v105, s89, v145
	v_med3_f32 v103, v103, s85, v226
	v_med3_f32 v104, v104, s85, v226
	v_exp_f32_e32 v103, v103
	v_exp_f32_e32 v104, v104
	v_rcp_f32_e32 v95, v95
	v_rcp_f32_e32 v102, v102
	v_add_f32_e32 v103, 1.0, v103
	v_add_f32_e32 v104, 1.0, v104
	v_rcp_f32_e32 v103, v103
	v_rcp_f32_e32 v104, v104
	v_mul_f32_e32 v95, v100, v95
	v_mul_f32_e32 v100, v96, v102
	v_mul_f32_e32 v96, v101, v103
	v_mul_f32_e32 v97, v97, v104
	v_cvt_pk_bf16_f32 v94, v98, v94
	v_cvt_pk_bf16_f32 v95, v95, v96
	v_cvt_pk_bf16_f32 v96, v110, v99
	v_cvt_pk_bf16_f32 v97, v100, v97
	ds_write_b128 v227, v[94:97]
	s_waitcnt lgkmcnt(1)
; __device__ __forceinline__ u32x4 pack8(const f32x4& v0, const f32x4& v1) { u32x4 w; w.x = cvt_pk_bf16(v0[0], v0[1]); w.y = cvt_pk_bf16(v0[2], v0[3]); w.z = cvt_pk_bf16(v1[0], v1[1]); w.w = cvt_pk_bf16(v1[2], v1[3]); return w; }
; #define UNPK0(q_) ((f32x4){bf_lo((q_).x), bf_hi((q_).x), bf_lo((q_).y), bf_hi((q_).y)})
; #define UNPK1(q_) ((f32x4){bf_lo((q_).z), bf_hi((q_).z), bf_lo((q_).w), bf_hi((q_).w)})
;     static __device__ __forceinline__ float eneg(float g) { return __builtin_amdgcn_exp2f(-1.4426950408889634f * fminf(fmaxf(g, -30.f), 30.f)); }
;     __device__ __forceinline__ void operator()(const f32x4 (&acc)[2][2][4][2], const Unit& u, int wr, int wc, int fr, int fq) const {
;     ...
;         for (int ai = 0; ai < 2; ++ai)
; #pragma unroll
;             for (int m = 0; m < 4; ++m) {
;                 pb.stage(rb[ai][m][0], rb[ai][m][1]); const u32x4 gb0 = pb.get(0), gb1 = pb.get(1);
;                 asm volatile("" ::: "memory");
; #pragma unroll
;                 for (int bj = 0; bj < 2; ++bj) { const u32x4 gb = bj ? gb1 : gb0;
;                     const f32x4 b0 = UNPK0(gb) + bb[bj][0], b1 = UNPK1(gb) + bb[bj][1];
;                     f32x4 v0 = acc[ai][bj][m][0], v1 = acc[ai][bj][m][1];
; #pragma unroll
;                     for (int k = 0; k < 4; ++k) { v0[k] *= __builtin_amdgcn_rcpf(1.0f + eneg(b0[k])); v1[k] *= __builtin_amdgcn_rcpf(1.0f + eneg(b1[k])); }
;                     po.put(bj, pack8(v0, v1)); }
;                 po.flush<false>(ai, m);
;                 asm volatile("" ::: "memory"); }
	v_lshlrev_b32_e32 v94, 16, v106
	v_and_b32_e32 v95, 0xffff0000, v106
	v_lshlrev_b32_e32 v98, 16, v108
	v_fma_f32 v94, v94, s89, v138
	v_fma_f32 v98, v98, s89, v134
	v_fma_f32 v95, v95, s89, v139
	v_med3_f32 v94, v94, s85, v226
	v_med3_f32 v98, v98, s85, v226
	v_med3_f32 v95, v95, s85, v226
	v_exp_f32_e32 v94, v94
	v_exp_f32_e32 v98, v98
	v_exp_f32_e32 v95, v95
	v_and_b32_e32 v99, 0xffff0000, v108
	v_add_f32_e32 v94, 1.0, v94
	v_add_f32_e32 v98, 1.0, v98
	v_add_f32_e32 v95, 1.0, v95
	v_fma_f32 v99, v99, s89, v135
	v_rcp_f32_e32 v94, v94
	v_rcp_f32_e32 v98, v98
	v_rcp_f32_e32 v95, v95
	v_med3_f32 v99, v99, s85, v226
	v_exp_f32_e32 v99, v99
	v_lshlrev_b32_e32 v96, 16, v107
	v_lshlrev_b32_e32 v100, 16, v109
	v_mul_f32_e32 v90, v90, v94
	v_mul_f32_e32 v94, v86, v98
	v_mul_f32_e32 v86, v91, v95
	v_fma_f32 v95, v96, s89, v140
	v_fma_f32 v96, v100, s89, v136
	v_add_f32_e32 v91, 1.0, v99
	v_med3_f32 v95, v95, s85, v226
	v_med3_f32 v96, v96, s85, v226
	v_rcp_f32_e32 v91, v91
	v_exp_f32_e32 v95, v95
	v_exp_f32_e32 v96, v96
	v_and_b32_e32 v97, 0xffff0000, v107
	v_and_b32_e32 v101, 0xffff0000, v109
	v_mul_f32_e32 v91, v87, v91
	v_add_f32_e32 v87, 1.0, v95
	v_add_f32_e32 v95, 1.0, v96
	v_fma_f32 v96, v97, s89, v141
	v_fma_f32 v97, v101, s89, v137
	v_med3_f32 v96, v96, s85, v226
	v_med3_f32 v97, v97, s85, v226
	v_exp_f32_e32 v96, v96
	v_exp_f32_e32 v97, v97
	v_rcp_f32_e32 v87, v87
	v_rcp_f32_e32 v95, v95
	v_add_f32_e32 v96, 1.0, v96
	v_add_f32_e32 v97, 1.0, v97
	v_rcp_f32_e32 v96, v96
	v_rcp_f32_e32 v97, v97
	v_mul_f32_e32 v87, v92, v87
	v_mul_f32_e32 v92, v88, v95
	v_mul_f32_e32 v88, v93, v96
	v_mul_f32_e32 v89, v89, v97
	v_cvt_pk_bf16_f32 v86, v90, v86
	v_cvt_pk_bf16_f32 v87, v87, v88
	v_cvt_pk_bf16_f32 v88, v94, v91
	v_cvt_pk_bf16_f32 v89, v92, v89
	ds_write_b128 v227, v[86:89] offset:64
	ds_read_b128 v[86:89], v3
	ds_read_b128 v[90:93], v3 offset:1152
	v_add_co_u32_e32 v94, vcc, s84, v4
	s_nop 1
	v_addc_co_u32_e32 v95, vcc, 0, v5, vcc
	s_waitcnt lgkmcnt(1)
	global_store_dwordx4 v[94:95], v[86:89], off
	s_waitcnt lgkmcnt(0)
	global_store_dwordx4 v[94:95], v[90:93], off offset:1024
	v_mov_b64_e32 v[86:87], v[182:183]
	v_mov_b64_e32 v[88:89], v[184:185]
	v_mov_b64_e32 v[90:91], v[186:187]
	v_mov_b64_e32 v[92:93], v[188:189]
	s_waitcnt lgkmcnt(0)
	v_lshlrev_b32_e32 v96, 16, v86
	v_and_b32_e32 v86, 0xffff0000, v86
	v_lshlrev_b32_e32 v98, 16, v88
	v_fma_f32 v96, v96, s89, v146
	v_fma_f32 v98, v98, s89, v142
	v_fma_f32 v86, v86, s89, v147
	v_med3_f32 v96, v96, s85, v226
	v_med3_f32 v98, v98, s85, v226
	v_med3_f32 v86, v86, s85, v226
	v_exp_f32_e32 v96, v96
	v_exp_f32_e32 v98, v98
	v_exp_f32_e32 v86, v86
	v_and_b32_e32 v88, 0xffff0000, v88
	v_fma_f32 v88, v88, s89, v143
	v_add_f32_e32 v96, 1.0, v96
	v_add_f32_e32 v98, 1.0, v98
	v_add_f32_e32 v86, 1.0, v86
	v_med3_f32 v88, v88, s85, v226
	v_rcp_f32_e32 v96, v96
	v_rcp_f32_e32 v98, v98
	v_rcp_f32_e32 v86, v86
	v_exp_f32_e32 v88, v88
	v_lshlrev_b32_e32 v97, 16, v87
	v_lshlrev_b32_e32 v99, 16, v89
	v_mul_f32_e32 v82, v82, v96
	v_mul_f32_e32 v96, v78, v98
	v_mul_f32_e32 v78, v83, v86
	v_add_f32_e32 v83, 1.0, v88
	v_fma_f32 v86, v97, s89, v148
	v_fma_f32 v88, v99, s89, v144
	v_med3_f32 v86, v86, s85, v226
	v_med3_f32 v88, v88, s85, v226
	v_rcp_f32_e32 v83, v83
	v_exp_f32_e32 v86, v86
	v_exp_f32_e32 v88, v88
	v_and_b32_e32 v87, 0xffff0000, v87
	v_and_b32_e32 v89, 0xffff0000, v89
	v_mul_f32_e32 v83, v79, v83
	v_add_f32_e32 v79, 1.0, v86
	v_add_f32_e32 v86, 1.0, v88
	v_fma_f32 v87, v87, s89, v149
	v_fma_f32 v88, v89, s89, v145
	v_med3_f32 v87, v87, s85, v226
	v_med3_f32 v88, v88, s85, v226
	v_exp_f32_e32 v87, v87
	v_exp_f32_e32 v88, v88
	v_rcp_f32_e32 v79, v79
	v_rcp_f32_e32 v86, v86
	v_add_f32_e32 v87, 1.0, v87
	v_add_f32_e32 v88, 1.0, v88
	v_rcp_f32_e32 v87, v87
	v_rcp_f32_e32 v88, v88
	v_mul_f32_e32 v79, v84, v79
	v_mul_f32_e32 v84, v80, v86
	v_mul_f32_e32 v80, v85, v87
	v_mul_f32_e32 v81, v81, v88
	v_cvt_pk_bf16_f32 v78, v82, v78
	v_cvt_pk_bf16_f32 v79, v79, v80
	v_cvt_pk_bf16_f32 v80, v96, v83
	v_cvt_pk_bf16_f32 v81, v84, v81
	ds_write_b128 v227, v[78:81]
	s_waitcnt lgkmcnt(1)
	v_lshlrev_b32_e32 v78, 16, v90
	v_and_b32_e32 v79, 0xffff0000, v90
	v_lshlrev_b32_e32 v82, 16, v92
	v_fma_f32 v78, v78, s89, v138
	v_fma_f32 v82, v82, s89, v134
	v_fma_f32 v79, v79, s89, v139
	v_med3_f32 v78, v78, s85, v226
	v_med3_f32 v82, v82, s85, v226
	v_med3_f32 v79, v79, s85, v226
	v_exp_f32_e32 v78, v78
	v_exp_f32_e32 v82, v82
	v_exp_f32_e32 v79, v79
	v_and_b32_e32 v83, 0xffff0000, v92
	v_add_f32_e32 v78, 1.0, v78
	v_add_f32_e32 v82, 1.0, v82
	v_add_f32_e32 v79, 1.0, v79
	v_fma_f32 v83, v83, s89, v135
	v_rcp_f32_e32 v78, v78
	v_rcp_f32_e32 v82, v82
	v_rcp_f32_e32 v79, v79
	v_med3_f32 v83, v83, s85, v226
	v_exp_f32_e32 v83, v83
	v_lshlrev_b32_e32 v80, 16, v91
	v_lshlrev_b32_e32 v84, 16, v93
	v_mul_f32_e32 v74, v74, v78
	v_mul_f32_e32 v78, v70, v82
	v_mul_f32_e32 v70, v75, v79
	v_fma_f32 v79, v80, s89, v140
	v_fma_f32 v80, v84, s89, v136
	v_add_f32_e32 v75, 1.0, v83
	v_med3_f32 v79, v79, s85, v226
	v_med3_f32 v80, v80, s85, v226
	v_rcp_f32_e32 v75, v75
	v_exp_f32_e32 v79, v79
	v_exp_f32_e32 v80, v80
	v_and_b32_e32 v81, 0xffff0000, v91
	v_and_b32_e32 v85, 0xffff0000, v93
	v_mul_f32_e32 v75, v71, v75
	v_add_f32_e32 v71, 1.0, v79
	v_add_f32_e32 v79, 1.0, v80
	v_fma_f32 v80, v81, s89, v141
	v_fma_f32 v81, v85, s89, v137
	v_med3_f32 v80, v80, s85, v226
	v_med3_f32 v81, v81, s85, v226
	v_exp_f32_e32 v80, v80
	v_exp_f32_e32 v81, v81
	v_rcp_f32_e32 v71, v71
	v_rcp_f32_e32 v79, v79
	v_add_f32_e32 v80, 1.0, v80
	v_add_f32_e32 v81, 1.0, v81
	v_rcp_f32_e32 v80, v80
	v_rcp_f32_e32 v81, v81
	v_mul_f32_e32 v71, v76, v71
	v_mul_f32_e32 v76, v72, v79
	v_mul_f32_e32 v72, v77, v80
	v_mul_f32_e32 v73, v73, v81
	v_cvt_pk_bf16_f32 v70, v74, v70
	v_cvt_pk_bf16_f32 v71, v71, v72
	v_cvt_pk_bf16_f32 v72, v78, v75
	v_cvt_pk_bf16_f32 v73, v76, v73
	ds_write_b128 v227, v[70:73] offset:64
	ds_read_b128 v[70:73], v3
	ds_read_b128 v[74:77], v3 offset:1152
	s_waitcnt lgkmcnt(1)
; __device__ __forceinline__ u32x4 pack8(const f32x4& v0, const f32x4& v1) { u32x4 w; w.x = cvt_pk_bf16(v0[0], v0[1]); w.y = cvt_pk_bf16(v0[2], v0[3]); w.z = cvt_pk_bf16(v1[0], v1[1]); w.w = cvt_pk_bf16(v1[2], v1[3]); return w; }
; #define UNPK0(q_) ((f32x4){bf_lo((q_).x), bf_hi((q_).x), bf_lo((q_).y), bf_hi((q_).y)})
; #define UNPK1(q_) ((f32x4){bf_lo((q_).z), bf_hi((q_).z), bf_lo((q_).w), bf_hi((q_).w)})
;     static __device__ __forceinline__ float eneg(float g) { return __builtin_amdgcn_exp2f(-1.4426950408889634f * fminf(fmaxf(g, -30.f), 30.f)); }
;     __device__ __forceinline__ void operator()(const f32x4 (&acc)[2][2][4][2], const Unit& u, int wr, int wc, int fr, int fq) const {
;     ...
;         for (int ai = 0; ai < 2; ++ai)
; #pragma unroll
;             for (int m = 0; m < 4; ++m) {
;                 pb.stage(rb[ai][m][0], rb[ai][m][1]); const u32x4 gb0 = pb.get(0), gb1 = pb.get(1);
;                 asm volatile("" ::: "memory");
; #pragma unroll
;                 for (int bj = 0; bj < 2; ++bj) { const u32x4 gb = bj ? gb1 : gb0;
;                     const f32x4 b0 = UNPK0(gb) + bb[bj][0], b1 = UNPK1(gb) + bb[bj][1];
;                     f32x4 v0 = acc[ai][bj][m][0], v1 = acc[ai][bj][m][1];
; #pragma unroll
;                     for (int k = 0; k < 4; ++k) { v0[k] *= __builtin_amdgcn_rcpf(1.0f + eneg(b0[k])); v1[k] *= __builtin_amdgcn_rcpf(1.0f + eneg(b1[k])); }
;                     po.put(bj, pack8(v0, v1)); }
;                 po.flush<false>(ai, m);
;                 asm volatile("" ::: "memory"); }
	global_store_dwordx4 v[94:95], v[70:73], off offset:2048
	s_waitcnt lgkmcnt(0)
	global_store_dwordx4 v[94:95], v[74:77], off offset:3072
	v_mov_b64_e32 v[70:71], v[178:179]
	v_mov_b64_e32 v[72:73], v[180:181]
	v_mov_b64_e32 v[74:75], v[174:175]
	v_mov_b64_e32 v[76:77], v[176:177]
	s_waitcnt lgkmcnt(0)
	v_lshlrev_b32_e32 v78, 16, v70
	v_and_b32_e32 v70, 0xffff0000, v70
	v_lshlrev_b32_e32 v80, 16, v72
	v_fma_f32 v78, v78, s89, v146
	v_fma_f32 v80, v80, s89, v142
	v_fma_f32 v70, v70, s89, v147
	v_med3_f32 v78, v78, s85, v226
	v_med3_f32 v80, v80, s85, v226
	v_med3_f32 v70, v70, s85, v226
	v_exp_f32_e32 v78, v78
	v_exp_f32_e32 v80, v80
	v_exp_f32_e32 v70, v70
	v_and_b32_e32 v72, 0xffff0000, v72
	v_fma_f32 v72, v72, s89, v143
	v_add_f32_e32 v78, 1.0, v78
	v_add_f32_e32 v80, 1.0, v80
	v_add_f32_e32 v70, 1.0, v70
	v_med3_f32 v72, v72, s85, v226
	v_rcp_f32_e32 v78, v78
	v_rcp_f32_e32 v80, v80
	v_rcp_f32_e32 v70, v70
	v_exp_f32_e32 v72, v72
	v_lshlrev_b32_e32 v79, 16, v71
	v_lshlrev_b32_e32 v81, 16, v73
	v_mul_f32_e32 v66, v66, v78
	v_mul_f32_e32 v78, v62, v80
	v_mul_f32_e32 v62, v67, v70
	v_add_f32_e32 v67, 1.0, v72
	v_fma_f32 v70, v79, s89, v148
	v_fma_f32 v72, v81, s89, v144
	v_med3_f32 v70, v70, s85, v226
	v_med3_f32 v72, v72, s85, v226
	v_rcp_f32_e32 v67, v67
	v_exp_f32_e32 v70, v70
	v_exp_f32_e32 v72, v72
	v_and_b32_e32 v71, 0xffff0000, v71
	v_and_b32_e32 v73, 0xffff0000, v73
	v_mul_f32_e32 v67, v63, v67
	v_add_f32_e32 v63, 1.0, v70
	v_add_f32_e32 v70, 1.0, v72
	v_fma_f32 v71, v71, s89, v149
	v_fma_f32 v72, v73, s89, v145
	v_med3_f32 v71, v71, s85, v226
	v_med3_f32 v72, v72, s85, v226
	v_exp_f32_e32 v71, v71
	v_exp_f32_e32 v72, v72
	v_rcp_f32_e32 v63, v63
	v_rcp_f32_e32 v70, v70
	v_add_f32_e32 v71, 1.0, v71
	v_add_f32_e32 v72, 1.0, v72
	v_rcp_f32_e32 v71, v71
	v_rcp_f32_e32 v72, v72
	v_mul_f32_e32 v63, v68, v63
	v_mul_f32_e32 v68, v64, v70
	v_mul_f32_e32 v64, v69, v71
	v_mul_f32_e32 v65, v65, v72
	v_cvt_pk_bf16_f32 v62, v66, v62
	v_cvt_pk_bf16_f32 v63, v63, v64
	v_cvt_pk_bf16_f32 v64, v78, v67
	v_cvt_pk_bf16_f32 v65, v68, v65
	ds_write_b128 v227, v[62:65]
	s_waitcnt lgkmcnt(1)
	v_lshlrev_b32_e32 v62, 16, v74
	v_and_b32_e32 v63, 0xffff0000, v74
	v_lshlrev_b32_e32 v66, 16, v76
	v_fma_f32 v62, v62, s89, v138
	v_fma_f32 v66, v66, s89, v134
	v_fma_f32 v63, v63, s89, v139
	v_med3_f32 v62, v62, s85, v226
	v_med3_f32 v66, v66, s85, v226
	v_med3_f32 v63, v63, s85, v226
	v_exp_f32_e32 v62, v62
	v_exp_f32_e32 v66, v66
	v_exp_f32_e32 v63, v63
	v_and_b32_e32 v67, 0xffff0000, v76
	v_add_f32_e32 v62, 1.0, v62
	v_add_f32_e32 v66, 1.0, v66
	v_add_f32_e32 v63, 1.0, v63
	v_fma_f32 v67, v67, s89, v135
	v_rcp_f32_e32 v62, v62
	v_rcp_f32_e32 v66, v66
	v_rcp_f32_e32 v63, v63
	v_med3_f32 v67, v67, s85, v226
	v_exp_f32_e32 v67, v67
	v_lshlrev_b32_e32 v64, 16, v75
	v_lshlrev_b32_e32 v68, 16, v77
	v_mul_f32_e32 v58, v58, v62
	v_mul_f32_e32 v62, v54, v66
	v_mul_f32_e32 v54, v59, v63
	v_fma_f32 v63, v64, s89, v140
	v_fma_f32 v64, v68, s89, v136
	v_add_f32_e32 v59, 1.0, v67
	v_med3_f32 v63, v63, s85, v226
	v_med3_f32 v64, v64, s85, v226
	v_rcp_f32_e32 v59, v59
	v_exp_f32_e32 v63, v63
	v_exp_f32_e32 v64, v64
	v_and_b32_e32 v65, 0xffff0000, v75
	v_and_b32_e32 v69, 0xffff0000, v77
	v_mul_f32_e32 v59, v55, v59
	v_add_f32_e32 v55, 1.0, v63
	v_add_f32_e32 v63, 1.0, v64
	v_fma_f32 v64, v65, s89, v141
	v_fma_f32 v65, v69, s89, v137
	v_med3_f32 v64, v64, s85, v226
	v_med3_f32 v65, v65, s85, v226
	v_exp_f32_e32 v64, v64
	v_exp_f32_e32 v65, v65
	v_rcp_f32_e32 v55, v55
	v_rcp_f32_e32 v63, v63
	v_add_f32_e32 v64, 1.0, v64
	v_add_f32_e32 v65, 1.0, v65
	v_rcp_f32_e32 v64, v64
	v_rcp_f32_e32 v65, v65
	v_mul_f32_e32 v55, v60, v55
	v_mul_f32_e32 v60, v56, v63
	v_mul_f32_e32 v56, v61, v64
	v_mul_f32_e32 v57, v57, v65
	v_cvt_pk_bf16_f32 v54, v58, v54
	v_cvt_pk_bf16_f32 v55, v55, v56
	v_cvt_pk_bf16_f32 v56, v62, v59
	v_cvt_pk_bf16_f32 v57, v60, v57
	ds_write_b128 v227, v[54:57] offset:64
	ds_read_b128 v[54:57], v3
	ds_read_b128 v[58:61], v3 offset:1152
	v_add_co_u32_e32 v62, vcc, s79, v4
	s_nop 1
	v_addc_co_u32_e32 v63, vcc, 0, v5, vcc
	v_add_co_u32_e32 v4, vcc, s86, v4
	s_nop 1
	v_addc_co_u32_e32 v5, vcc, 0, v5, vcc
	s_waitcnt lgkmcnt(1)
	global_store_dwordx4 v[4:5], v[54:57], off offset:-4096
	s_waitcnt lgkmcnt(0)
	global_store_dwordx4 v[62:63], v[58:61], off offset:1024
	v_mov_b64_e32 v[54:55], v[166:167]
	v_mov_b64_e32 v[56:57], v[168:169]
	v_mov_b64_e32 v[58:59], v[170:171]
	v_mov_b64_e32 v[60:61], v[172:173]
	s_andn2_b64 vcc, exec, s[4:5]
	s_mov_b64 s[4:5], -1
	s_waitcnt lgkmcnt(0)
	v_lshlrev_b32_e32 v64, 16, v54
	v_and_b32_e32 v54, 0xffff0000, v54
	v_lshlrev_b32_e32 v66, 16, v56
	v_fma_f32 v64, v64, s89, v146
	v_fma_f32 v66, v66, s89, v142
	v_fma_f32 v54, v54, s89, v147
	v_med3_f32 v64, v64, s85, v226
	v_med3_f32 v66, v66, s85, v226
	v_med3_f32 v54, v54, s85, v226
	v_exp_f32_e32 v64, v64
	v_exp_f32_e32 v66, v66
	v_exp_f32_e32 v54, v54
	v_and_b32_e32 v56, 0xffff0000, v56
	v_fma_f32 v56, v56, s89, v143
	v_add_f32_e32 v64, 1.0, v64
	v_add_f32_e32 v66, 1.0, v66
	v_add_f32_e32 v54, 1.0, v54
	v_med3_f32 v56, v56, s85, v226
	v_rcp_f32_e32 v64, v64
	v_rcp_f32_e32 v66, v66
	v_rcp_f32_e32 v54, v54
	v_exp_f32_e32 v56, v56
	v_lshlrev_b32_e32 v65, 16, v55
	v_lshlrev_b32_e32 v67, 16, v57
	v_mul_f32_e32 v50, v50, v64
	v_mul_f32_e32 v64, v46, v66
	v_mul_f32_e32 v46, v51, v54
	v_add_f32_e32 v51, 1.0, v56
	v_fma_f32 v54, v65, s89, v148
	v_fma_f32 v56, v67, s89, v144
	v_med3_f32 v54, v54, s85, v226
	v_med3_f32 v56, v56, s85, v226
	v_rcp_f32_e32 v51, v51
	v_exp_f32_e32 v54, v54
	v_exp_f32_e32 v56, v56
	v_and_b32_e32 v55, 0xffff0000, v55
	v_and_b32_e32 v57, 0xffff0000, v57
	v_mul_f32_e32 v51, v47, v51
	v_add_f32_e32 v47, 1.0, v54
	v_add_f32_e32 v54, 1.0, v56
	v_fma_f32 v55, v55, s89, v149
	v_fma_f32 v56, v57, s89, v145
	v_med3_f32 v55, v55, s85, v226
	v_med3_f32 v56, v56, s85, v226
	v_exp_f32_e32 v55, v55
	v_exp_f32_e32 v56, v56
	v_rcp_f32_e32 v47, v47
	v_rcp_f32_e32 v54, v54
	v_add_f32_e32 v55, 1.0, v55
	v_add_f32_e32 v56, 1.0, v56
	v_rcp_f32_e32 v55, v55
	v_rcp_f32_e32 v56, v56
	v_mul_f32_e32 v47, v52, v47
	v_mul_f32_e32 v52, v48, v54
	v_mul_f32_e32 v48, v53, v55
	v_mul_f32_e32 v49, v49, v56
	v_cvt_pk_bf16_f32 v46, v50, v46
	v_cvt_pk_bf16_f32 v47, v47, v48
	v_cvt_pk_bf16_f32 v48, v64, v51
	v_cvt_pk_bf16_f32 v49, v52, v49
	ds_write_b128 v227, v[46:49]
	s_waitcnt lgkmcnt(1)
; __device__ __forceinline__ u32x4 pack8(const f32x4& v0, const f32x4& v1) { u32x4 w; w.x = cvt_pk_bf16(v0[0], v0[1]); w.y = cvt_pk_bf16(v0[2], v0[3]); w.z = cvt_pk_bf16(v1[0], v1[1]); w.w = cvt_pk_bf16(v1[2], v1[3]); return w; }
; #define UNPK0(q_) ((f32x4){bf_lo((q_).x), bf_hi((q_).x), bf_lo((q_).y), bf_hi((q_).y)})
; #define UNPK1(q_) ((f32x4){bf_lo((q_).z), bf_hi((q_).z), bf_lo((q_).w), bf_hi((q_).w)})
;     static __device__ __forceinline__ float eneg(float g) { return __builtin_amdgcn_exp2f(-1.4426950408889634f * fminf(fmaxf(g, -30.f), 30.f)); }
;     __device__ __forceinline__ void operator()(const f32x4 (&acc)[2][2][4][2], const Unit& u, int wr, int wc, int fr, int fq) const {
;     ...
;         for (int ai = 0; ai < 2; ++ai)
; #pragma unroll
;             for (int m = 0; m < 4; ++m) {
;                 pb.stage(rb[ai][m][0], rb[ai][m][1]); const u32x4 gb0 = pb.get(0), gb1 = pb.get(1);
;                 asm volatile("" ::: "memory");
; #pragma unroll
;                 for (int bj = 0; bj < 2; ++bj) { const u32x4 gb = bj ? gb1 : gb0;
;                     const f32x4 b0 = UNPK0(gb) + bb[bj][0], b1 = UNPK1(gb) + bb[bj][1];
;                     f32x4 v0 = acc[ai][bj][m][0], v1 = acc[ai][bj][m][1];
; #pragma unroll
;                     for (int k = 0; k < 4; ++k) { v0[k] *= __builtin_amdgcn_rcpf(1.0f + eneg(b0[k])); v1[k] *= __builtin_amdgcn_rcpf(1.0f + eneg(b1[k])); }
;                     po.put(bj, pack8(v0, v1)); }
;                 po.flush<false>(ai, m);
;                 asm volatile("" ::: "memory"); }
	v_lshlrev_b32_e32 v46, 16, v58
	v_and_b32_e32 v47, 0xffff0000, v58
	v_lshlrev_b32_e32 v50, 16, v60
	v_fma_f32 v46, v46, s89, v138
	v_fma_f32 v50, v50, s89, v134
	v_fma_f32 v47, v47, s89, v139
	v_med3_f32 v46, v46, s85, v226
	v_med3_f32 v50, v50, s85, v226
	v_med3_f32 v47, v47, s85, v226
	v_exp_f32_e32 v46, v46
	v_exp_f32_e32 v50, v50
	v_exp_f32_e32 v47, v47
	v_and_b32_e32 v51, 0xffff0000, v60
	v_add_f32_e32 v46, 1.0, v46
	v_add_f32_e32 v50, 1.0, v50
	v_add_f32_e32 v47, 1.0, v47
	v_fma_f32 v51, v51, s89, v135
	v_rcp_f32_e32 v46, v46
	v_rcp_f32_e32 v50, v50
	v_rcp_f32_e32 v47, v47
	v_med3_f32 v51, v51, s85, v226
	v_exp_f32_e32 v51, v51
	v_lshlrev_b32_e32 v48, 16, v59
	v_lshlrev_b32_e32 v52, 16, v61
	v_mul_f32_e32 v42, v42, v46
	v_mul_f32_e32 v46, v38, v50
	v_mul_f32_e32 v38, v43, v47
	v_fma_f32 v47, v48, s89, v140
	v_fma_f32 v48, v52, s89, v136
	v_add_f32_e32 v43, 1.0, v51
	v_med3_f32 v47, v47, s85, v226
	v_med3_f32 v48, v48, s85, v226
	v_rcp_f32_e32 v43, v43
	v_exp_f32_e32 v47, v47
	v_exp_f32_e32 v48, v48
	v_and_b32_e32 v49, 0xffff0000, v59
	v_and_b32_e32 v53, 0xffff0000, v61
	v_mul_f32_e32 v43, v39, v43
	v_add_f32_e32 v39, 1.0, v47
	v_add_f32_e32 v47, 1.0, v48
	v_fma_f32 v48, v49, s89, v141
	v_fma_f32 v49, v53, s89, v137
	v_med3_f32 v48, v48, s85, v226
	v_med3_f32 v49, v49, s85, v226
	v_exp_f32_e32 v48, v48
	v_exp_f32_e32 v49, v49
	v_rcp_f32_e32 v39, v39
	v_rcp_f32_e32 v47, v47
	v_add_f32_e32 v48, 1.0, v48
	v_add_f32_e32 v49, 1.0, v49
	v_rcp_f32_e32 v48, v48
	v_rcp_f32_e32 v49, v49
	v_mul_f32_e32 v39, v44, v39
	v_mul_f32_e32 v44, v40, v47
	v_mul_f32_e32 v40, v45, v48
	v_mul_f32_e32 v41, v41, v49
	v_cvt_pk_bf16_f32 v38, v42, v38
	v_cvt_pk_bf16_f32 v39, v39, v40
	v_cvt_pk_bf16_f32 v40, v46, v43
	v_cvt_pk_bf16_f32 v41, v44, v41
	ds_write_b128 v227, v[38:41] offset:64
	ds_read_b128 v[38:41], v3
	ds_read_b128 v[42:45], v3 offset:1152
	s_waitcnt lgkmcnt(1)
	global_store_dwordx4 v[62:63], v[38:41], off offset:2048
	s_waitcnt lgkmcnt(0)
	global_store_dwordx4 v[62:63], v[42:45], off offset:3072
	v_mov_b64_e32 v[38:39], v[158:159]
	v_mov_b64_e32 v[40:41], v[160:161]
	v_mov_b64_e32 v[42:43], v[162:163]
	v_mov_b64_e32 v[44:45], v[164:165]
	s_waitcnt lgkmcnt(0)
	v_lshlrev_b32_e32 v46, 16, v38
	v_and_b32_e32 v38, 0xffff0000, v38
	v_lshlrev_b32_e32 v48, 16, v40
	v_fma_f32 v46, v46, s89, v146
	v_fma_f32 v48, v48, s89, v142
	v_fma_f32 v38, v38, s89, v147
	v_med3_f32 v46, v46, s85, v226
	v_med3_f32 v48, v48, s85, v226
	v_med3_f32 v38, v38, s85, v226
	v_exp_f32_e32 v46, v46
	v_exp_f32_e32 v48, v48
	v_exp_f32_e32 v38, v38
	v_and_b32_e32 v40, 0xffff0000, v40
	v_fma_f32 v40, v40, s89, v143
	v_add_f32_e32 v46, 1.0, v46
	v_add_f32_e32 v48, 1.0, v48
	v_add_f32_e32 v38, 1.0, v38
	v_med3_f32 v40, v40, s85, v226
	v_rcp_f32_e32 v46, v46
	v_rcp_f32_e32 v48, v48
	v_rcp_f32_e32 v38, v38
	v_exp_f32_e32 v40, v40
	v_lshlrev_b32_e32 v47, 16, v39
	v_lshlrev_b32_e32 v49, 16, v41
	v_mul_f32_e32 v34, v34, v46
	v_mul_f32_e32 v46, v30, v48
	v_mul_f32_e32 v30, v35, v38
	v_add_f32_e32 v35, 1.0, v40
	v_fma_f32 v38, v47, s89, v148
	v_fma_f32 v40, v49, s89, v144
	v_med3_f32 v38, v38, s85, v226
	v_med3_f32 v40, v40, s85, v226
	v_rcp_f32_e32 v35, v35
	v_exp_f32_e32 v38, v38
	v_exp_f32_e32 v40, v40
	v_and_b32_e32 v39, 0xffff0000, v39
	v_and_b32_e32 v41, 0xffff0000, v41
	v_mul_f32_e32 v35, v31, v35
	v_add_f32_e32 v31, 1.0, v38
	v_add_f32_e32 v38, 1.0, v40
	v_fma_f32 v39, v39, s89, v149
	v_fma_f32 v40, v41, s89, v145
	v_med3_f32 v39, v39, s85, v226
	v_med3_f32 v40, v40, s85, v226
	v_exp_f32_e32 v39, v39
	v_exp_f32_e32 v40, v40
	v_rcp_f32_e32 v31, v31
	v_rcp_f32_e32 v38, v38
	v_add_f32_e32 v39, 1.0, v39
	v_add_f32_e32 v40, 1.0, v40
	v_rcp_f32_e32 v39, v39
	v_rcp_f32_e32 v40, v40
	v_mul_f32_e32 v31, v36, v31
	v_mul_f32_e32 v36, v32, v38
	v_mul_f32_e32 v32, v37, v39
	v_mul_f32_e32 v33, v33, v40
	v_cvt_pk_bf16_f32 v30, v34, v30
	v_cvt_pk_bf16_f32 v31, v31, v32
	v_cvt_pk_bf16_f32 v32, v46, v35
	v_cvt_pk_bf16_f32 v33, v36, v33
	ds_write_b128 v227, v[30:33]
	s_waitcnt lgkmcnt(1)
	v_lshlrev_b32_e32 v30, 16, v42
	v_and_b32_e32 v31, 0xffff0000, v42
	v_lshlrev_b32_e32 v34, 16, v44
	v_fma_f32 v30, v30, s89, v138
	v_fma_f32 v34, v34, s89, v134
	v_fma_f32 v31, v31, s89, v139
	v_med3_f32 v30, v30, s85, v226
	v_med3_f32 v34, v34, s85, v226
	v_med3_f32 v31, v31, s85, v226
	v_exp_f32_e32 v30, v30
	v_exp_f32_e32 v34, v34
	v_exp_f32_e32 v31, v31
	v_and_b32_e32 v35, 0xffff0000, v44
	v_add_f32_e32 v30, 1.0, v30
	v_add_f32_e32 v34, 1.0, v34
	v_add_f32_e32 v31, 1.0, v31
	v_fma_f32 v35, v35, s89, v135
	v_rcp_f32_e32 v30, v30
	v_rcp_f32_e32 v34, v34
	v_rcp_f32_e32 v31, v31
	v_med3_f32 v35, v35, s85, v226
	v_exp_f32_e32 v35, v35
	v_lshlrev_b32_e32 v32, 16, v43
	v_lshlrev_b32_e32 v36, 16, v45
	v_mul_f32_e32 v26, v26, v30
	v_mul_f32_e32 v30, v22, v34
	v_mul_f32_e32 v22, v27, v31
	v_fma_f32 v31, v32, s89, v140
	v_fma_f32 v32, v36, s89, v136
	v_add_f32_e32 v27, 1.0, v35
	v_med3_f32 v31, v31, s85, v226
	v_med3_f32 v32, v32, s85, v226
	v_rcp_f32_e32 v27, v27
	v_exp_f32_e32 v31, v31
	v_exp_f32_e32 v32, v32
	v_and_b32_e32 v33, 0xffff0000, v43
	v_and_b32_e32 v37, 0xffff0000, v45
	v_mul_f32_e32 v27, v23, v27
	v_add_f32_e32 v23, 1.0, v31
	v_add_f32_e32 v31, 1.0, v32
	v_fma_f32 v32, v33, s89, v141
	v_fma_f32 v33, v37, s89, v137
	v_med3_f32 v32, v32, s85, v226
	v_med3_f32 v33, v33, s85, v226
	v_exp_f32_e32 v32, v32
	v_exp_f32_e32 v33, v33
	v_rcp_f32_e32 v23, v23
	v_rcp_f32_e32 v31, v31
	v_add_f32_e32 v32, 1.0, v32
	v_add_f32_e32 v33, 1.0, v33
	v_rcp_f32_e32 v32, v32
	v_rcp_f32_e32 v33, v33
	v_mul_f32_e32 v23, v28, v23
	v_mul_f32_e32 v28, v24, v31
	v_mul_f32_e32 v24, v29, v32
	v_mul_f32_e32 v25, v25, v33
	v_cvt_pk_bf16_f32 v22, v26, v22
	v_cvt_pk_bf16_f32 v23, v23, v24
	v_cvt_pk_bf16_f32 v24, v30, v27
	v_cvt_pk_bf16_f32 v25, v28, v25
	ds_write_b128 v227, v[22:25] offset:64
	ds_read_b128 v[22:25], v3
	ds_read_b128 v[26:29], v3 offset:1152
	s_waitcnt lgkmcnt(1)
; __device__ __forceinline__ u32x4 pack8(const f32x4& v0, const f32x4& v1) { u32x4 w; w.x = cvt_pk_bf16(v0[0], v0[1]); w.y = cvt_pk_bf16(v0[2], v0[3]); w.z = cvt_pk_bf16(v1[0], v1[1]); w.w = cvt_pk_bf16(v1[2], v1[3]); return w; }
; #define UNPK0(q_) ((f32x4){bf_lo((q_).x), bf_hi((q_).x), bf_lo((q_).y), bf_hi((q_).y)})
; #define UNPK1(q_) ((f32x4){bf_lo((q_).z), bf_hi((q_).z), bf_lo((q_).w), bf_hi((q_).w)})
;     static __device__ __forceinline__ float eneg(float g) { return __builtin_amdgcn_exp2f(-1.4426950408889634f * fminf(fmaxf(g, -30.f), 30.f)); }
;     __device__ __forceinline__ void operator()(const f32x4 (&acc)[2][2][4][2], const Unit& u, int wr, int wc, int fr, int fq) const {
;     ...
;         for (int ai = 0; ai < 2; ++ai)
; #pragma unroll
;             for (int m = 0; m < 4; ++m) {
;                 pb.stage(rb[ai][m][0], rb[ai][m][1]); const u32x4 gb0 = pb.get(0), gb1 = pb.get(1);
;                 asm volatile("" ::: "memory");
; #pragma unroll
;                 for (int bj = 0; bj < 2; ++bj) { const u32x4 gb = bj ? gb1 : gb0;
;                     const f32x4 b0 = UNPK0(gb) + bb[bj][0], b1 = UNPK1(gb) + bb[bj][1];
;                     f32x4 v0 = acc[ai][bj][m][0], v1 = acc[ai][bj][m][1];
; #pragma unroll
;                     for (int k = 0; k < 4; ++k) { v0[k] *= __builtin_amdgcn_rcpf(1.0f + eneg(b0[k])); v1[k] *= __builtin_amdgcn_rcpf(1.0f + eneg(b1[k])); }
;                     po.put(bj, pack8(v0, v1)); }
;                 po.flush<false>(ai, m);
;                 asm volatile("" ::: "memory"); }
	global_store_dwordx4 v[4:5], v[22:25], off
	s_waitcnt lgkmcnt(0)
	global_store_dwordx4 v[4:5], v[26:29], off offset:1024
	v_mov_b64_e32 v[22:23], v[150:151]
	v_mov_b64_e32 v[24:25], v[152:153]
	v_mov_b64_e32 v[26:27], v[154:155]
	v_mov_b64_e32 v[28:29], v[156:157]
	s_waitcnt lgkmcnt(0)
	v_lshlrev_b32_e32 v30, 16, v22
	v_and_b32_e32 v22, 0xffff0000, v22
	v_lshlrev_b32_e32 v32, 16, v24
	v_fma_f32 v30, v30, s89, v146
	v_fma_f32 v32, v32, s89, v142
	v_fma_f32 v22, v22, s89, v147
	v_med3_f32 v30, v30, s85, v226
	v_med3_f32 v32, v32, s85, v226
	v_med3_f32 v22, v22, s85, v226
	v_exp_f32_e32 v30, v30
	v_exp_f32_e32 v32, v32
	v_exp_f32_e32 v22, v22
	v_and_b32_e32 v24, 0xffff0000, v24
	v_fma_f32 v24, v24, s89, v143
	v_add_f32_e32 v30, 1.0, v30
	v_add_f32_e32 v32, 1.0, v32
	v_add_f32_e32 v22, 1.0, v22
	v_med3_f32 v24, v24, s85, v226
	v_rcp_f32_e32 v30, v30
	v_rcp_f32_e32 v32, v32
	v_rcp_f32_e32 v22, v22
	v_exp_f32_e32 v24, v24
	v_lshlrev_b32_e32 v31, 16, v23
	v_lshlrev_b32_e32 v33, 16, v25
	v_mul_f32_e32 v18, v18, v30
	v_mul_f32_e32 v30, v14, v32
	v_mul_f32_e32 v14, v19, v22
	v_add_f32_e32 v19, 1.0, v24
	v_fma_f32 v22, v31, s89, v148
	v_fma_f32 v24, v33, s89, v144
	v_med3_f32 v22, v22, s85, v226
	v_med3_f32 v24, v24, s85, v226
	v_rcp_f32_e32 v19, v19
	v_exp_f32_e32 v22, v22
	v_exp_f32_e32 v24, v24
	v_and_b32_e32 v23, 0xffff0000, v23
	v_and_b32_e32 v25, 0xffff0000, v25
	v_mul_f32_e32 v19, v15, v19
	v_add_f32_e32 v15, 1.0, v22
	v_add_f32_e32 v22, 1.0, v24
	v_fma_f32 v23, v23, s89, v149
	v_fma_f32 v24, v25, s89, v145
	v_med3_f32 v23, v23, s85, v226
	v_med3_f32 v24, v24, s85, v226
	v_exp_f32_e32 v23, v23
	v_exp_f32_e32 v24, v24
	v_rcp_f32_e32 v15, v15
	v_rcp_f32_e32 v22, v22
	v_add_f32_e32 v23, 1.0, v23
	v_add_f32_e32 v24, 1.0, v24
	v_rcp_f32_e32 v23, v23
	v_rcp_f32_e32 v24, v24
	v_mul_f32_e32 v15, v20, v15
	v_mul_f32_e32 v20, v16, v22
	v_mul_f32_e32 v16, v21, v23
	v_mul_f32_e32 v17, v17, v24
	v_cvt_pk_bf16_f32 v14, v18, v14
	v_cvt_pk_bf16_f32 v15, v15, v16
	v_cvt_pk_bf16_f32 v16, v30, v19
	v_cvt_pk_bf16_f32 v17, v20, v17
	ds_write_b128 v227, v[14:17]
	s_waitcnt lgkmcnt(1)
	v_lshlrev_b32_e32 v14, 16, v26
	v_and_b32_e32 v15, 0xffff0000, v26
	v_lshlrev_b32_e32 v18, 16, v28
	v_fma_f32 v14, v14, s89, v138
	v_fma_f32 v18, v18, s89, v134
	v_fma_f32 v15, v15, s89, v139
	v_med3_f32 v14, v14, s85, v226
	v_med3_f32 v18, v18, s85, v226
	v_med3_f32 v15, v15, s85, v226
	v_exp_f32_e32 v14, v14
	v_exp_f32_e32 v18, v18
	v_exp_f32_e32 v15, v15
	v_and_b32_e32 v19, 0xffff0000, v28
	v_add_f32_e32 v14, 1.0, v14
	v_add_f32_e32 v18, 1.0, v18
	v_add_f32_e32 v15, 1.0, v15
	v_fma_f32 v19, v19, s89, v135
	v_rcp_f32_e32 v14, v14
	v_rcp_f32_e32 v18, v18
	v_rcp_f32_e32 v15, v15
	v_med3_f32 v19, v19, s85, v226
	v_exp_f32_e32 v19, v19
	v_lshlrev_b32_e32 v16, 16, v27
	v_lshlrev_b32_e32 v20, 16, v29
	v_mul_f32_e32 v10, v10, v14
	v_mul_f32_e32 v14, v6, v18
	v_mul_f32_e32 v6, v11, v15
	v_fma_f32 v15, v16, s89, v140
	v_fma_f32 v16, v20, s89, v136
	v_add_f32_e32 v11, 1.0, v19
	v_med3_f32 v15, v15, s85, v226
	v_med3_f32 v16, v16, s85, v226
	v_rcp_f32_e32 v11, v11
	v_exp_f32_e32 v15, v15
	v_exp_f32_e32 v16, v16
	v_and_b32_e32 v17, 0xffff0000, v27
	v_and_b32_e32 v21, 0xffff0000, v29
	v_mul_f32_e32 v11, v7, v11
	v_add_f32_e32 v7, 1.0, v15
	v_add_f32_e32 v15, 1.0, v16
	v_fma_f32 v16, v17, s89, v141
	v_fma_f32 v17, v21, s89, v137
	v_med3_f32 v16, v16, s85, v226
	v_med3_f32 v17, v17, s85, v226
	v_exp_f32_e32 v16, v16
	v_exp_f32_e32 v17, v17
	v_rcp_f32_e32 v7, v7
	v_rcp_f32_e32 v15, v15
	v_add_f32_e32 v16, 1.0, v16
	v_add_f32_e32 v17, 1.0, v17
	v_rcp_f32_e32 v16, v16
	v_rcp_f32_e32 v17, v17
	v_mul_f32_e32 v7, v12, v7
	v_mul_f32_e32 v12, v8, v15
	v_mul_f32_e32 v8, v13, v16
	v_mul_f32_e32 v9, v9, v17
	v_cvt_pk_bf16_f32 v6, v10, v6
	v_cvt_pk_bf16_f32 v7, v7, v8
	v_cvt_pk_bf16_f32 v8, v14, v11
	v_cvt_pk_bf16_f32 v9, v12, v9
	ds_write_b128 v227, v[6:9] offset:64
	ds_read_b128 v[6:9], v3
	ds_read_b128 v[10:13], v3 offset:1152
	s_waitcnt lgkmcnt(1)
	global_store_dwordx4 v[4:5], v[6:9], off offset:2048
	s_waitcnt lgkmcnt(0)
	global_store_dwordx4 v[4:5], v[10:13], off offset:3072
	s_cbranch_vccnz .LBB0_372
	s_andn2_b64 vcc, exec, s[10:11]
	s_cbranch_vccnz .LBB0_371
	s_barrier
	s_branch .LBB0_371
